# v25 + pool_prep hand-rewritten: all w+32 rows per thread loaded up front, outgoing window term recomputed from registers (no serialized per-row round trips)
# speedup vs baseline: 1.0115x; 1.0115x over previous
; __device__ __forceinline__ f32x4 ld4bf(const bf16* p) { const v2u w = *(const v2u*)p; return (f32x4){bf_lo(w.x), bf_hi(w.x), bf_lo(w.y), bf_hi(w.y)}; }
; __device__ __forceinline__ void pool_prep(const bf16* X, const float* ss, const float* gain, bf16* PB, LAS unsigned char* lds, int vcu, int G, int tid) {
;     ...
;         const int q = tid & 255, half = tid >> 8, w = 2 << (q >> 6);
;         const f32x4 gn = *(const f32x4*)(gain + 4 * q);
;         const int ra = r0 + 32 * half;
;         const bf16* xp = X + 4 * q;
;         f32x4 S = {0.f, 0.f, 0.f, 0.f};
; #pragma unroll
;         for (int j = 1; j <= 16; ++j) { const int row = ra - j; if (j <= w && row >= bstart) S += ld4bf(xp + (size_t)row * DM) * rsl[row - r0 + 16]; }
.LBB0_313:
	s_or_b64 exec, exec, s[0:1]
	s_waitcnt lgkmcnt(0)
	s_barrier
	global_load_dwordx4 v[2:5], v[10:11], off
	v_add_u32_e32 v16, s12, v33
	v_subrev_u32_e32 v20, s9, v16
	v_cmp_eq_u32_e64 s[6:7], 0, v20
	v_ashrrev_i32_e32 v17, 31, v16
	v_lshlrev_b64 v[18:19], 11, v[16:17]
	v_lshl_add_u64 v[22:23], v[12:13], 0, v[18:19]
	v_lshl_add_u64 v[24:25], v[14:15], 0, v[18:19]
	v_lshlrev_b32_e32 v21, 2, v33
	v_cvt_f32_i32_e32 v196, v32
	v_readfirstlane_b32 s0, v32
	s_cmp_eq_u32 s0, 2
	s_cbranch_scc1 .Lmy_pool_w2
	s_cmp_eq_u32 s0, 4
	s_cbranch_scc1 .Lmy_pool_w4
	s_cmp_eq_u32 s0, 8
	s_cbranch_scc1 .Lmy_pool_w8
	s_mov_b32 s0, 32768
	v_subrev_co_u32_e32 v198, vcc, s0, v22
	s_nop 1
	v_subbrev_co_u32_e32 v199, vcc, 0, v23, vcc
	s_mov_b64 s[0:1], 0x1000
	global_load_dwordx2 v[100:101], v[198:199], off
	global_load_dwordx2 v[102:103], v[198:199], off offset:2048
	v_lshl_add_u64 v[198:199], v[198:199], 0, s[0:1]
	global_load_dwordx2 v[104:105], v[198:199], off
	global_load_dwordx2 v[106:107], v[198:199], off offset:2048
	v_lshl_add_u64 v[198:199], v[198:199], 0, s[0:1]
	global_load_dwordx2 v[108:109], v[198:199], off
	global_load_dwordx2 v[110:111], v[198:199], off offset:2048
	v_lshl_add_u64 v[198:199], v[198:199], 0, s[0:1]
	global_load_dwordx2 v[112:113], v[198:199], off
	global_load_dwordx2 v[114:115], v[198:199], off offset:2048
	v_lshl_add_u64 v[198:199], v[198:199], 0, s[0:1]
	global_load_dwordx2 v[116:117], v[198:199], off
	global_load_dwordx2 v[118:119], v[198:199], off offset:2048
	v_lshl_add_u64 v[198:199], v[198:199], 0, s[0:1]
	global_load_dwordx2 v[120:121], v[198:199], off
	global_load_dwordx2 v[122:123], v[198:199], off offset:2048
	v_lshl_add_u64 v[198:199], v[198:199], 0, s[0:1]
	global_load_dwordx2 v[124:125], v[198:199], off
	global_load_dwordx2 v[126:127], v[198:199], off offset:2048
	v_lshl_add_u64 v[198:199], v[198:199], 0, s[0:1]
	global_load_dwordx2 v[128:129], v[198:199], off
	global_load_dwordx2 v[130:131], v[198:199], off offset:2048
	v_lshl_add_u64 v[198:199], v[198:199], 0, s[0:1]
	global_load_dwordx2 v[132:133], v[198:199], off
	global_load_dwordx2 v[134:135], v[198:199], off offset:2048
	v_lshl_add_u64 v[198:199], v[198:199], 0, s[0:1]
	global_load_dwordx2 v[136:137], v[198:199], off
	global_load_dwordx2 v[138:139], v[198:199], off offset:2048
	v_lshl_add_u64 v[198:199], v[198:199], 0, s[0:1]
	global_load_dwordx2 v[140:141], v[198:199], off
	global_load_dwordx2 v[142:143], v[198:199], off offset:2048
	v_lshl_add_u64 v[198:199], v[198:199], 0, s[0:1]
	global_load_dwordx2 v[144:145], v[198:199], off
	global_load_dwordx2 v[146:147], v[198:199], off offset:2048
	v_lshl_add_u64 v[198:199], v[198:199], 0, s[0:1]
	global_load_dwordx2 v[148:149], v[198:199], off
	global_load_dwordx2 v[150:151], v[198:199], off offset:2048
	v_lshl_add_u64 v[198:199], v[198:199], 0, s[0:1]
	global_load_dwordx2 v[152:153], v[198:199], off
	global_load_dwordx2 v[154:155], v[198:199], off offset:2048
	v_lshl_add_u64 v[198:199], v[198:199], 0, s[0:1]
	global_load_dwordx2 v[156:157], v[198:199], off
	global_load_dwordx2 v[158:159], v[198:199], off offset:2048
	v_lshl_add_u64 v[198:199], v[198:199], 0, s[0:1]
	global_load_dwordx2 v[160:161], v[198:199], off
	global_load_dwordx2 v[162:163], v[198:199], off offset:2048
	v_lshl_add_u64 v[198:199], v[198:199], 0, s[0:1]
	global_load_dwordx2 v[164:165], v[198:199], off
	global_load_dwordx2 v[166:167], v[198:199], off offset:2048
	v_lshl_add_u64 v[198:199], v[198:199], 0, s[0:1]
	global_load_dwordx2 v[168:169], v[198:199], off
	global_load_dwordx2 v[170:171], v[198:199], off offset:2048
	v_lshl_add_u64 v[198:199], v[198:199], 0, s[0:1]
	global_load_dwordx2 v[172:173], v[198:199], off
	global_load_dwordx2 v[174:175], v[198:199], off offset:2048
	v_lshl_add_u64 v[198:199], v[198:199], 0, s[0:1]
	global_load_dwordx2 v[176:177], v[198:199], off
	global_load_dwordx2 v[178:179], v[198:199], off offset:2048
	v_lshl_add_u64 v[198:199], v[198:199], 0, s[0:1]
	global_load_dwordx2 v[180:181], v[198:199], off
	global_load_dwordx2 v[182:183], v[198:199], off offset:2048
	v_lshl_add_u64 v[198:199], v[198:199], 0, s[0:1]
	global_load_dwordx2 v[184:185], v[198:199], off
	global_load_dwordx2 v[186:187], v[198:199], off offset:2048
	v_lshl_add_u64 v[198:199], v[198:199], 0, s[0:1]
	global_load_dwordx2 v[188:189], v[198:199], off
	global_load_dwordx2 v[190:191], v[198:199], off offset:2048
	v_lshl_add_u64 v[198:199], v[198:199], 0, s[0:1]
	global_load_dwordx2 v[192:193], v[198:199], off
	global_load_dwordx2 v[194:195], v[198:199], off offset:2048
	ds_read_b32 v40, v21 offset:0
	ds_read_b32 v41, v21 offset:4
	ds_read_b32 v42, v21 offset:8
	ds_read_b32 v43, v21 offset:12
	ds_read_b32 v44, v21 offset:16
	ds_read_b32 v45, v21 offset:20
	ds_read_b32 v46, v21 offset:24
	ds_read_b32 v47, v21 offset:28
	ds_read_b32 v48, v21 offset:32
	ds_read_b32 v49, v21 offset:36
	ds_read_b32 v50, v21 offset:40
	ds_read_b32 v51, v21 offset:44
	s_waitcnt lgkmcnt(0)
	ds_read_b32 v52, v21 offset:48
	ds_read_b32 v53, v21 offset:52
	ds_read_b32 v54, v21 offset:56
	ds_read_b32 v55, v21 offset:60
	ds_read_b32 v56, v21 offset:64
	ds_read_b32 v57, v21 offset:68
	ds_read_b32 v58, v21 offset:72
	ds_read_b32 v59, v21 offset:76
	ds_read_b32 v60, v21 offset:80
	ds_read_b32 v61, v21 offset:84
	ds_read_b32 v62, v21 offset:88
	ds_read_b32 v63, v21 offset:92
	s_waitcnt lgkmcnt(0)
	ds_read_b32 v64, v21 offset:96
	ds_read_b32 v65, v21 offset:100
	ds_read_b32 v66, v21 offset:104
	ds_read_b32 v67, v21 offset:108
	ds_read_b32 v68, v21 offset:112
	ds_read_b32 v69, v21 offset:116
	ds_read_b32 v70, v21 offset:120
	ds_read_b32 v71, v21 offset:124
	ds_read_b32 v72, v21 offset:128
	ds_read_b32 v73, v21 offset:132
	ds_read_b32 v74, v21 offset:136
	ds_read_b32 v75, v21 offset:140
	s_waitcnt lgkmcnt(0)
; __device__ __forceinline__ unsigned pk2(float lo, float hi) { return pg8::cvt_pk_bf16(lo, hi); }
; __device__ __forceinline__ f32x4 ld4bf(const bf16* p) { const v2u w = *(const v2u*)p; return (f32x4){bf_lo(w.x), bf_hi(w.x), bf_lo(w.y), bf_hi(w.y)}; }
; __device__ __forceinline__ void pool_prep(const bf16* X, const float* ss, const float* gain, bf16* PB, LAS unsigned char* lds, int vcu, int G, int tid) {
;     ...
;         for (int j = 1; j <= 16; ++j) { const int row = ra - j; if (j <= w && row >= bstart) S += ld4bf(xp + (size_t)row * DM) * rsl[row - r0 + 16]; }
;     ...
;         for (int i = 0; i < 32; ++i) { const int row = ra + i, t = row - bstart;
;             const f32x4 xn = ld4bf(xp + (size_t)row * DM) * rsl[row - r0 + 16];
;             f32x4 old = {0.f, 0.f, 0.f, 0.f};
;             if (t >= w) old = ld4bf(xp + (size_t)(row - w) * DM) * rsl[row - w - r0 + 16];
;             S = S + xn - old;
;             const int cnt = (t + 1 < w) ? t + 1 : w;
;             const f32x4 p = (S * (1.0f / (float)cnt) - xn) * gn;
;             v2u o; o.x = pk2(p[0], p[1]); o.y = pk2(p[2], p[3]); *(v2u*)(PB + (size_t)row * DM + 4 * q) = o; }
	ds_read_b32 v76, v21 offset:144
	ds_read_b32 v77, v21 offset:148
	ds_read_b32 v78, v21 offset:152
	ds_read_b32 v79, v21 offset:156
	ds_read_b32 v80, v21 offset:160
	ds_read_b32 v81, v21 offset:164
	ds_read_b32 v82, v21 offset:168
	ds_read_b32 v83, v21 offset:172
	ds_read_b32 v84, v21 offset:176
	ds_read_b32 v85, v21 offset:180
	ds_read_b32 v86, v21 offset:184
	ds_read_b32 v87, v21 offset:188
	s_waitcnt lgkmcnt(0)
	v_div_scale_f32 v26, s[0:1], v196, v196, 1.0
	v_rcp_f32_e32 v27, v26
	s_nop 0
	v_fma_f32 v28, -v26, v27, 1.0
	v_fmac_f32_e32 v27, v28, v27
	v_div_scale_f32 v28, vcc, 1.0, v196, 1.0
	v_mul_f32_e32 v29, v28, v27
	v_fma_f32 v30, -v26, v29, v28
	v_fmac_f32_e32 v29, v30, v27
	v_fma_f32 v26, -v26, v29, v28
	s_nop 1
	v_div_fmas_f32 v197, v26, v27, v29
	v_div_fixup_f32 v197, v197, v196, 1.0
	v_mov_b32_e32 v6, 0
	v_mov_b32_e32 v7, 0
	v_mov_b32_e32 v8, 0
	v_mov_b32_e32 v9, 0
	s_waitcnt lgkmcnt(0)
	s_waitcnt vmcnt(32)
	v_cndmask_b32_e64 v100, v100, 0, s[6:7]
	v_cndmask_b32_e64 v101, v101, 0, s[6:7]
	v_cndmask_b32_e64 v102, v102, 0, s[6:7]
	v_cndmask_b32_e64 v103, v103, 0, s[6:7]
	v_cndmask_b32_e64 v104, v104, 0, s[6:7]
	v_cndmask_b32_e64 v105, v105, 0, s[6:7]
	v_cndmask_b32_e64 v106, v106, 0, s[6:7]
	v_cndmask_b32_e64 v107, v107, 0, s[6:7]
	v_cndmask_b32_e64 v108, v108, 0, s[6:7]
	v_cndmask_b32_e64 v109, v109, 0, s[6:7]
	v_cndmask_b32_e64 v110, v110, 0, s[6:7]
	v_cndmask_b32_e64 v111, v111, 0, s[6:7]
	v_cndmask_b32_e64 v112, v112, 0, s[6:7]
	v_cndmask_b32_e64 v113, v113, 0, s[6:7]
	v_cndmask_b32_e64 v114, v114, 0, s[6:7]
	v_cndmask_b32_e64 v115, v115, 0, s[6:7]
	v_cndmask_b32_e64 v116, v116, 0, s[6:7]
	v_cndmask_b32_e64 v117, v117, 0, s[6:7]
	v_cndmask_b32_e64 v118, v118, 0, s[6:7]
	v_cndmask_b32_e64 v119, v119, 0, s[6:7]
	v_cndmask_b32_e64 v120, v120, 0, s[6:7]
	v_cndmask_b32_e64 v121, v121, 0, s[6:7]
	v_cndmask_b32_e64 v122, v122, 0, s[6:7]
	v_cndmask_b32_e64 v123, v123, 0, s[6:7]
	v_cndmask_b32_e64 v124, v124, 0, s[6:7]
	v_cndmask_b32_e64 v125, v125, 0, s[6:7]
	v_cndmask_b32_e64 v126, v126, 0, s[6:7]
	v_cndmask_b32_e64 v127, v127, 0, s[6:7]
	v_cndmask_b32_e64 v128, v128, 0, s[6:7]
	v_cndmask_b32_e64 v129, v129, 0, s[6:7]
	v_cndmask_b32_e64 v130, v130, 0, s[6:7]
	v_cndmask_b32_e64 v131, v131, 0, s[6:7]
	v_lshlrev_b32_e32 v200, 16, v130
	v_and_b32_e32 v201, 0xffff0000, v130
	v_lshlrev_b32_e32 v202, 16, v131
	v_and_b32_e32 v203, 0xffff0000, v131
	v_fma_f32 v6, v55, v200, v6
	v_fma_f32 v7, v55, v201, v7
	v_fma_f32 v8, v55, v202, v8
	v_fma_f32 v9, v55, v203, v9
	v_lshlrev_b32_e32 v200, 16, v128
	v_and_b32_e32 v201, 0xffff0000, v128
	v_lshlrev_b32_e32 v202, 16, v129
	v_and_b32_e32 v203, 0xffff0000, v129
	v_fma_f32 v6, v54, v200, v6
	v_fma_f32 v7, v54, v201, v7
	v_fma_f32 v8, v54, v202, v8
	v_fma_f32 v9, v54, v203, v9
	v_lshlrev_b32_e32 v200, 16, v126
	v_and_b32_e32 v201, 0xffff0000, v126
	v_lshlrev_b32_e32 v202, 16, v127
	v_and_b32_e32 v203, 0xffff0000, v127
	v_fma_f32 v6, v53, v200, v6
	v_fma_f32 v7, v53, v201, v7
	v_fma_f32 v8, v53, v202, v8
	v_fma_f32 v9, v53, v203, v9
	v_lshlrev_b32_e32 v200, 16, v124
	v_and_b32_e32 v201, 0xffff0000, v124
	v_lshlrev_b32_e32 v202, 16, v125
	v_and_b32_e32 v203, 0xffff0000, v125
	v_fma_f32 v6, v52, v200, v6
	v_fma_f32 v7, v52, v201, v7
	v_fma_f32 v8, v52, v202, v8
	v_fma_f32 v9, v52, v203, v9
	v_lshlrev_b32_e32 v200, 16, v122
	v_and_b32_e32 v201, 0xffff0000, v122
	v_lshlrev_b32_e32 v202, 16, v123
	v_and_b32_e32 v203, 0xffff0000, v123
	v_fma_f32 v6, v51, v200, v6
	v_fma_f32 v7, v51, v201, v7
	v_fma_f32 v8, v51, v202, v8
	v_fma_f32 v9, v51, v203, v9
	v_lshlrev_b32_e32 v200, 16, v120
	v_and_b32_e32 v201, 0xffff0000, v120
	v_lshlrev_b32_e32 v202, 16, v121
	v_and_b32_e32 v203, 0xffff0000, v121
	v_fma_f32 v6, v50, v200, v6
	v_fma_f32 v7, v50, v201, v7
	v_fma_f32 v8, v50, v202, v8
	v_fma_f32 v9, v50, v203, v9
	v_lshlrev_b32_e32 v200, 16, v118
	v_and_b32_e32 v201, 0xffff0000, v118
	v_lshlrev_b32_e32 v202, 16, v119
	v_and_b32_e32 v203, 0xffff0000, v119
	v_fma_f32 v6, v49, v200, v6
	v_fma_f32 v7, v49, v201, v7
	v_fma_f32 v8, v49, v202, v8
	v_fma_f32 v9, v49, v203, v9
	v_lshlrev_b32_e32 v200, 16, v116
	v_and_b32_e32 v201, 0xffff0000, v116
	v_lshlrev_b32_e32 v202, 16, v117
	v_and_b32_e32 v203, 0xffff0000, v117
	v_fma_f32 v6, v48, v200, v6
	v_fma_f32 v7, v48, v201, v7
	v_fma_f32 v8, v48, v202, v8
	v_fma_f32 v9, v48, v203, v9
	v_lshlrev_b32_e32 v200, 16, v114
	v_and_b32_e32 v201, 0xffff0000, v114
	v_lshlrev_b32_e32 v202, 16, v115
	v_and_b32_e32 v203, 0xffff0000, v115
	v_fma_f32 v6, v47, v200, v6
	v_fma_f32 v7, v47, v201, v7
	v_fma_f32 v8, v47, v202, v8
	v_fma_f32 v9, v47, v203, v9
	v_lshlrev_b32_e32 v200, 16, v112
	v_and_b32_e32 v201, 0xffff0000, v112
	v_lshlrev_b32_e32 v202, 16, v113
	v_and_b32_e32 v203, 0xffff0000, v113
	v_fma_f32 v6, v46, v200, v6
	v_fma_f32 v7, v46, v201, v7
	v_fma_f32 v8, v46, v202, v8
	v_fma_f32 v9, v46, v203, v9
	v_lshlrev_b32_e32 v200, 16, v110
	v_and_b32_e32 v201, 0xffff0000, v110
	v_lshlrev_b32_e32 v202, 16, v111
	v_and_b32_e32 v203, 0xffff0000, v111
	v_fma_f32 v6, v45, v200, v6
	v_fma_f32 v7, v45, v201, v7
	v_fma_f32 v8, v45, v202, v8
	v_fma_f32 v9, v45, v203, v9
	v_lshlrev_b32_e32 v200, 16, v108
	v_and_b32_e32 v201, 0xffff0000, v108
	v_lshlrev_b32_e32 v202, 16, v109
	v_and_b32_e32 v203, 0xffff0000, v109
	v_fma_f32 v6, v44, v200, v6
	v_fma_f32 v7, v44, v201, v7
	v_fma_f32 v8, v44, v202, v8
	v_fma_f32 v9, v44, v203, v9
	v_lshlrev_b32_e32 v200, 16, v106
	v_and_b32_e32 v201, 0xffff0000, v106
	v_lshlrev_b32_e32 v202, 16, v107
	v_and_b32_e32 v203, 0xffff0000, v107
	v_fma_f32 v6, v43, v200, v6
	v_fma_f32 v7, v43, v201, v7
	v_fma_f32 v8, v43, v202, v8
	v_fma_f32 v9, v43, v203, v9
	v_lshlrev_b32_e32 v200, 16, v104
	v_and_b32_e32 v201, 0xffff0000, v104
	v_lshlrev_b32_e32 v202, 16, v105
	v_and_b32_e32 v203, 0xffff0000, v105
	v_fma_f32 v6, v42, v200, v6
	v_fma_f32 v7, v42, v201, v7
	v_fma_f32 v8, v42, v202, v8
	v_fma_f32 v9, v42, v203, v9
	v_lshlrev_b32_e32 v200, 16, v102
	v_and_b32_e32 v201, 0xffff0000, v102
	v_lshlrev_b32_e32 v202, 16, v103
	v_and_b32_e32 v203, 0xffff0000, v103
	v_fma_f32 v6, v41, v200, v6
	v_fma_f32 v7, v41, v201, v7
	v_fma_f32 v8, v41, v202, v8
	v_fma_f32 v9, v41, v203, v9
	v_lshlrev_b32_e32 v200, 16, v100
	v_and_b32_e32 v201, 0xffff0000, v100
	v_lshlrev_b32_e32 v202, 16, v101
	v_and_b32_e32 v203, 0xffff0000, v101
	v_fma_f32 v6, v40, v200, v6
	v_fma_f32 v7, v40, v201, v7
	v_fma_f32 v8, v40, v202, v8
	v_fma_f32 v9, v40, v203, v9
	s_waitcnt vmcnt(31)
; __device__ __forceinline__ unsigned pk2(float lo, float hi) { return pg8::cvt_pk_bf16(lo, hi); }
; __device__ __forceinline__ f32x4 ld4bf(const bf16* p) { const v2u w = *(const v2u*)p; return (f32x4){bf_lo(w.x), bf_hi(w.x), bf_lo(w.y), bf_hi(w.y)}; }
; __device__ __forceinline__ void pool_prep(const bf16* X, const float* ss, const float* gain, bf16* PB, LAS unsigned char* lds, int vcu, int G, int tid) {
;     ...
;         for (int i = 0; i < 32; ++i) { const int row = ra + i, t = row - bstart;
;             const f32x4 xn = ld4bf(xp + (size_t)row * DM) * rsl[row - r0 + 16];
;             f32x4 old = {0.f, 0.f, 0.f, 0.f};
;             if (t >= w) old = ld4bf(xp + (size_t)(row - w) * DM) * rsl[row - w - r0 + 16];
;             S = S + xn - old;
;             const int cnt = (t + 1 < w) ? t + 1 : w;
;             const f32x4 p = (S * (1.0f / (float)cnt) - xn) * gn;
;             v2u o; o.x = pk2(p[0], p[1]); o.y = pk2(p[2], p[3]); *(v2u*)(PB + (size_t)row * DM + 4 * q) = o; }
	v_lshlrev_b32_e32 v200, 16, v132
	v_and_b32_e32 v201, 0xffff0000, v132
	v_lshlrev_b32_e32 v202, 16, v133
	v_and_b32_e32 v203, 0xffff0000, v133
	v_mul_f32_e32 v204, v56, v200
	v_mul_f32_e32 v205, v56, v201
	v_mul_f32_e32 v206, v56, v202
	v_mul_f32_e32 v207, v56, v203
	v_fma_f32 v6, v56, v200, v6
	v_fma_f32 v7, v56, v201, v7
	v_fma_f32 v8, v56, v202, v8
	v_fma_f32 v9, v56, v203, v9
	v_lshlrev_b32_e32 v88, 16, v100
	v_and_b32_e32 v89, 0xffff0000, v100
	v_lshlrev_b32_e32 v90, 16, v101
	v_and_b32_e32 v91, 0xffff0000, v101
	v_mul_f32_e32 v88, v40, v88
	v_mul_f32_e32 v89, v40, v89
	v_mul_f32_e32 v90, v40, v90
	v_mul_f32_e32 v91, v40, v91
	v_sub_f32_e32 v6, v6, v88
	v_sub_f32_e32 v7, v7, v89
	v_sub_f32_e32 v8, v8, v90
	v_sub_f32_e32 v9, v9, v91
	v_add_u32_e32 v92, 1, v20
	v_min_i32_e32 v92, v92, v32
	v_cvt_f32_i32_e32 v92, v92
	v_div_scale_f32 v26, s[0:1], v92, v92, 1.0
	v_rcp_f32_e32 v27, v26
	s_nop 0
	v_fma_f32 v28, -v26, v27, 1.0
	v_fmac_f32_e32 v27, v28, v27
	v_div_scale_f32 v28, vcc, 1.0, v92, 1.0
	v_mul_f32_e32 v29, v28, v27
	v_fma_f32 v30, -v26, v29, v28
	v_fmac_f32_e32 v29, v30, v27
	v_fma_f32 v26, -v26, v29, v28
	s_nop 1
	v_div_fmas_f32 v93, v26, v27, v29
	v_div_fixup_f32 v93, v93, v92, 1.0
	v_fma_f32 v214, v93, v6, -v204
	v_fma_f32 v215, v93, v7, -v205
	v_fma_f32 v216, v93, v8, -v206
	v_fma_f32 v217, v93, v9, -v207
	v_mul_f32_e32 v214, v2, v214
	v_mul_f32_e32 v215, v3, v215
	v_mul_f32_e32 v216, v4, v216
	v_mul_f32_e32 v217, v5, v217
	v_cvt_pk_bf16_f32 v218, v214, v215
	v_cvt_pk_bf16_f32 v219, v216, v217
	global_store_dwordx2 v[24:25], v[218:219], off sc1
	s_waitcnt vmcnt(31)
	v_lshlrev_b32_e32 v200, 16, v134
	v_and_b32_e32 v201, 0xffff0000, v134
	v_lshlrev_b32_e32 v202, 16, v135
	v_and_b32_e32 v203, 0xffff0000, v135
	v_mul_f32_e32 v204, v57, v200
	v_mul_f32_e32 v205, v57, v201
	v_mul_f32_e32 v206, v57, v202
	v_mul_f32_e32 v207, v57, v203
	v_fma_f32 v6, v57, v200, v6
	v_fma_f32 v7, v57, v201, v7
	v_fma_f32 v8, v57, v202, v8
	v_fma_f32 v9, v57, v203, v9
	v_lshlrev_b32_e32 v88, 16, v102
	v_and_b32_e32 v89, 0xffff0000, v102
	v_lshlrev_b32_e32 v90, 16, v103
	v_and_b32_e32 v91, 0xffff0000, v103
	v_mul_f32_e32 v88, v41, v88
	v_mul_f32_e32 v89, v41, v89
	v_mul_f32_e32 v90, v41, v90
	v_mul_f32_e32 v91, v41, v91
	v_sub_f32_e32 v6, v6, v88
	v_sub_f32_e32 v7, v7, v89
	v_sub_f32_e32 v8, v8, v90
	v_sub_f32_e32 v9, v9, v91
	v_add_u32_e32 v92, 2, v20
	v_min_i32_e32 v92, v92, v32
	v_cvt_f32_i32_e32 v92, v92
	v_div_scale_f32 v26, s[0:1], v92, v92, 1.0
	v_rcp_f32_e32 v27, v26
	s_nop 0
	v_fma_f32 v28, -v26, v27, 1.0
	v_fmac_f32_e32 v27, v28, v27
	v_div_scale_f32 v28, vcc, 1.0, v92, 1.0
	v_mul_f32_e32 v29, v28, v27
	v_fma_f32 v30, -v26, v29, v28
	v_fmac_f32_e32 v29, v30, v27
	v_fma_f32 v26, -v26, v29, v28
	s_nop 1
	v_div_fmas_f32 v93, v26, v27, v29
	v_div_fixup_f32 v93, v93, v92, 1.0
	v_fma_f32 v214, v93, v6, -v204
	v_fma_f32 v215, v93, v7, -v205
	v_fma_f32 v216, v93, v8, -v206
	v_fma_f32 v217, v93, v9, -v207
	v_mul_f32_e32 v214, v2, v214
	v_mul_f32_e32 v215, v3, v215
	v_mul_f32_e32 v216, v4, v216
	v_mul_f32_e32 v217, v5, v217
	v_cvt_pk_bf16_f32 v218, v214, v215
	v_cvt_pk_bf16_f32 v219, v216, v217
	global_store_dwordx2 v[24:25], v[218:219], off offset:2048 sc1
	s_mov_b64 s[0:1], 0x1000
	v_lshl_add_u64 v[24:25], v[24:25], 0, s[0:1]
	s_waitcnt vmcnt(31)
	v_lshlrev_b32_e32 v200, 16, v136
	v_and_b32_e32 v201, 0xffff0000, v136
	v_lshlrev_b32_e32 v202, 16, v137
	v_and_b32_e32 v203, 0xffff0000, v137
	v_mul_f32_e32 v204, v58, v200
	v_mul_f32_e32 v205, v58, v201
	v_mul_f32_e32 v206, v58, v202
	v_mul_f32_e32 v207, v58, v203
	v_fma_f32 v6, v58, v200, v6
	v_fma_f32 v7, v58, v201, v7
	v_fma_f32 v8, v58, v202, v8
	v_fma_f32 v9, v58, v203, v9
	v_lshlrev_b32_e32 v88, 16, v104
	v_and_b32_e32 v89, 0xffff0000, v104
	v_lshlrev_b32_e32 v90, 16, v105
	v_and_b32_e32 v91, 0xffff0000, v105
	v_mul_f32_e32 v88, v42, v88
	v_mul_f32_e32 v89, v42, v89
	v_mul_f32_e32 v90, v42, v90
	v_mul_f32_e32 v91, v42, v91
	v_sub_f32_e32 v6, v6, v88
	v_sub_f32_e32 v7, v7, v89
	v_sub_f32_e32 v8, v8, v90
	v_sub_f32_e32 v9, v9, v91
	v_add_u32_e32 v92, 3, v20
	v_min_i32_e32 v92, v92, v32
	v_cvt_f32_i32_e32 v92, v92
	v_div_scale_f32 v26, s[0:1], v92, v92, 1.0
	v_rcp_f32_e32 v27, v26
	s_nop 0
	v_fma_f32 v28, -v26, v27, 1.0
	v_fmac_f32_e32 v27, v28, v27
	v_div_scale_f32 v28, vcc, 1.0, v92, 1.0
	v_mul_f32_e32 v29, v28, v27
	v_fma_f32 v30, -v26, v29, v28
	v_fmac_f32_e32 v29, v30, v27
	v_fma_f32 v26, -v26, v29, v28
	s_nop 1
	v_div_fmas_f32 v93, v26, v27, v29
	v_div_fixup_f32 v93, v93, v92, 1.0
	v_fma_f32 v214, v93, v6, -v204
	v_fma_f32 v215, v93, v7, -v205
	v_fma_f32 v216, v93, v8, -v206
	v_fma_f32 v217, v93, v9, -v207
	v_mul_f32_e32 v214, v2, v214
	v_mul_f32_e32 v215, v3, v215
	v_mul_f32_e32 v216, v4, v216
	v_mul_f32_e32 v217, v5, v217
	v_cvt_pk_bf16_f32 v218, v214, v215
	v_cvt_pk_bf16_f32 v219, v216, v217
	global_store_dwordx2 v[24:25], v[218:219], off sc1
	s_waitcnt vmcnt(31)
; __device__ __forceinline__ unsigned pk2(float lo, float hi) { return pg8::cvt_pk_bf16(lo, hi); }
; __device__ __forceinline__ f32x4 ld4bf(const bf16* p) { const v2u w = *(const v2u*)p; return (f32x4){bf_lo(w.x), bf_hi(w.x), bf_lo(w.y), bf_hi(w.y)}; }
; __device__ __forceinline__ void pool_prep(const bf16* X, const float* ss, const float* gain, bf16* PB, LAS unsigned char* lds, int vcu, int G, int tid) {
;     ...
;         for (int i = 0; i < 32; ++i) { const int row = ra + i, t = row - bstart;
;             const f32x4 xn = ld4bf(xp + (size_t)row * DM) * rsl[row - r0 + 16];
;             f32x4 old = {0.f, 0.f, 0.f, 0.f};
;             if (t >= w) old = ld4bf(xp + (size_t)(row - w) * DM) * rsl[row - w - r0 + 16];
;             S = S + xn - old;
;             const int cnt = (t + 1 < w) ? t + 1 : w;
;             const f32x4 p = (S * (1.0f / (float)cnt) - xn) * gn;
;             v2u o; o.x = pk2(p[0], p[1]); o.y = pk2(p[2], p[3]); *(v2u*)(PB + (size_t)row * DM + 4 * q) = o; }
	v_lshlrev_b32_e32 v200, 16, v138
	v_and_b32_e32 v201, 0xffff0000, v138
	v_lshlrev_b32_e32 v202, 16, v139
	v_and_b32_e32 v203, 0xffff0000, v139
	v_mul_f32_e32 v204, v59, v200
	v_mul_f32_e32 v205, v59, v201
	v_mul_f32_e32 v206, v59, v202
	v_mul_f32_e32 v207, v59, v203
	v_fma_f32 v6, v59, v200, v6
	v_fma_f32 v7, v59, v201, v7
	v_fma_f32 v8, v59, v202, v8
	v_fma_f32 v9, v59, v203, v9
	v_lshlrev_b32_e32 v88, 16, v106
	v_and_b32_e32 v89, 0xffff0000, v106
	v_lshlrev_b32_e32 v90, 16, v107
	v_and_b32_e32 v91, 0xffff0000, v107
	v_mul_f32_e32 v88, v43, v88
	v_mul_f32_e32 v89, v43, v89
	v_mul_f32_e32 v90, v43, v90
	v_mul_f32_e32 v91, v43, v91
	v_sub_f32_e32 v6, v6, v88
	v_sub_f32_e32 v7, v7, v89
	v_sub_f32_e32 v8, v8, v90
	v_sub_f32_e32 v9, v9, v91
	v_add_u32_e32 v92, 4, v20
	v_min_i32_e32 v92, v92, v32
	v_cvt_f32_i32_e32 v92, v92
	v_div_scale_f32 v26, s[0:1], v92, v92, 1.0
	v_rcp_f32_e32 v27, v26
	s_nop 0
	v_fma_f32 v28, -v26, v27, 1.0
	v_fmac_f32_e32 v27, v28, v27
	v_div_scale_f32 v28, vcc, 1.0, v92, 1.0
	v_mul_f32_e32 v29, v28, v27
	v_fma_f32 v30, -v26, v29, v28
	v_fmac_f32_e32 v29, v30, v27
	v_fma_f32 v26, -v26, v29, v28
	s_nop 1
	v_div_fmas_f32 v93, v26, v27, v29
	v_div_fixup_f32 v93, v93, v92, 1.0
	v_fma_f32 v214, v93, v6, -v204
	v_fma_f32 v215, v93, v7, -v205
	v_fma_f32 v216, v93, v8, -v206
	v_fma_f32 v217, v93, v9, -v207
	v_mul_f32_e32 v214, v2, v214
	v_mul_f32_e32 v215, v3, v215
	v_mul_f32_e32 v216, v4, v216
	v_mul_f32_e32 v217, v5, v217
	v_cvt_pk_bf16_f32 v218, v214, v215
	v_cvt_pk_bf16_f32 v219, v216, v217
	global_store_dwordx2 v[24:25], v[218:219], off offset:2048 sc1
	s_mov_b64 s[0:1], 0x1000
	v_lshl_add_u64 v[24:25], v[24:25], 0, s[0:1]
	s_waitcnt vmcnt(31)
	v_lshlrev_b32_e32 v200, 16, v140
	v_and_b32_e32 v201, 0xffff0000, v140
	v_lshlrev_b32_e32 v202, 16, v141
	v_and_b32_e32 v203, 0xffff0000, v141
	v_mul_f32_e32 v204, v60, v200
	v_mul_f32_e32 v205, v60, v201
	v_mul_f32_e32 v206, v60, v202
	v_mul_f32_e32 v207, v60, v203
	v_fma_f32 v6, v60, v200, v6
	v_fma_f32 v7, v60, v201, v7
	v_fma_f32 v8, v60, v202, v8
	v_fma_f32 v9, v60, v203, v9
	v_lshlrev_b32_e32 v88, 16, v108
	v_and_b32_e32 v89, 0xffff0000, v108
	v_lshlrev_b32_e32 v90, 16, v109
	v_and_b32_e32 v91, 0xffff0000, v109
	v_mul_f32_e32 v88, v44, v88
	v_mul_f32_e32 v89, v44, v89
	v_mul_f32_e32 v90, v44, v90
	v_mul_f32_e32 v91, v44, v91
	v_sub_f32_e32 v6, v6, v88
	v_sub_f32_e32 v7, v7, v89
	v_sub_f32_e32 v8, v8, v90
	v_sub_f32_e32 v9, v9, v91
	v_add_u32_e32 v92, 5, v20
	v_min_i32_e32 v92, v92, v32
	v_cvt_f32_i32_e32 v92, v92
	v_div_scale_f32 v26, s[0:1], v92, v92, 1.0
	v_rcp_f32_e32 v27, v26
	s_nop 0
	v_fma_f32 v28, -v26, v27, 1.0
	v_fmac_f32_e32 v27, v28, v27
	v_div_scale_f32 v28, vcc, 1.0, v92, 1.0
	v_mul_f32_e32 v29, v28, v27
	v_fma_f32 v30, -v26, v29, v28
	v_fmac_f32_e32 v29, v30, v27
	v_fma_f32 v26, -v26, v29, v28
	s_nop 1
	v_div_fmas_f32 v93, v26, v27, v29
	v_div_fixup_f32 v93, v93, v92, 1.0
	v_fma_f32 v214, v93, v6, -v204
	v_fma_f32 v215, v93, v7, -v205
	v_fma_f32 v216, v93, v8, -v206
	v_fma_f32 v217, v93, v9, -v207
	v_mul_f32_e32 v214, v2, v214
	v_mul_f32_e32 v215, v3, v215
	v_mul_f32_e32 v216, v4, v216
	v_mul_f32_e32 v217, v5, v217
	v_cvt_pk_bf16_f32 v218, v214, v215
	v_cvt_pk_bf16_f32 v219, v216, v217
	global_store_dwordx2 v[24:25], v[218:219], off sc1
	s_waitcnt vmcnt(31)
	v_lshlrev_b32_e32 v200, 16, v142
	v_and_b32_e32 v201, 0xffff0000, v142
	v_lshlrev_b32_e32 v202, 16, v143
	v_and_b32_e32 v203, 0xffff0000, v143
	v_mul_f32_e32 v204, v61, v200
	v_mul_f32_e32 v205, v61, v201
	v_mul_f32_e32 v206, v61, v202
	v_mul_f32_e32 v207, v61, v203
	v_fma_f32 v6, v61, v200, v6
	v_fma_f32 v7, v61, v201, v7
	v_fma_f32 v8, v61, v202, v8
	v_fma_f32 v9, v61, v203, v9
	v_lshlrev_b32_e32 v88, 16, v110
	v_and_b32_e32 v89, 0xffff0000, v110
	v_lshlrev_b32_e32 v90, 16, v111
	v_and_b32_e32 v91, 0xffff0000, v111
	v_mul_f32_e32 v88, v45, v88
	v_mul_f32_e32 v89, v45, v89
	v_mul_f32_e32 v90, v45, v90
	v_mul_f32_e32 v91, v45, v91
	v_sub_f32_e32 v6, v6, v88
	v_sub_f32_e32 v7, v7, v89
	v_sub_f32_e32 v8, v8, v90
	v_sub_f32_e32 v9, v9, v91
	v_add_u32_e32 v92, 6, v20
	v_min_i32_e32 v92, v92, v32
	v_cvt_f32_i32_e32 v92, v92
	v_div_scale_f32 v26, s[0:1], v92, v92, 1.0
	v_rcp_f32_e32 v27, v26
	s_nop 0
	v_fma_f32 v28, -v26, v27, 1.0
	v_fmac_f32_e32 v27, v28, v27
	v_div_scale_f32 v28, vcc, 1.0, v92, 1.0
	v_mul_f32_e32 v29, v28, v27
	v_fma_f32 v30, -v26, v29, v28
	v_fmac_f32_e32 v29, v30, v27
	v_fma_f32 v26, -v26, v29, v28
	s_nop 1
	v_div_fmas_f32 v93, v26, v27, v29
	v_div_fixup_f32 v93, v93, v92, 1.0
	v_fma_f32 v214, v93, v6, -v204
	v_fma_f32 v215, v93, v7, -v205
	v_fma_f32 v216, v93, v8, -v206
	v_fma_f32 v217, v93, v9, -v207
	v_mul_f32_e32 v214, v2, v214
	v_mul_f32_e32 v215, v3, v215
	v_mul_f32_e32 v216, v4, v216
	v_mul_f32_e32 v217, v5, v217
	v_cvt_pk_bf16_f32 v218, v214, v215
	v_cvt_pk_bf16_f32 v219, v216, v217
	global_store_dwordx2 v[24:25], v[218:219], off offset:2048 sc1
	s_mov_b64 s[0:1], 0x1000
	v_lshl_add_u64 v[24:25], v[24:25], 0, s[0:1]
	s_waitcnt vmcnt(31)
; __device__ __forceinline__ unsigned pk2(float lo, float hi) { return pg8::cvt_pk_bf16(lo, hi); }
; __device__ __forceinline__ f32x4 ld4bf(const bf16* p) { const v2u w = *(const v2u*)p; return (f32x4){bf_lo(w.x), bf_hi(w.x), bf_lo(w.y), bf_hi(w.y)}; }
; __device__ __forceinline__ void pool_prep(const bf16* X, const float* ss, const float* gain, bf16* PB, LAS unsigned char* lds, int vcu, int G, int tid) {
;     ...
;         for (int i = 0; i < 32; ++i) { const int row = ra + i, t = row - bstart;
;             const f32x4 xn = ld4bf(xp + (size_t)row * DM) * rsl[row - r0 + 16];
;             f32x4 old = {0.f, 0.f, 0.f, 0.f};
;             if (t >= w) old = ld4bf(xp + (size_t)(row - w) * DM) * rsl[row - w - r0 + 16];
;             S = S + xn - old;
;             const int cnt = (t + 1 < w) ? t + 1 : w;
;             const f32x4 p = (S * (1.0f / (float)cnt) - xn) * gn;
;             v2u o; o.x = pk2(p[0], p[1]); o.y = pk2(p[2], p[3]); *(v2u*)(PB + (size_t)row * DM + 4 * q) = o; }
	v_lshlrev_b32_e32 v200, 16, v144
	v_and_b32_e32 v201, 0xffff0000, v144
	v_lshlrev_b32_e32 v202, 16, v145
	v_and_b32_e32 v203, 0xffff0000, v145
	v_mul_f32_e32 v204, v62, v200
	v_mul_f32_e32 v205, v62, v201
	v_mul_f32_e32 v206, v62, v202
	v_mul_f32_e32 v207, v62, v203
	v_fma_f32 v6, v62, v200, v6
	v_fma_f32 v7, v62, v201, v7
	v_fma_f32 v8, v62, v202, v8
	v_fma_f32 v9, v62, v203, v9
	v_lshlrev_b32_e32 v88, 16, v112
	v_and_b32_e32 v89, 0xffff0000, v112
	v_lshlrev_b32_e32 v90, 16, v113
	v_and_b32_e32 v91, 0xffff0000, v113
	v_mul_f32_e32 v88, v46, v88
	v_mul_f32_e32 v89, v46, v89
	v_mul_f32_e32 v90, v46, v90
	v_mul_f32_e32 v91, v46, v91
	v_sub_f32_e32 v6, v6, v88
	v_sub_f32_e32 v7, v7, v89
	v_sub_f32_e32 v8, v8, v90
	v_sub_f32_e32 v9, v9, v91
	v_add_u32_e32 v92, 7, v20
	v_min_i32_e32 v92, v92, v32
	v_cvt_f32_i32_e32 v92, v92
	v_div_scale_f32 v26, s[0:1], v92, v92, 1.0
	v_rcp_f32_e32 v27, v26
	s_nop 0
	v_fma_f32 v28, -v26, v27, 1.0
	v_fmac_f32_e32 v27, v28, v27
	v_div_scale_f32 v28, vcc, 1.0, v92, 1.0
	v_mul_f32_e32 v29, v28, v27
	v_fma_f32 v30, -v26, v29, v28
	v_fmac_f32_e32 v29, v30, v27
	v_fma_f32 v26, -v26, v29, v28
	s_nop 1
	v_div_fmas_f32 v93, v26, v27, v29
	v_div_fixup_f32 v93, v93, v92, 1.0
	v_fma_f32 v214, v93, v6, -v204
	v_fma_f32 v215, v93, v7, -v205
	v_fma_f32 v216, v93, v8, -v206
	v_fma_f32 v217, v93, v9, -v207
	v_mul_f32_e32 v214, v2, v214
	v_mul_f32_e32 v215, v3, v215
	v_mul_f32_e32 v216, v4, v216
	v_mul_f32_e32 v217, v5, v217
	v_cvt_pk_bf16_f32 v218, v214, v215
	v_cvt_pk_bf16_f32 v219, v216, v217
	global_store_dwordx2 v[24:25], v[218:219], off sc1
	s_waitcnt vmcnt(31)
	v_lshlrev_b32_e32 v200, 16, v146
	v_and_b32_e32 v201, 0xffff0000, v146
	v_lshlrev_b32_e32 v202, 16, v147
	v_and_b32_e32 v203, 0xffff0000, v147
	v_mul_f32_e32 v204, v63, v200
	v_mul_f32_e32 v205, v63, v201
	v_mul_f32_e32 v206, v63, v202
	v_mul_f32_e32 v207, v63, v203
	v_fma_f32 v6, v63, v200, v6
	v_fma_f32 v7, v63, v201, v7
	v_fma_f32 v8, v63, v202, v8
	v_fma_f32 v9, v63, v203, v9
	v_lshlrev_b32_e32 v88, 16, v114
	v_and_b32_e32 v89, 0xffff0000, v114
	v_lshlrev_b32_e32 v90, 16, v115
	v_and_b32_e32 v91, 0xffff0000, v115
	v_mul_f32_e32 v88, v47, v88
	v_mul_f32_e32 v89, v47, v89
	v_mul_f32_e32 v90, v47, v90
	v_mul_f32_e32 v91, v47, v91
	v_sub_f32_e32 v6, v6, v88
	v_sub_f32_e32 v7, v7, v89
	v_sub_f32_e32 v8, v8, v90
	v_sub_f32_e32 v9, v9, v91
	v_add_u32_e32 v92, 8, v20
	v_min_i32_e32 v92, v92, v32
	v_cvt_f32_i32_e32 v92, v92
	v_div_scale_f32 v26, s[0:1], v92, v92, 1.0
	v_rcp_f32_e32 v27, v26
	s_nop 0
	v_fma_f32 v28, -v26, v27, 1.0
	v_fmac_f32_e32 v27, v28, v27
	v_div_scale_f32 v28, vcc, 1.0, v92, 1.0
	v_mul_f32_e32 v29, v28, v27
	v_fma_f32 v30, -v26, v29, v28
	v_fmac_f32_e32 v29, v30, v27
	v_fma_f32 v26, -v26, v29, v28
	s_nop 1
	v_div_fmas_f32 v93, v26, v27, v29
	v_div_fixup_f32 v93, v93, v92, 1.0
	v_fma_f32 v214, v93, v6, -v204
	v_fma_f32 v215, v93, v7, -v205
	v_fma_f32 v216, v93, v8, -v206
	v_fma_f32 v217, v93, v9, -v207
	v_mul_f32_e32 v214, v2, v214
	v_mul_f32_e32 v215, v3, v215
	v_mul_f32_e32 v216, v4, v216
	v_mul_f32_e32 v217, v5, v217
	v_cvt_pk_bf16_f32 v218, v214, v215
	v_cvt_pk_bf16_f32 v219, v216, v217
	global_store_dwordx2 v[24:25], v[218:219], off offset:2048 sc1
	s_mov_b64 s[0:1], 0x1000
	v_lshl_add_u64 v[24:25], v[24:25], 0, s[0:1]
	s_waitcnt vmcnt(31)
	v_lshlrev_b32_e32 v200, 16, v148
	v_and_b32_e32 v201, 0xffff0000, v148
	v_lshlrev_b32_e32 v202, 16, v149
	v_and_b32_e32 v203, 0xffff0000, v149
	v_mul_f32_e32 v204, v64, v200
	v_mul_f32_e32 v205, v64, v201
	v_mul_f32_e32 v206, v64, v202
	v_mul_f32_e32 v207, v64, v203
	v_fma_f32 v6, v64, v200, v6
	v_fma_f32 v7, v64, v201, v7
	v_fma_f32 v8, v64, v202, v8
	v_fma_f32 v9, v64, v203, v9
	v_lshlrev_b32_e32 v88, 16, v116
	v_and_b32_e32 v89, 0xffff0000, v116
	v_lshlrev_b32_e32 v90, 16, v117
	v_and_b32_e32 v91, 0xffff0000, v117
	v_mul_f32_e32 v88, v48, v88
	v_mul_f32_e32 v89, v48, v89
	v_mul_f32_e32 v90, v48, v90
	v_mul_f32_e32 v91, v48, v91
	v_sub_f32_e32 v6, v6, v88
	v_sub_f32_e32 v7, v7, v89
	v_sub_f32_e32 v8, v8, v90
	v_sub_f32_e32 v9, v9, v91
	v_add_u32_e32 v92, 9, v20
	v_min_i32_e32 v92, v92, v32
	v_cvt_f32_i32_e32 v92, v92
	v_div_scale_f32 v26, s[0:1], v92, v92, 1.0
	v_rcp_f32_e32 v27, v26
	s_nop 0
	v_fma_f32 v28, -v26, v27, 1.0
	v_fmac_f32_e32 v27, v28, v27
	v_div_scale_f32 v28, vcc, 1.0, v92, 1.0
	v_mul_f32_e32 v29, v28, v27
	v_fma_f32 v30, -v26, v29, v28
	v_fmac_f32_e32 v29, v30, v27
	v_fma_f32 v26, -v26, v29, v28
	s_nop 1
	v_div_fmas_f32 v93, v26, v27, v29
	v_div_fixup_f32 v93, v93, v92, 1.0
	v_fma_f32 v214, v93, v6, -v204
	v_fma_f32 v215, v93, v7, -v205
	v_fma_f32 v216, v93, v8, -v206
	v_fma_f32 v217, v93, v9, -v207
	v_mul_f32_e32 v214, v2, v214
	v_mul_f32_e32 v215, v3, v215
	v_mul_f32_e32 v216, v4, v216
	v_mul_f32_e32 v217, v5, v217
	v_cvt_pk_bf16_f32 v218, v214, v215
	v_cvt_pk_bf16_f32 v219, v216, v217
	global_store_dwordx2 v[24:25], v[218:219], off sc1
	s_waitcnt vmcnt(31)
; __device__ __forceinline__ unsigned pk2(float lo, float hi) { return pg8::cvt_pk_bf16(lo, hi); }
; __device__ __forceinline__ f32x4 ld4bf(const bf16* p) { const v2u w = *(const v2u*)p; return (f32x4){bf_lo(w.x), bf_hi(w.x), bf_lo(w.y), bf_hi(w.y)}; }
; __device__ __forceinline__ void pool_prep(const bf16* X, const float* ss, const float* gain, bf16* PB, LAS unsigned char* lds, int vcu, int G, int tid) {
;     ...
;         for (int i = 0; i < 32; ++i) { const int row = ra + i, t = row - bstart;
;             const f32x4 xn = ld4bf(xp + (size_t)row * DM) * rsl[row - r0 + 16];
;             f32x4 old = {0.f, 0.f, 0.f, 0.f};
;             if (t >= w) old = ld4bf(xp + (size_t)(row - w) * DM) * rsl[row - w - r0 + 16];
;             S = S + xn - old;
;             const int cnt = (t + 1 < w) ? t + 1 : w;
;             const f32x4 p = (S * (1.0f / (float)cnt) - xn) * gn;
;             v2u o; o.x = pk2(p[0], p[1]); o.y = pk2(p[2], p[3]); *(v2u*)(PB + (size_t)row * DM + 4 * q) = o; }
	v_lshlrev_b32_e32 v200, 16, v150
	v_and_b32_e32 v201, 0xffff0000, v150
	v_lshlrev_b32_e32 v202, 16, v151
	v_and_b32_e32 v203, 0xffff0000, v151
	v_mul_f32_e32 v204, v65, v200
	v_mul_f32_e32 v205, v65, v201
	v_mul_f32_e32 v206, v65, v202
	v_mul_f32_e32 v207, v65, v203
	v_fma_f32 v6, v65, v200, v6
	v_fma_f32 v7, v65, v201, v7
	v_fma_f32 v8, v65, v202, v8
	v_fma_f32 v9, v65, v203, v9
	v_lshlrev_b32_e32 v88, 16, v118
	v_and_b32_e32 v89, 0xffff0000, v118
	v_lshlrev_b32_e32 v90, 16, v119
	v_and_b32_e32 v91, 0xffff0000, v119
	v_mul_f32_e32 v88, v49, v88
	v_mul_f32_e32 v89, v49, v89
	v_mul_f32_e32 v90, v49, v90
	v_mul_f32_e32 v91, v49, v91
	v_sub_f32_e32 v6, v6, v88
	v_sub_f32_e32 v7, v7, v89
	v_sub_f32_e32 v8, v8, v90
	v_sub_f32_e32 v9, v9, v91
	v_add_u32_e32 v92, 10, v20
	v_min_i32_e32 v92, v92, v32
	v_cvt_f32_i32_e32 v92, v92
	v_div_scale_f32 v26, s[0:1], v92, v92, 1.0
	v_rcp_f32_e32 v27, v26
	s_nop 0
	v_fma_f32 v28, -v26, v27, 1.0
	v_fmac_f32_e32 v27, v28, v27
	v_div_scale_f32 v28, vcc, 1.0, v92, 1.0
	v_mul_f32_e32 v29, v28, v27
	v_fma_f32 v30, -v26, v29, v28
	v_fmac_f32_e32 v29, v30, v27
	v_fma_f32 v26, -v26, v29, v28
	s_nop 1
	v_div_fmas_f32 v93, v26, v27, v29
	v_div_fixup_f32 v93, v93, v92, 1.0
	v_fma_f32 v214, v93, v6, -v204
	v_fma_f32 v215, v93, v7, -v205
	v_fma_f32 v216, v93, v8, -v206
	v_fma_f32 v217, v93, v9, -v207
	v_mul_f32_e32 v214, v2, v214
	v_mul_f32_e32 v215, v3, v215
	v_mul_f32_e32 v216, v4, v216
	v_mul_f32_e32 v217, v5, v217
	v_cvt_pk_bf16_f32 v218, v214, v215
	v_cvt_pk_bf16_f32 v219, v216, v217
	global_store_dwordx2 v[24:25], v[218:219], off offset:2048 sc1
	s_mov_b64 s[0:1], 0x1000
	v_lshl_add_u64 v[24:25], v[24:25], 0, s[0:1]
	s_waitcnt vmcnt(31)
	v_lshlrev_b32_e32 v200, 16, v152
	v_and_b32_e32 v201, 0xffff0000, v152
	v_lshlrev_b32_e32 v202, 16, v153
	v_and_b32_e32 v203, 0xffff0000, v153
	v_mul_f32_e32 v204, v66, v200
	v_mul_f32_e32 v205, v66, v201
	v_mul_f32_e32 v206, v66, v202
	v_mul_f32_e32 v207, v66, v203
	v_fma_f32 v6, v66, v200, v6
	v_fma_f32 v7, v66, v201, v7
	v_fma_f32 v8, v66, v202, v8
	v_fma_f32 v9, v66, v203, v9
	v_lshlrev_b32_e32 v88, 16, v120
	v_and_b32_e32 v89, 0xffff0000, v120
	v_lshlrev_b32_e32 v90, 16, v121
	v_and_b32_e32 v91, 0xffff0000, v121
	v_mul_f32_e32 v88, v50, v88
	v_mul_f32_e32 v89, v50, v89
	v_mul_f32_e32 v90, v50, v90
	v_mul_f32_e32 v91, v50, v91
	v_sub_f32_e32 v6, v6, v88
	v_sub_f32_e32 v7, v7, v89
	v_sub_f32_e32 v8, v8, v90
	v_sub_f32_e32 v9, v9, v91
	v_add_u32_e32 v92, 11, v20
	v_min_i32_e32 v92, v92, v32
	v_cvt_f32_i32_e32 v92, v92
	v_div_scale_f32 v26, s[0:1], v92, v92, 1.0
	v_rcp_f32_e32 v27, v26
	s_nop 0
	v_fma_f32 v28, -v26, v27, 1.0
	v_fmac_f32_e32 v27, v28, v27
	v_div_scale_f32 v28, vcc, 1.0, v92, 1.0
	v_mul_f32_e32 v29, v28, v27
	v_fma_f32 v30, -v26, v29, v28
	v_fmac_f32_e32 v29, v30, v27
	v_fma_f32 v26, -v26, v29, v28
	s_nop 1
	v_div_fmas_f32 v93, v26, v27, v29
	v_div_fixup_f32 v93, v93, v92, 1.0
	v_fma_f32 v214, v93, v6, -v204
	v_fma_f32 v215, v93, v7, -v205
	v_fma_f32 v216, v93, v8, -v206
	v_fma_f32 v217, v93, v9, -v207
	v_mul_f32_e32 v214, v2, v214
	v_mul_f32_e32 v215, v3, v215
	v_mul_f32_e32 v216, v4, v216
	v_mul_f32_e32 v217, v5, v217
	v_cvt_pk_bf16_f32 v218, v214, v215
	v_cvt_pk_bf16_f32 v219, v216, v217
	global_store_dwordx2 v[24:25], v[218:219], off sc1
	s_waitcnt vmcnt(31)
	v_lshlrev_b32_e32 v200, 16, v154
	v_and_b32_e32 v201, 0xffff0000, v154
	v_lshlrev_b32_e32 v202, 16, v155
	v_and_b32_e32 v203, 0xffff0000, v155
	v_mul_f32_e32 v204, v67, v200
	v_mul_f32_e32 v205, v67, v201
	v_mul_f32_e32 v206, v67, v202
	v_mul_f32_e32 v207, v67, v203
	v_fma_f32 v6, v67, v200, v6
	v_fma_f32 v7, v67, v201, v7
	v_fma_f32 v8, v67, v202, v8
	v_fma_f32 v9, v67, v203, v9
	v_lshlrev_b32_e32 v88, 16, v122
	v_and_b32_e32 v89, 0xffff0000, v122
	v_lshlrev_b32_e32 v90, 16, v123
	v_and_b32_e32 v91, 0xffff0000, v123
	v_mul_f32_e32 v88, v51, v88
	v_mul_f32_e32 v89, v51, v89
	v_mul_f32_e32 v90, v51, v90
	v_mul_f32_e32 v91, v51, v91
	v_sub_f32_e32 v6, v6, v88
	v_sub_f32_e32 v7, v7, v89
	v_sub_f32_e32 v8, v8, v90
	v_sub_f32_e32 v9, v9, v91
	v_add_u32_e32 v92, 12, v20
	v_min_i32_e32 v92, v92, v32
	v_cvt_f32_i32_e32 v92, v92
	v_div_scale_f32 v26, s[0:1], v92, v92, 1.0
	v_rcp_f32_e32 v27, v26
	s_nop 0
	v_fma_f32 v28, -v26, v27, 1.0
	v_fmac_f32_e32 v27, v28, v27
	v_div_scale_f32 v28, vcc, 1.0, v92, 1.0
	v_mul_f32_e32 v29, v28, v27
	v_fma_f32 v30, -v26, v29, v28
	v_fmac_f32_e32 v29, v30, v27
	v_fma_f32 v26, -v26, v29, v28
	s_nop 1
	v_div_fmas_f32 v93, v26, v27, v29
	v_div_fixup_f32 v93, v93, v92, 1.0
	v_fma_f32 v214, v93, v6, -v204
	v_fma_f32 v215, v93, v7, -v205
	v_fma_f32 v216, v93, v8, -v206
	v_fma_f32 v217, v93, v9, -v207
	v_mul_f32_e32 v214, v2, v214
	v_mul_f32_e32 v215, v3, v215
	v_mul_f32_e32 v216, v4, v216
	v_mul_f32_e32 v217, v5, v217
	v_cvt_pk_bf16_f32 v218, v214, v215
	v_cvt_pk_bf16_f32 v219, v216, v217
	global_store_dwordx2 v[24:25], v[218:219], off offset:2048 sc1
	s_mov_b64 s[0:1], 0x1000
	v_lshl_add_u64 v[24:25], v[24:25], 0, s[0:1]
	s_waitcnt vmcnt(31)
; __device__ __forceinline__ unsigned pk2(float lo, float hi) { return pg8::cvt_pk_bf16(lo, hi); }
; __device__ __forceinline__ f32x4 ld4bf(const bf16* p) { const v2u w = *(const v2u*)p; return (f32x4){bf_lo(w.x), bf_hi(w.x), bf_lo(w.y), bf_hi(w.y)}; }
; __device__ __forceinline__ void pool_prep(const bf16* X, const float* ss, const float* gain, bf16* PB, LAS unsigned char* lds, int vcu, int G, int tid) {
;     ...
;         for (int i = 0; i < 32; ++i) { const int row = ra + i, t = row - bstart;
;             const f32x4 xn = ld4bf(xp + (size_t)row * DM) * rsl[row - r0 + 16];
;             f32x4 old = {0.f, 0.f, 0.f, 0.f};
;             if (t >= w) old = ld4bf(xp + (size_t)(row - w) * DM) * rsl[row - w - r0 + 16];
;             S = S + xn - old;
;             const int cnt = (t + 1 < w) ? t + 1 : w;
;             const f32x4 p = (S * (1.0f / (float)cnt) - xn) * gn;
;             v2u o; o.x = pk2(p[0], p[1]); o.y = pk2(p[2], p[3]); *(v2u*)(PB + (size_t)row * DM + 4 * q) = o; }
	v_lshlrev_b32_e32 v200, 16, v156
	v_and_b32_e32 v201, 0xffff0000, v156
	v_lshlrev_b32_e32 v202, 16, v157
	v_and_b32_e32 v203, 0xffff0000, v157
	v_mul_f32_e32 v204, v68, v200
	v_mul_f32_e32 v205, v68, v201
	v_mul_f32_e32 v206, v68, v202
	v_mul_f32_e32 v207, v68, v203
	v_fma_f32 v6, v68, v200, v6
	v_fma_f32 v7, v68, v201, v7
	v_fma_f32 v8, v68, v202, v8
	v_fma_f32 v9, v68, v203, v9
	v_lshlrev_b32_e32 v88, 16, v124
	v_and_b32_e32 v89, 0xffff0000, v124
	v_lshlrev_b32_e32 v90, 16, v125
	v_and_b32_e32 v91, 0xffff0000, v125
	v_mul_f32_e32 v88, v52, v88
	v_mul_f32_e32 v89, v52, v89
	v_mul_f32_e32 v90, v52, v90
	v_mul_f32_e32 v91, v52, v91
	v_sub_f32_e32 v6, v6, v88
	v_sub_f32_e32 v7, v7, v89
	v_sub_f32_e32 v8, v8, v90
	v_sub_f32_e32 v9, v9, v91
	v_add_u32_e32 v92, 13, v20
	v_min_i32_e32 v92, v92, v32
	v_cvt_f32_i32_e32 v92, v92
	v_div_scale_f32 v26, s[0:1], v92, v92, 1.0
	v_rcp_f32_e32 v27, v26
	s_nop 0
	v_fma_f32 v28, -v26, v27, 1.0
	v_fmac_f32_e32 v27, v28, v27
	v_div_scale_f32 v28, vcc, 1.0, v92, 1.0
	v_mul_f32_e32 v29, v28, v27
	v_fma_f32 v30, -v26, v29, v28
	v_fmac_f32_e32 v29, v30, v27
	v_fma_f32 v26, -v26, v29, v28
	s_nop 1
	v_div_fmas_f32 v93, v26, v27, v29
	v_div_fixup_f32 v93, v93, v92, 1.0
	v_fma_f32 v214, v93, v6, -v204
	v_fma_f32 v215, v93, v7, -v205
	v_fma_f32 v216, v93, v8, -v206
	v_fma_f32 v217, v93, v9, -v207
	v_mul_f32_e32 v214, v2, v214
	v_mul_f32_e32 v215, v3, v215
	v_mul_f32_e32 v216, v4, v216
	v_mul_f32_e32 v217, v5, v217
	v_cvt_pk_bf16_f32 v218, v214, v215
	v_cvt_pk_bf16_f32 v219, v216, v217
	global_store_dwordx2 v[24:25], v[218:219], off sc1
	s_waitcnt vmcnt(31)
	v_lshlrev_b32_e32 v200, 16, v158
	v_and_b32_e32 v201, 0xffff0000, v158
	v_lshlrev_b32_e32 v202, 16, v159
	v_and_b32_e32 v203, 0xffff0000, v159
	v_mul_f32_e32 v204, v69, v200
	v_mul_f32_e32 v205, v69, v201
	v_mul_f32_e32 v206, v69, v202
	v_mul_f32_e32 v207, v69, v203
	v_fma_f32 v6, v69, v200, v6
	v_fma_f32 v7, v69, v201, v7
	v_fma_f32 v8, v69, v202, v8
	v_fma_f32 v9, v69, v203, v9
	v_lshlrev_b32_e32 v88, 16, v126
	v_and_b32_e32 v89, 0xffff0000, v126
	v_lshlrev_b32_e32 v90, 16, v127
	v_and_b32_e32 v91, 0xffff0000, v127
	v_mul_f32_e32 v88, v53, v88
	v_mul_f32_e32 v89, v53, v89
	v_mul_f32_e32 v90, v53, v90
	v_mul_f32_e32 v91, v53, v91
	v_sub_f32_e32 v6, v6, v88
	v_sub_f32_e32 v7, v7, v89
	v_sub_f32_e32 v8, v8, v90
	v_sub_f32_e32 v9, v9, v91
	v_add_u32_e32 v92, 14, v20
	v_min_i32_e32 v92, v92, v32
	v_cvt_f32_i32_e32 v92, v92
	v_div_scale_f32 v26, s[0:1], v92, v92, 1.0
	v_rcp_f32_e32 v27, v26
	s_nop 0
	v_fma_f32 v28, -v26, v27, 1.0
	v_fmac_f32_e32 v27, v28, v27
	v_div_scale_f32 v28, vcc, 1.0, v92, 1.0
	v_mul_f32_e32 v29, v28, v27
	v_fma_f32 v30, -v26, v29, v28
	v_fmac_f32_e32 v29, v30, v27
	v_fma_f32 v26, -v26, v29, v28
	s_nop 1
	v_div_fmas_f32 v93, v26, v27, v29
	v_div_fixup_f32 v93, v93, v92, 1.0
	v_fma_f32 v214, v93, v6, -v204
	v_fma_f32 v215, v93, v7, -v205
	v_fma_f32 v216, v93, v8, -v206
	v_fma_f32 v217, v93, v9, -v207
	v_mul_f32_e32 v214, v2, v214
	v_mul_f32_e32 v215, v3, v215
	v_mul_f32_e32 v216, v4, v216
	v_mul_f32_e32 v217, v5, v217
	v_cvt_pk_bf16_f32 v218, v214, v215
	v_cvt_pk_bf16_f32 v219, v216, v217
	global_store_dwordx2 v[24:25], v[218:219], off offset:2048 sc1
	s_mov_b64 s[0:1], 0x1000
	v_lshl_add_u64 v[24:25], v[24:25], 0, s[0:1]
	s_waitcnt vmcnt(31)
	v_lshlrev_b32_e32 v200, 16, v160
	v_and_b32_e32 v201, 0xffff0000, v160
	v_lshlrev_b32_e32 v202, 16, v161
	v_and_b32_e32 v203, 0xffff0000, v161
	v_mul_f32_e32 v204, v70, v200
	v_mul_f32_e32 v205, v70, v201
	v_mul_f32_e32 v206, v70, v202
	v_mul_f32_e32 v207, v70, v203
	v_fma_f32 v6, v70, v200, v6
	v_fma_f32 v7, v70, v201, v7
	v_fma_f32 v8, v70, v202, v8
	v_fma_f32 v9, v70, v203, v9
	v_lshlrev_b32_e32 v88, 16, v128
	v_and_b32_e32 v89, 0xffff0000, v128
	v_lshlrev_b32_e32 v90, 16, v129
	v_and_b32_e32 v91, 0xffff0000, v129
	v_mul_f32_e32 v88, v54, v88
	v_mul_f32_e32 v89, v54, v89
	v_mul_f32_e32 v90, v54, v90
	v_mul_f32_e32 v91, v54, v91
	v_sub_f32_e32 v6, v6, v88
	v_sub_f32_e32 v7, v7, v89
	v_sub_f32_e32 v8, v8, v90
	v_sub_f32_e32 v9, v9, v91
	v_add_u32_e32 v92, 15, v20
	v_min_i32_e32 v92, v92, v32
	v_cvt_f32_i32_e32 v92, v92
	v_div_scale_f32 v26, s[0:1], v92, v92, 1.0
	v_rcp_f32_e32 v27, v26
	s_nop 0
	v_fma_f32 v28, -v26, v27, 1.0
	v_fmac_f32_e32 v27, v28, v27
	v_div_scale_f32 v28, vcc, 1.0, v92, 1.0
	v_mul_f32_e32 v29, v28, v27
	v_fma_f32 v30, -v26, v29, v28
	v_fmac_f32_e32 v29, v30, v27
	v_fma_f32 v26, -v26, v29, v28
	s_nop 1
	v_div_fmas_f32 v93, v26, v27, v29
	v_div_fixup_f32 v93, v93, v92, 1.0
	v_fma_f32 v214, v93, v6, -v204
	v_fma_f32 v215, v93, v7, -v205
	v_fma_f32 v216, v93, v8, -v206
	v_fma_f32 v217, v93, v9, -v207
	v_mul_f32_e32 v214, v2, v214
	v_mul_f32_e32 v215, v3, v215
	v_mul_f32_e32 v216, v4, v216
	v_mul_f32_e32 v217, v5, v217
	v_cvt_pk_bf16_f32 v218, v214, v215
	v_cvt_pk_bf16_f32 v219, v216, v217
	global_store_dwordx2 v[24:25], v[218:219], off sc1
	s_waitcnt vmcnt(31)
	v_lshlrev_b32_e32 v200, 16, v162
	v_and_b32_e32 v201, 0xffff0000, v162
	v_lshlrev_b32_e32 v202, 16, v163
	v_and_b32_e32 v203, 0xffff0000, v163
	v_mul_f32_e32 v204, v71, v200
	v_mul_f32_e32 v205, v71, v201
	v_mul_f32_e32 v206, v71, v202
	v_mul_f32_e32 v207, v71, v203
	v_fma_f32 v6, v71, v200, v6
	v_fma_f32 v7, v71, v201, v7
	v_fma_f32 v8, v71, v202, v8
	v_fma_f32 v9, v71, v203, v9
	v_lshlrev_b32_e32 v88, 16, v130
	v_and_b32_e32 v89, 0xffff0000, v130
	v_lshlrev_b32_e32 v90, 16, v131
	v_and_b32_e32 v91, 0xffff0000, v131
	v_mul_f32_e32 v88, v55, v88
	v_mul_f32_e32 v89, v55, v89
	v_mul_f32_e32 v90, v55, v90
	v_mul_f32_e32 v91, v55, v91
	v_sub_f32_e32 v6, v6, v88
	v_sub_f32_e32 v7, v7, v89
	v_sub_f32_e32 v8, v8, v90
	v_sub_f32_e32 v9, v9, v91
	v_fma_f32 v214, v197, v6, -v204
	v_fma_f32 v215, v197, v7, -v205
	v_fma_f32 v216, v197, v8, -v206
	v_fma_f32 v217, v197, v9, -v207
	v_mul_f32_e32 v214, v2, v214
	v_mul_f32_e32 v215, v3, v215
	v_mul_f32_e32 v216, v4, v216
	v_mul_f32_e32 v217, v5, v217
	v_cvt_pk_bf16_f32 v218, v214, v215
	v_cvt_pk_bf16_f32 v219, v216, v217
	global_store_dwordx2 v[24:25], v[218:219], off offset:2048 sc1
	s_mov_b64 s[0:1], 0x1000
	v_lshl_add_u64 v[24:25], v[24:25], 0, s[0:1]
	s_waitcnt vmcnt(31)
; __device__ __forceinline__ unsigned pk2(float lo, float hi) { return pg8::cvt_pk_bf16(lo, hi); }
; __device__ __forceinline__ f32x4 ld4bf(const bf16* p) { const v2u w = *(const v2u*)p; return (f32x4){bf_lo(w.x), bf_hi(w.x), bf_lo(w.y), bf_hi(w.y)}; }
; __device__ __forceinline__ void pool_prep(const bf16* X, const float* ss, const float* gain, bf16* PB, LAS unsigned char* lds, int vcu, int G, int tid) {
;     ...
;         for (int i = 0; i < 32; ++i) { const int row = ra + i, t = row - bstart;
;             const f32x4 xn = ld4bf(xp + (size_t)row * DM) * rsl[row - r0 + 16];
;             f32x4 old = {0.f, 0.f, 0.f, 0.f};
;             if (t >= w) old = ld4bf(xp + (size_t)(row - w) * DM) * rsl[row - w - r0 + 16];
;             S = S + xn - old;
;             const int cnt = (t + 1 < w) ? t + 1 : w;
;             const f32x4 p = (S * (1.0f / (float)cnt) - xn) * gn;
;             v2u o; o.x = pk2(p[0], p[1]); o.y = pk2(p[2], p[3]); *(v2u*)(PB + (size_t)row * DM + 4 * q) = o; }
	v_lshlrev_b32_e32 v200, 16, v164
	v_and_b32_e32 v201, 0xffff0000, v164
	v_lshlrev_b32_e32 v202, 16, v165
	v_and_b32_e32 v203, 0xffff0000, v165
	v_mul_f32_e32 v204, v72, v200
	v_mul_f32_e32 v205, v72, v201
	v_mul_f32_e32 v206, v72, v202
	v_mul_f32_e32 v207, v72, v203
	v_fma_f32 v6, v72, v200, v6
	v_fma_f32 v7, v72, v201, v7
	v_fma_f32 v8, v72, v202, v8
	v_fma_f32 v9, v72, v203, v9
	v_lshlrev_b32_e32 v88, 16, v132
	v_and_b32_e32 v89, 0xffff0000, v132
	v_lshlrev_b32_e32 v90, 16, v133
	v_and_b32_e32 v91, 0xffff0000, v133
	v_mul_f32_e32 v88, v56, v88
	v_mul_f32_e32 v89, v56, v89
	v_mul_f32_e32 v90, v56, v90
	v_mul_f32_e32 v91, v56, v91
	v_sub_f32_e32 v6, v6, v88
	v_sub_f32_e32 v7, v7, v89
	v_sub_f32_e32 v8, v8, v90
	v_sub_f32_e32 v9, v9, v91
	v_fma_f32 v214, v197, v6, -v204
	v_fma_f32 v215, v197, v7, -v205
	v_fma_f32 v216, v197, v8, -v206
	v_fma_f32 v217, v197, v9, -v207
	v_mul_f32_e32 v214, v2, v214
	v_mul_f32_e32 v215, v3, v215
	v_mul_f32_e32 v216, v4, v216
	v_mul_f32_e32 v217, v5, v217
	v_cvt_pk_bf16_f32 v218, v214, v215
	v_cvt_pk_bf16_f32 v219, v216, v217
	global_store_dwordx2 v[24:25], v[218:219], off sc1
	s_waitcnt vmcnt(31)
	v_lshlrev_b32_e32 v200, 16, v166
	v_and_b32_e32 v201, 0xffff0000, v166
	v_lshlrev_b32_e32 v202, 16, v167
	v_and_b32_e32 v203, 0xffff0000, v167
	v_mul_f32_e32 v204, v73, v200
	v_mul_f32_e32 v205, v73, v201
	v_mul_f32_e32 v206, v73, v202
	v_mul_f32_e32 v207, v73, v203
	v_fma_f32 v6, v73, v200, v6
	v_fma_f32 v7, v73, v201, v7
	v_fma_f32 v8, v73, v202, v8
	v_fma_f32 v9, v73, v203, v9
	v_lshlrev_b32_e32 v88, 16, v134
	v_and_b32_e32 v89, 0xffff0000, v134
	v_lshlrev_b32_e32 v90, 16, v135
	v_and_b32_e32 v91, 0xffff0000, v135
	v_mul_f32_e32 v88, v57, v88
	v_mul_f32_e32 v89, v57, v89
	v_mul_f32_e32 v90, v57, v90
	v_mul_f32_e32 v91, v57, v91
	v_sub_f32_e32 v6, v6, v88
	v_sub_f32_e32 v7, v7, v89
	v_sub_f32_e32 v8, v8, v90
	v_sub_f32_e32 v9, v9, v91
	v_fma_f32 v214, v197, v6, -v204
	v_fma_f32 v215, v197, v7, -v205
	v_fma_f32 v216, v197, v8, -v206
	v_fma_f32 v217, v197, v9, -v207
	v_mul_f32_e32 v214, v2, v214
	v_mul_f32_e32 v215, v3, v215
	v_mul_f32_e32 v216, v4, v216
	v_mul_f32_e32 v217, v5, v217
	v_cvt_pk_bf16_f32 v218, v214, v215
	v_cvt_pk_bf16_f32 v219, v216, v217
	global_store_dwordx2 v[24:25], v[218:219], off offset:2048 sc1
	s_mov_b64 s[0:1], 0x1000
	v_lshl_add_u64 v[24:25], v[24:25], 0, s[0:1]
	s_waitcnt vmcnt(31)
	v_lshlrev_b32_e32 v200, 16, v168
	v_and_b32_e32 v201, 0xffff0000, v168
	v_lshlrev_b32_e32 v202, 16, v169
	v_and_b32_e32 v203, 0xffff0000, v169
	v_mul_f32_e32 v204, v74, v200
	v_mul_f32_e32 v205, v74, v201
	v_mul_f32_e32 v206, v74, v202
	v_mul_f32_e32 v207, v74, v203
	v_fma_f32 v6, v74, v200, v6
	v_fma_f32 v7, v74, v201, v7
	v_fma_f32 v8, v74, v202, v8
	v_fma_f32 v9, v74, v203, v9
	v_lshlrev_b32_e32 v88, 16, v136
	v_and_b32_e32 v89, 0xffff0000, v136
	v_lshlrev_b32_e32 v90, 16, v137
	v_and_b32_e32 v91, 0xffff0000, v137
	v_mul_f32_e32 v88, v58, v88
	v_mul_f32_e32 v89, v58, v89
	v_mul_f32_e32 v90, v58, v90
	v_mul_f32_e32 v91, v58, v91
	v_sub_f32_e32 v6, v6, v88
	v_sub_f32_e32 v7, v7, v89
	v_sub_f32_e32 v8, v8, v90
	v_sub_f32_e32 v9, v9, v91
	v_fma_f32 v214, v197, v6, -v204
	v_fma_f32 v215, v197, v7, -v205
	v_fma_f32 v216, v197, v8, -v206
	v_fma_f32 v217, v197, v9, -v207
	v_mul_f32_e32 v214, v2, v214
	v_mul_f32_e32 v215, v3, v215
	v_mul_f32_e32 v216, v4, v216
	v_mul_f32_e32 v217, v5, v217
	v_cvt_pk_bf16_f32 v218, v214, v215
	v_cvt_pk_bf16_f32 v219, v216, v217
	global_store_dwordx2 v[24:25], v[218:219], off sc1
	s_waitcnt vmcnt(31)
	v_lshlrev_b32_e32 v200, 16, v170
	v_and_b32_e32 v201, 0xffff0000, v170
	v_lshlrev_b32_e32 v202, 16, v171
	v_and_b32_e32 v203, 0xffff0000, v171
	v_mul_f32_e32 v204, v75, v200
	v_mul_f32_e32 v205, v75, v201
	v_mul_f32_e32 v206, v75, v202
	v_mul_f32_e32 v207, v75, v203
	v_fma_f32 v6, v75, v200, v6
	v_fma_f32 v7, v75, v201, v7
	v_fma_f32 v8, v75, v202, v8
	v_fma_f32 v9, v75, v203, v9
	v_lshlrev_b32_e32 v88, 16, v138
	v_and_b32_e32 v89, 0xffff0000, v138
	v_lshlrev_b32_e32 v90, 16, v139
	v_and_b32_e32 v91, 0xffff0000, v139
	v_mul_f32_e32 v88, v59, v88
	v_mul_f32_e32 v89, v59, v89
	v_mul_f32_e32 v90, v59, v90
	v_mul_f32_e32 v91, v59, v91
	v_sub_f32_e32 v6, v6, v88
	v_sub_f32_e32 v7, v7, v89
	v_sub_f32_e32 v8, v8, v90
	v_sub_f32_e32 v9, v9, v91
	v_fma_f32 v214, v197, v6, -v204
	v_fma_f32 v215, v197, v7, -v205
	v_fma_f32 v216, v197, v8, -v206
	v_fma_f32 v217, v197, v9, -v207
	v_mul_f32_e32 v214, v2, v214
	v_mul_f32_e32 v215, v3, v215
	v_mul_f32_e32 v216, v4, v216
	v_mul_f32_e32 v217, v5, v217
	v_cvt_pk_bf16_f32 v218, v214, v215
	v_cvt_pk_bf16_f32 v219, v216, v217
	global_store_dwordx2 v[24:25], v[218:219], off offset:2048 sc1
	s_mov_b64 s[0:1], 0x1000
	v_lshl_add_u64 v[24:25], v[24:25], 0, s[0:1]
	s_waitcnt vmcnt(31)
	v_lshlrev_b32_e32 v200, 16, v172
	v_and_b32_e32 v201, 0xffff0000, v172
	v_lshlrev_b32_e32 v202, 16, v173
	v_and_b32_e32 v203, 0xffff0000, v173
	v_mul_f32_e32 v204, v76, v200
	v_mul_f32_e32 v205, v76, v201
	v_mul_f32_e32 v206, v76, v202
	v_mul_f32_e32 v207, v76, v203
	v_fma_f32 v6, v76, v200, v6
	v_fma_f32 v7, v76, v201, v7
	v_fma_f32 v8, v76, v202, v8
	v_fma_f32 v9, v76, v203, v9
	v_lshlrev_b32_e32 v88, 16, v140
	v_and_b32_e32 v89, 0xffff0000, v140
	v_lshlrev_b32_e32 v90, 16, v141
	v_and_b32_e32 v91, 0xffff0000, v141
	v_mul_f32_e32 v88, v60, v88
	v_mul_f32_e32 v89, v60, v89
	v_mul_f32_e32 v90, v60, v90
	v_mul_f32_e32 v91, v60, v91
	v_sub_f32_e32 v6, v6, v88
	v_sub_f32_e32 v7, v7, v89
	v_sub_f32_e32 v8, v8, v90
	v_sub_f32_e32 v9, v9, v91
	v_fma_f32 v214, v197, v6, -v204
	v_fma_f32 v215, v197, v7, -v205
	v_fma_f32 v216, v197, v8, -v206
	v_fma_f32 v217, v197, v9, -v207
	v_mul_f32_e32 v214, v2, v214
	v_mul_f32_e32 v215, v3, v215
	v_mul_f32_e32 v216, v4, v216
	v_mul_f32_e32 v217, v5, v217
	v_cvt_pk_bf16_f32 v218, v214, v215
	v_cvt_pk_bf16_f32 v219, v216, v217
	global_store_dwordx2 v[24:25], v[218:219], off sc1
	s_waitcnt vmcnt(31)
; __device__ __forceinline__ unsigned pk2(float lo, float hi) { return pg8::cvt_pk_bf16(lo, hi); }
; __device__ __forceinline__ f32x4 ld4bf(const bf16* p) { const v2u w = *(const v2u*)p; return (f32x4){bf_lo(w.x), bf_hi(w.x), bf_lo(w.y), bf_hi(w.y)}; }
; __device__ __forceinline__ void pool_prep(const bf16* X, const float* ss, const float* gain, bf16* PB, LAS unsigned char* lds, int vcu, int G, int tid) {
;     ...
;         for (int i = 0; i < 32; ++i) { const int row = ra + i, t = row - bstart;
;             const f32x4 xn = ld4bf(xp + (size_t)row * DM) * rsl[row - r0 + 16];
;             f32x4 old = {0.f, 0.f, 0.f, 0.f};
;             if (t >= w) old = ld4bf(xp + (size_t)(row - w) * DM) * rsl[row - w - r0 + 16];
;             S = S + xn - old;
;             const int cnt = (t + 1 < w) ? t + 1 : w;
;             const f32x4 p = (S * (1.0f / (float)cnt) - xn) * gn;
;             v2u o; o.x = pk2(p[0], p[1]); o.y = pk2(p[2], p[3]); *(v2u*)(PB + (size_t)row * DM + 4 * q) = o; }
	v_lshlrev_b32_e32 v200, 16, v174
	v_and_b32_e32 v201, 0xffff0000, v174
	v_lshlrev_b32_e32 v202, 16, v175
	v_and_b32_e32 v203, 0xffff0000, v175
	v_mul_f32_e32 v204, v77, v200
	v_mul_f32_e32 v205, v77, v201
	v_mul_f32_e32 v206, v77, v202
	v_mul_f32_e32 v207, v77, v203
	v_fma_f32 v6, v77, v200, v6
	v_fma_f32 v7, v77, v201, v7
	v_fma_f32 v8, v77, v202, v8
	v_fma_f32 v9, v77, v203, v9
	v_lshlrev_b32_e32 v88, 16, v142
	v_and_b32_e32 v89, 0xffff0000, v142
	v_lshlrev_b32_e32 v90, 16, v143
	v_and_b32_e32 v91, 0xffff0000, v143
	v_mul_f32_e32 v88, v61, v88
	v_mul_f32_e32 v89, v61, v89
	v_mul_f32_e32 v90, v61, v90
	v_mul_f32_e32 v91, v61, v91
	v_sub_f32_e32 v6, v6, v88
	v_sub_f32_e32 v7, v7, v89
	v_sub_f32_e32 v8, v8, v90
	v_sub_f32_e32 v9, v9, v91
	v_fma_f32 v214, v197, v6, -v204
	v_fma_f32 v215, v197, v7, -v205
	v_fma_f32 v216, v197, v8, -v206
	v_fma_f32 v217, v197, v9, -v207
	v_mul_f32_e32 v214, v2, v214
	v_mul_f32_e32 v215, v3, v215
	v_mul_f32_e32 v216, v4, v216
	v_mul_f32_e32 v217, v5, v217
	v_cvt_pk_bf16_f32 v218, v214, v215
	v_cvt_pk_bf16_f32 v219, v216, v217
	global_store_dwordx2 v[24:25], v[218:219], off offset:2048 sc1
	s_mov_b64 s[0:1], 0x1000
	v_lshl_add_u64 v[24:25], v[24:25], 0, s[0:1]
	s_waitcnt vmcnt(31)
	v_lshlrev_b32_e32 v200, 16, v176
	v_and_b32_e32 v201, 0xffff0000, v176
	v_lshlrev_b32_e32 v202, 16, v177
	v_and_b32_e32 v203, 0xffff0000, v177
	v_mul_f32_e32 v204, v78, v200
	v_mul_f32_e32 v205, v78, v201
	v_mul_f32_e32 v206, v78, v202
	v_mul_f32_e32 v207, v78, v203
	v_fma_f32 v6, v78, v200, v6
	v_fma_f32 v7, v78, v201, v7
	v_fma_f32 v8, v78, v202, v8
	v_fma_f32 v9, v78, v203, v9
	v_lshlrev_b32_e32 v88, 16, v144
	v_and_b32_e32 v89, 0xffff0000, v144
	v_lshlrev_b32_e32 v90, 16, v145
	v_and_b32_e32 v91, 0xffff0000, v145
	v_mul_f32_e32 v88, v62, v88
	v_mul_f32_e32 v89, v62, v89
	v_mul_f32_e32 v90, v62, v90
	v_mul_f32_e32 v91, v62, v91
	v_sub_f32_e32 v6, v6, v88
	v_sub_f32_e32 v7, v7, v89
	v_sub_f32_e32 v8, v8, v90
	v_sub_f32_e32 v9, v9, v91
	v_fma_f32 v214, v197, v6, -v204
	v_fma_f32 v215, v197, v7, -v205
	v_fma_f32 v216, v197, v8, -v206
	v_fma_f32 v217, v197, v9, -v207
	v_mul_f32_e32 v214, v2, v214
	v_mul_f32_e32 v215, v3, v215
	v_mul_f32_e32 v216, v4, v216
	v_mul_f32_e32 v217, v5, v217
	v_cvt_pk_bf16_f32 v218, v214, v215
	v_cvt_pk_bf16_f32 v219, v216, v217
	global_store_dwordx2 v[24:25], v[218:219], off sc1
	s_waitcnt vmcnt(31)
	v_lshlrev_b32_e32 v200, 16, v178
	v_and_b32_e32 v201, 0xffff0000, v178
	v_lshlrev_b32_e32 v202, 16, v179
	v_and_b32_e32 v203, 0xffff0000, v179
	v_mul_f32_e32 v204, v79, v200
	v_mul_f32_e32 v205, v79, v201
	v_mul_f32_e32 v206, v79, v202
	v_mul_f32_e32 v207, v79, v203
	v_fma_f32 v6, v79, v200, v6
	v_fma_f32 v7, v79, v201, v7
	v_fma_f32 v8, v79, v202, v8
	v_fma_f32 v9, v79, v203, v9
	v_lshlrev_b32_e32 v88, 16, v146
	v_and_b32_e32 v89, 0xffff0000, v146
	v_lshlrev_b32_e32 v90, 16, v147
	v_and_b32_e32 v91, 0xffff0000, v147
	v_mul_f32_e32 v88, v63, v88
	v_mul_f32_e32 v89, v63, v89
	v_mul_f32_e32 v90, v63, v90
	v_mul_f32_e32 v91, v63, v91
	v_sub_f32_e32 v6, v6, v88
	v_sub_f32_e32 v7, v7, v89
	v_sub_f32_e32 v8, v8, v90
	v_sub_f32_e32 v9, v9, v91
	v_fma_f32 v214, v197, v6, -v204
	v_fma_f32 v215, v197, v7, -v205
	v_fma_f32 v216, v197, v8, -v206
	v_fma_f32 v217, v197, v9, -v207
	v_mul_f32_e32 v214, v2, v214
	v_mul_f32_e32 v215, v3, v215
	v_mul_f32_e32 v216, v4, v216
	v_mul_f32_e32 v217, v5, v217
	v_cvt_pk_bf16_f32 v218, v214, v215
	v_cvt_pk_bf16_f32 v219, v216, v217
	global_store_dwordx2 v[24:25], v[218:219], off offset:2048 sc1
	s_mov_b64 s[0:1], 0x1000
	v_lshl_add_u64 v[24:25], v[24:25], 0, s[0:1]
	s_waitcnt vmcnt(31)
	v_lshlrev_b32_e32 v200, 16, v180
	v_and_b32_e32 v201, 0xffff0000, v180
	v_lshlrev_b32_e32 v202, 16, v181
	v_and_b32_e32 v203, 0xffff0000, v181
	v_mul_f32_e32 v204, v80, v200
	v_mul_f32_e32 v205, v80, v201
	v_mul_f32_e32 v206, v80, v202
	v_mul_f32_e32 v207, v80, v203
	v_fma_f32 v6, v80, v200, v6
	v_fma_f32 v7, v80, v201, v7
	v_fma_f32 v8, v80, v202, v8
	v_fma_f32 v9, v80, v203, v9
	v_lshlrev_b32_e32 v88, 16, v148
	v_and_b32_e32 v89, 0xffff0000, v148
	v_lshlrev_b32_e32 v90, 16, v149
	v_and_b32_e32 v91, 0xffff0000, v149
	v_mul_f32_e32 v88, v64, v88
	v_mul_f32_e32 v89, v64, v89
	v_mul_f32_e32 v90, v64, v90
	v_mul_f32_e32 v91, v64, v91
	v_sub_f32_e32 v6, v6, v88
	v_sub_f32_e32 v7, v7, v89
	v_sub_f32_e32 v8, v8, v90
	v_sub_f32_e32 v9, v9, v91
	v_fma_f32 v214, v197, v6, -v204
	v_fma_f32 v215, v197, v7, -v205
	v_fma_f32 v216, v197, v8, -v206
	v_fma_f32 v217, v197, v9, -v207
	v_mul_f32_e32 v214, v2, v214
	v_mul_f32_e32 v215, v3, v215
	v_mul_f32_e32 v216, v4, v216
	v_mul_f32_e32 v217, v5, v217
	v_cvt_pk_bf16_f32 v218, v214, v215
	v_cvt_pk_bf16_f32 v219, v216, v217
	global_store_dwordx2 v[24:25], v[218:219], off sc1
	s_waitcnt vmcnt(31)
	v_lshlrev_b32_e32 v200, 16, v182
	v_and_b32_e32 v201, 0xffff0000, v182
	v_lshlrev_b32_e32 v202, 16, v183
	v_and_b32_e32 v203, 0xffff0000, v183
	v_mul_f32_e32 v204, v81, v200
	v_mul_f32_e32 v205, v81, v201
	v_mul_f32_e32 v206, v81, v202
	v_mul_f32_e32 v207, v81, v203
	v_fma_f32 v6, v81, v200, v6
	v_fma_f32 v7, v81, v201, v7
	v_fma_f32 v8, v81, v202, v8
	v_fma_f32 v9, v81, v203, v9
	v_lshlrev_b32_e32 v88, 16, v150
	v_and_b32_e32 v89, 0xffff0000, v150
	v_lshlrev_b32_e32 v90, 16, v151
	v_and_b32_e32 v91, 0xffff0000, v151
	v_mul_f32_e32 v88, v65, v88
	v_mul_f32_e32 v89, v65, v89
	v_mul_f32_e32 v90, v65, v90
	v_mul_f32_e32 v91, v65, v91
	v_sub_f32_e32 v6, v6, v88
	v_sub_f32_e32 v7, v7, v89
	v_sub_f32_e32 v8, v8, v90
	v_sub_f32_e32 v9, v9, v91
	v_fma_f32 v214, v197, v6, -v204
	v_fma_f32 v215, v197, v7, -v205
	v_fma_f32 v216, v197, v8, -v206
	v_fma_f32 v217, v197, v9, -v207
	v_mul_f32_e32 v214, v2, v214
	v_mul_f32_e32 v215, v3, v215
	v_mul_f32_e32 v216, v4, v216
	v_mul_f32_e32 v217, v5, v217
	v_cvt_pk_bf16_f32 v218, v214, v215
	v_cvt_pk_bf16_f32 v219, v216, v217
	global_store_dwordx2 v[24:25], v[218:219], off offset:2048 sc1
	s_mov_b64 s[0:1], 0x1000
	v_lshl_add_u64 v[24:25], v[24:25], 0, s[0:1]
	s_waitcnt vmcnt(31)
; __device__ __forceinline__ unsigned pk2(float lo, float hi) { return pg8::cvt_pk_bf16(lo, hi); }
; __device__ __forceinline__ f32x4 ld4bf(const bf16* p) { const v2u w = *(const v2u*)p; return (f32x4){bf_lo(w.x), bf_hi(w.x), bf_lo(w.y), bf_hi(w.y)}; }
; __device__ __forceinline__ void pool_prep(const bf16* X, const float* ss, const float* gain, bf16* PB, LAS unsigned char* lds, int vcu, int G, int tid) {
;     ...
;         for (int i = 0; i < 32; ++i) { const int row = ra + i, t = row - bstart;
;             const f32x4 xn = ld4bf(xp + (size_t)row * DM) * rsl[row - r0 + 16];
;             f32x4 old = {0.f, 0.f, 0.f, 0.f};
;             if (t >= w) old = ld4bf(xp + (size_t)(row - w) * DM) * rsl[row - w - r0 + 16];
;             S = S + xn - old;
;             const int cnt = (t + 1 < w) ? t + 1 : w;
;             const f32x4 p = (S * (1.0f / (float)cnt) - xn) * gn;
;             v2u o; o.x = pk2(p[0], p[1]); o.y = pk2(p[2], p[3]); *(v2u*)(PB + (size_t)row * DM + 4 * q) = o; }
	v_lshlrev_b32_e32 v200, 16, v184
	v_and_b32_e32 v201, 0xffff0000, v184
	v_lshlrev_b32_e32 v202, 16, v185
	v_and_b32_e32 v203, 0xffff0000, v185
	v_mul_f32_e32 v204, v82, v200
	v_mul_f32_e32 v205, v82, v201
	v_mul_f32_e32 v206, v82, v202
	v_mul_f32_e32 v207, v82, v203
	v_fma_f32 v6, v82, v200, v6
	v_fma_f32 v7, v82, v201, v7
	v_fma_f32 v8, v82, v202, v8
	v_fma_f32 v9, v82, v203, v9
	v_lshlrev_b32_e32 v88, 16, v152
	v_and_b32_e32 v89, 0xffff0000, v152
	v_lshlrev_b32_e32 v90, 16, v153
	v_and_b32_e32 v91, 0xffff0000, v153
	v_mul_f32_e32 v88, v66, v88
	v_mul_f32_e32 v89, v66, v89
	v_mul_f32_e32 v90, v66, v90
	v_mul_f32_e32 v91, v66, v91
	v_sub_f32_e32 v6, v6, v88
	v_sub_f32_e32 v7, v7, v89
	v_sub_f32_e32 v8, v8, v90
	v_sub_f32_e32 v9, v9, v91
	v_fma_f32 v214, v197, v6, -v204
	v_fma_f32 v215, v197, v7, -v205
	v_fma_f32 v216, v197, v8, -v206
	v_fma_f32 v217, v197, v9, -v207
	v_mul_f32_e32 v214, v2, v214
	v_mul_f32_e32 v215, v3, v215
	v_mul_f32_e32 v216, v4, v216
	v_mul_f32_e32 v217, v5, v217
	v_cvt_pk_bf16_f32 v218, v214, v215
	v_cvt_pk_bf16_f32 v219, v216, v217
	global_store_dwordx2 v[24:25], v[218:219], off sc1
	s_waitcnt vmcnt(31)
	v_lshlrev_b32_e32 v200, 16, v186
	v_and_b32_e32 v201, 0xffff0000, v186
	v_lshlrev_b32_e32 v202, 16, v187
	v_and_b32_e32 v203, 0xffff0000, v187
	v_mul_f32_e32 v204, v83, v200
	v_mul_f32_e32 v205, v83, v201
	v_mul_f32_e32 v206, v83, v202
	v_mul_f32_e32 v207, v83, v203
	v_fma_f32 v6, v83, v200, v6
	v_fma_f32 v7, v83, v201, v7
	v_fma_f32 v8, v83, v202, v8
	v_fma_f32 v9, v83, v203, v9
	v_lshlrev_b32_e32 v88, 16, v154
	v_and_b32_e32 v89, 0xffff0000, v154
	v_lshlrev_b32_e32 v90, 16, v155
	v_and_b32_e32 v91, 0xffff0000, v155
	v_mul_f32_e32 v88, v67, v88
	v_mul_f32_e32 v89, v67, v89
	v_mul_f32_e32 v90, v67, v90
	v_mul_f32_e32 v91, v67, v91
	v_sub_f32_e32 v6, v6, v88
	v_sub_f32_e32 v7, v7, v89
	v_sub_f32_e32 v8, v8, v90
	v_sub_f32_e32 v9, v9, v91
	v_fma_f32 v214, v197, v6, -v204
	v_fma_f32 v215, v197, v7, -v205
	v_fma_f32 v216, v197, v8, -v206
	v_fma_f32 v217, v197, v9, -v207
	v_mul_f32_e32 v214, v2, v214
	v_mul_f32_e32 v215, v3, v215
	v_mul_f32_e32 v216, v4, v216
	v_mul_f32_e32 v217, v5, v217
	v_cvt_pk_bf16_f32 v218, v214, v215
	v_cvt_pk_bf16_f32 v219, v216, v217
	global_store_dwordx2 v[24:25], v[218:219], off offset:2048 sc1
	s_mov_b64 s[0:1], 0x1000
	v_lshl_add_u64 v[24:25], v[24:25], 0, s[0:1]
	s_waitcnt vmcnt(31)
	v_lshlrev_b32_e32 v200, 16, v188
	v_and_b32_e32 v201, 0xffff0000, v188
	v_lshlrev_b32_e32 v202, 16, v189
	v_and_b32_e32 v203, 0xffff0000, v189
	v_mul_f32_e32 v204, v84, v200
	v_mul_f32_e32 v205, v84, v201
	v_mul_f32_e32 v206, v84, v202
	v_mul_f32_e32 v207, v84, v203
	v_fma_f32 v6, v84, v200, v6
	v_fma_f32 v7, v84, v201, v7
	v_fma_f32 v8, v84, v202, v8
	v_fma_f32 v9, v84, v203, v9
	v_lshlrev_b32_e32 v88, 16, v156
	v_and_b32_e32 v89, 0xffff0000, v156
	v_lshlrev_b32_e32 v90, 16, v157
	v_and_b32_e32 v91, 0xffff0000, v157
	v_mul_f32_e32 v88, v68, v88
	v_mul_f32_e32 v89, v68, v89
	v_mul_f32_e32 v90, v68, v90
	v_mul_f32_e32 v91, v68, v91
	v_sub_f32_e32 v6, v6, v88
	v_sub_f32_e32 v7, v7, v89
	v_sub_f32_e32 v8, v8, v90
	v_sub_f32_e32 v9, v9, v91
	v_fma_f32 v214, v197, v6, -v204
	v_fma_f32 v215, v197, v7, -v205
	v_fma_f32 v216, v197, v8, -v206
	v_fma_f32 v217, v197, v9, -v207
	v_mul_f32_e32 v214, v2, v214
	v_mul_f32_e32 v215, v3, v215
	v_mul_f32_e32 v216, v4, v216
	v_mul_f32_e32 v217, v5, v217
	v_cvt_pk_bf16_f32 v218, v214, v215
	v_cvt_pk_bf16_f32 v219, v216, v217
	global_store_dwordx2 v[24:25], v[218:219], off sc1
	s_waitcnt vmcnt(31)
	v_lshlrev_b32_e32 v200, 16, v190
	v_and_b32_e32 v201, 0xffff0000, v190
	v_lshlrev_b32_e32 v202, 16, v191
	v_and_b32_e32 v203, 0xffff0000, v191
	v_mul_f32_e32 v204, v85, v200
	v_mul_f32_e32 v205, v85, v201
	v_mul_f32_e32 v206, v85, v202
	v_mul_f32_e32 v207, v85, v203
	v_fma_f32 v6, v85, v200, v6
	v_fma_f32 v7, v85, v201, v7
	v_fma_f32 v8, v85, v202, v8
	v_fma_f32 v9, v85, v203, v9
	v_lshlrev_b32_e32 v88, 16, v158
	v_and_b32_e32 v89, 0xffff0000, v158
	v_lshlrev_b32_e32 v90, 16, v159
	v_and_b32_e32 v91, 0xffff0000, v159
	v_mul_f32_e32 v88, v69, v88
	v_mul_f32_e32 v89, v69, v89
	v_mul_f32_e32 v90, v69, v90
	v_mul_f32_e32 v91, v69, v91
	v_sub_f32_e32 v6, v6, v88
	v_sub_f32_e32 v7, v7, v89
	v_sub_f32_e32 v8, v8, v90
	v_sub_f32_e32 v9, v9, v91
	v_fma_f32 v214, v197, v6, -v204
	v_fma_f32 v215, v197, v7, -v205
	v_fma_f32 v216, v197, v8, -v206
	v_fma_f32 v217, v197, v9, -v207
	v_mul_f32_e32 v214, v2, v214
	v_mul_f32_e32 v215, v3, v215
	v_mul_f32_e32 v216, v4, v216
	v_mul_f32_e32 v217, v5, v217
	v_cvt_pk_bf16_f32 v218, v214, v215
	v_cvt_pk_bf16_f32 v219, v216, v217
	global_store_dwordx2 v[24:25], v[218:219], off offset:2048 sc1
	s_mov_b64 s[0:1], 0x1000
	v_lshl_add_u64 v[24:25], v[24:25], 0, s[0:1]
	s_waitcnt vmcnt(31)
	v_lshlrev_b32_e32 v200, 16, v192
	v_and_b32_e32 v201, 0xffff0000, v192
	v_lshlrev_b32_e32 v202, 16, v193
	v_and_b32_e32 v203, 0xffff0000, v193
	v_mul_f32_e32 v204, v86, v200
	v_mul_f32_e32 v205, v86, v201
	v_mul_f32_e32 v206, v86, v202
	v_mul_f32_e32 v207, v86, v203
	v_fma_f32 v6, v86, v200, v6
	v_fma_f32 v7, v86, v201, v7
	v_fma_f32 v8, v86, v202, v8
	v_fma_f32 v9, v86, v203, v9
	v_lshlrev_b32_e32 v88, 16, v160
	v_and_b32_e32 v89, 0xffff0000, v160
	v_lshlrev_b32_e32 v90, 16, v161
	v_and_b32_e32 v91, 0xffff0000, v161
	v_mul_f32_e32 v88, v70, v88
	v_mul_f32_e32 v89, v70, v89
	v_mul_f32_e32 v90, v70, v90
	v_mul_f32_e32 v91, v70, v91
	v_sub_f32_e32 v6, v6, v88
	v_sub_f32_e32 v7, v7, v89
	v_sub_f32_e32 v8, v8, v90
	v_sub_f32_e32 v9, v9, v91
	v_fma_f32 v214, v197, v6, -v204
	v_fma_f32 v215, v197, v7, -v205
	v_fma_f32 v216, v197, v8, -v206
	v_fma_f32 v217, v197, v9, -v207
	v_mul_f32_e32 v214, v2, v214
	v_mul_f32_e32 v215, v3, v215
	v_mul_f32_e32 v216, v4, v216
	v_mul_f32_e32 v217, v5, v217
	v_cvt_pk_bf16_f32 v218, v214, v215
	v_cvt_pk_bf16_f32 v219, v216, v217
	global_store_dwordx2 v[24:25], v[218:219], off sc1
	s_waitcnt vmcnt(31)
	v_lshlrev_b32_e32 v200, 16, v194
	v_and_b32_e32 v201, 0xffff0000, v194
	v_lshlrev_b32_e32 v202, 16, v195
	v_and_b32_e32 v203, 0xffff0000, v195
	v_mul_f32_e32 v204, v87, v200
	v_mul_f32_e32 v205, v87, v201
	v_mul_f32_e32 v206, v87, v202
	v_mul_f32_e32 v207, v87, v203
	v_fma_f32 v6, v87, v200, v6
	v_fma_f32 v7, v87, v201, v7
	v_fma_f32 v8, v87, v202, v8
	v_fma_f32 v9, v87, v203, v9
	v_lshlrev_b32_e32 v88, 16, v162
	v_and_b32_e32 v89, 0xffff0000, v162
	v_lshlrev_b32_e32 v90, 16, v163
	v_and_b32_e32 v91, 0xffff0000, v163
	v_mul_f32_e32 v88, v71, v88
	v_mul_f32_e32 v89, v71, v89
	v_mul_f32_e32 v90, v71, v90
	v_mul_f32_e32 v91, v71, v91
	v_sub_f32_e32 v6, v6, v88
	v_sub_f32_e32 v7, v7, v89
	v_sub_f32_e32 v8, v8, v90
	v_sub_f32_e32 v9, v9, v91
	v_fma_f32 v214, v197, v6, -v204
	v_fma_f32 v215, v197, v7, -v205
	v_fma_f32 v216, v197, v8, -v206
	v_fma_f32 v217, v197, v9, -v207
	v_mul_f32_e32 v214, v2, v214
	v_mul_f32_e32 v215, v3, v215
	v_mul_f32_e32 v216, v4, v216
	v_mul_f32_e32 v217, v5, v217
	v_cvt_pk_bf16_f32 v218, v214, v215
	v_cvt_pk_bf16_f32 v219, v216, v217
	global_store_dwordx2 v[24:25], v[218:219], off offset:2048 sc1
	s_branch .LBB0_308
; __device__ __forceinline__ f32x4 ld4bf(const bf16* p) { const v2u w = *(const v2u*)p; return (f32x4){bf_lo(w.x), bf_hi(w.x), bf_lo(w.y), bf_hi(w.y)}; }
; __device__ __forceinline__ void pool_prep(const bf16* X, const float* ss, const float* gain, bf16* PB, LAS unsigned char* lds, int vcu, int G, int tid) {
;     ...
;         const int q = tid & 255, half = tid >> 8, w = 2 << (q >> 6);
;         const f32x4 gn = *(const f32x4*)(gain + 4 * q);
;         const int ra = r0 + 32 * half;
;         const bf16* xp = X + 4 * q;
;         f32x4 S = {0.f, 0.f, 0.f, 0.f};
; #pragma unroll
;         for (int j = 1; j <= 16; ++j) { const int row = ra - j; if (j <= w && row >= bstart) S += ld4bf(xp + (size_t)row * DM) * rsl[row - r0 + 16]; }
.Lmy_pool_w8:
	s_mov_b32 s0, 16384
	v_subrev_co_u32_e32 v198, vcc, s0, v22
	s_nop 1
	v_subbrev_co_u32_e32 v199, vcc, 0, v23, vcc
	s_mov_b64 s[0:1], 0x1000
	global_load_dwordx2 v[100:101], v[198:199], off
	global_load_dwordx2 v[102:103], v[198:199], off offset:2048
	v_lshl_add_u64 v[198:199], v[198:199], 0, s[0:1]
	global_load_dwordx2 v[104:105], v[198:199], off
	global_load_dwordx2 v[106:107], v[198:199], off offset:2048
	v_lshl_add_u64 v[198:199], v[198:199], 0, s[0:1]
	global_load_dwordx2 v[108:109], v[198:199], off
	global_load_dwordx2 v[110:111], v[198:199], off offset:2048
	v_lshl_add_u64 v[198:199], v[198:199], 0, s[0:1]
	global_load_dwordx2 v[112:113], v[198:199], off
	global_load_dwordx2 v[114:115], v[198:199], off offset:2048
	v_lshl_add_u64 v[198:199], v[198:199], 0, s[0:1]
	global_load_dwordx2 v[116:117], v[198:199], off
	global_load_dwordx2 v[118:119], v[198:199], off offset:2048
	v_lshl_add_u64 v[198:199], v[198:199], 0, s[0:1]
	global_load_dwordx2 v[120:121], v[198:199], off
	global_load_dwordx2 v[122:123], v[198:199], off offset:2048
	v_lshl_add_u64 v[198:199], v[198:199], 0, s[0:1]
	global_load_dwordx2 v[124:125], v[198:199], off
	global_load_dwordx2 v[126:127], v[198:199], off offset:2048
	v_lshl_add_u64 v[198:199], v[198:199], 0, s[0:1]
	global_load_dwordx2 v[128:129], v[198:199], off
	global_load_dwordx2 v[130:131], v[198:199], off offset:2048
	v_lshl_add_u64 v[198:199], v[198:199], 0, s[0:1]
	global_load_dwordx2 v[132:133], v[198:199], off
	global_load_dwordx2 v[134:135], v[198:199], off offset:2048
	v_lshl_add_u64 v[198:199], v[198:199], 0, s[0:1]
	global_load_dwordx2 v[136:137], v[198:199], off
	global_load_dwordx2 v[138:139], v[198:199], off offset:2048
	v_lshl_add_u64 v[198:199], v[198:199], 0, s[0:1]
	global_load_dwordx2 v[140:141], v[198:199], off
	global_load_dwordx2 v[142:143], v[198:199], off offset:2048
	v_lshl_add_u64 v[198:199], v[198:199], 0, s[0:1]
	global_load_dwordx2 v[144:145], v[198:199], off
	global_load_dwordx2 v[146:147], v[198:199], off offset:2048
	v_lshl_add_u64 v[198:199], v[198:199], 0, s[0:1]
	global_load_dwordx2 v[148:149], v[198:199], off
	global_load_dwordx2 v[150:151], v[198:199], off offset:2048
	v_lshl_add_u64 v[198:199], v[198:199], 0, s[0:1]
	global_load_dwordx2 v[152:153], v[198:199], off
	global_load_dwordx2 v[154:155], v[198:199], off offset:2048
	v_lshl_add_u64 v[198:199], v[198:199], 0, s[0:1]
	global_load_dwordx2 v[156:157], v[198:199], off
	global_load_dwordx2 v[158:159], v[198:199], off offset:2048
	v_lshl_add_u64 v[198:199], v[198:199], 0, s[0:1]
	global_load_dwordx2 v[160:161], v[198:199], off
	global_load_dwordx2 v[162:163], v[198:199], off offset:2048
	v_lshl_add_u64 v[198:199], v[198:199], 0, s[0:1]
	global_load_dwordx2 v[164:165], v[198:199], off
	global_load_dwordx2 v[166:167], v[198:199], off offset:2048
	v_lshl_add_u64 v[198:199], v[198:199], 0, s[0:1]
	global_load_dwordx2 v[168:169], v[198:199], off
	global_load_dwordx2 v[170:171], v[198:199], off offset:2048
	v_lshl_add_u64 v[198:199], v[198:199], 0, s[0:1]
	global_load_dwordx2 v[172:173], v[198:199], off
	global_load_dwordx2 v[174:175], v[198:199], off offset:2048
	v_lshl_add_u64 v[198:199], v[198:199], 0, s[0:1]
	global_load_dwordx2 v[176:177], v[198:199], off
	global_load_dwordx2 v[178:179], v[198:199], off offset:2048
	ds_read_b32 v40, v21 offset:32
	ds_read_b32 v41, v21 offset:36
	ds_read_b32 v42, v21 offset:40
	ds_read_b32 v43, v21 offset:44
	ds_read_b32 v44, v21 offset:48
	ds_read_b32 v45, v21 offset:52
	ds_read_b32 v46, v21 offset:56
	ds_read_b32 v47, v21 offset:60
	ds_read_b32 v48, v21 offset:64
	ds_read_b32 v49, v21 offset:68
	ds_read_b32 v50, v21 offset:72
	ds_read_b32 v51, v21 offset:76
	s_waitcnt lgkmcnt(0)
	ds_read_b32 v52, v21 offset:80
	ds_read_b32 v53, v21 offset:84
	ds_read_b32 v54, v21 offset:88
	ds_read_b32 v55, v21 offset:92
	ds_read_b32 v56, v21 offset:96
	ds_read_b32 v57, v21 offset:100
	ds_read_b32 v58, v21 offset:104
	ds_read_b32 v59, v21 offset:108
	ds_read_b32 v60, v21 offset:112
	ds_read_b32 v61, v21 offset:116
	ds_read_b32 v62, v21 offset:120
	ds_read_b32 v63, v21 offset:124
	s_waitcnt lgkmcnt(0)
	ds_read_b32 v64, v21 offset:128
	ds_read_b32 v65, v21 offset:132
	ds_read_b32 v66, v21 offset:136
	ds_read_b32 v67, v21 offset:140
	ds_read_b32 v68, v21 offset:144
	ds_read_b32 v69, v21 offset:148
	ds_read_b32 v70, v21 offset:152
	ds_read_b32 v71, v21 offset:156
	ds_read_b32 v72, v21 offset:160
	ds_read_b32 v73, v21 offset:164
	ds_read_b32 v74, v21 offset:168
	ds_read_b32 v75, v21 offset:172
	s_waitcnt lgkmcnt(0)
	ds_read_b32 v76, v21 offset:176
	ds_read_b32 v77, v21 offset:180
	ds_read_b32 v78, v21 offset:184
	ds_read_b32 v79, v21 offset:188
	v_div_scale_f32 v26, s[0:1], v196, v196, 1.0
	v_rcp_f32_e32 v27, v26
	s_nop 0
	v_fma_f32 v28, -v26, v27, 1.0
	v_fmac_f32_e32 v27, v28, v27
	v_div_scale_f32 v28, vcc, 1.0, v196, 1.0
	v_mul_f32_e32 v29, v28, v27
	v_fma_f32 v30, -v26, v29, v28
	v_fmac_f32_e32 v29, v30, v27
	v_fma_f32 v26, -v26, v29, v28
	s_nop 1
	v_div_fmas_f32 v197, v26, v27, v29
	v_div_fixup_f32 v197, v197, v196, 1.0
	v_mov_b32_e32 v6, 0
	v_mov_b32_e32 v7, 0
	v_mov_b32_e32 v8, 0
	v_mov_b32_e32 v9, 0
	s_waitcnt lgkmcnt(0)
	s_waitcnt vmcnt(32)
; __device__ __forceinline__ unsigned pk2(float lo, float hi) { return pg8::cvt_pk_bf16(lo, hi); }
; __device__ __forceinline__ f32x4 ld4bf(const bf16* p) { const v2u w = *(const v2u*)p; return (f32x4){bf_lo(w.x), bf_hi(w.x), bf_lo(w.y), bf_hi(w.y)}; }
; __device__ __forceinline__ void pool_prep(const bf16* X, const float* ss, const float* gain, bf16* PB, LAS unsigned char* lds, int vcu, int G, int tid) {
;     ...
;         for (int j = 1; j <= 16; ++j) { const int row = ra - j; if (j <= w && row >= bstart) S += ld4bf(xp + (size_t)row * DM) * rsl[row - r0 + 16]; }
;     ...
;         for (int i = 0; i < 32; ++i) { const int row = ra + i, t = row - bstart;
;             const f32x4 xn = ld4bf(xp + (size_t)row * DM) * rsl[row - r0 + 16];
;             f32x4 old = {0.f, 0.f, 0.f, 0.f};
;             if (t >= w) old = ld4bf(xp + (size_t)(row - w) * DM) * rsl[row - w - r0 + 16];
;             S = S + xn - old;
;             const int cnt = (t + 1 < w) ? t + 1 : w;
;             const f32x4 p = (S * (1.0f / (float)cnt) - xn) * gn;
;             v2u o; o.x = pk2(p[0], p[1]); o.y = pk2(p[2], p[3]); *(v2u*)(PB + (size_t)row * DM + 4 * q) = o; }
	v_cndmask_b32_e64 v100, v100, 0, s[6:7]
	v_cndmask_b32_e64 v101, v101, 0, s[6:7]
	v_cndmask_b32_e64 v102, v102, 0, s[6:7]
	v_cndmask_b32_e64 v103, v103, 0, s[6:7]
	v_cndmask_b32_e64 v104, v104, 0, s[6:7]
	v_cndmask_b32_e64 v105, v105, 0, s[6:7]
	v_cndmask_b32_e64 v106, v106, 0, s[6:7]
	v_cndmask_b32_e64 v107, v107, 0, s[6:7]
	v_cndmask_b32_e64 v108, v108, 0, s[6:7]
	v_cndmask_b32_e64 v109, v109, 0, s[6:7]
	v_cndmask_b32_e64 v110, v110, 0, s[6:7]
	v_cndmask_b32_e64 v111, v111, 0, s[6:7]
	v_cndmask_b32_e64 v112, v112, 0, s[6:7]
	v_cndmask_b32_e64 v113, v113, 0, s[6:7]
	v_cndmask_b32_e64 v114, v114, 0, s[6:7]
	v_cndmask_b32_e64 v115, v115, 0, s[6:7]
	v_lshlrev_b32_e32 v200, 16, v114
	v_and_b32_e32 v201, 0xffff0000, v114
	v_lshlrev_b32_e32 v202, 16, v115
	v_and_b32_e32 v203, 0xffff0000, v115
	v_fma_f32 v6, v47, v200, v6
	v_fma_f32 v7, v47, v201, v7
	v_fma_f32 v8, v47, v202, v8
	v_fma_f32 v9, v47, v203, v9
	v_lshlrev_b32_e32 v200, 16, v112
	v_and_b32_e32 v201, 0xffff0000, v112
	v_lshlrev_b32_e32 v202, 16, v113
	v_and_b32_e32 v203, 0xffff0000, v113
	v_fma_f32 v6, v46, v200, v6
	v_fma_f32 v7, v46, v201, v7
	v_fma_f32 v8, v46, v202, v8
	v_fma_f32 v9, v46, v203, v9
	v_lshlrev_b32_e32 v200, 16, v110
	v_and_b32_e32 v201, 0xffff0000, v110
	v_lshlrev_b32_e32 v202, 16, v111
	v_and_b32_e32 v203, 0xffff0000, v111
	v_fma_f32 v6, v45, v200, v6
	v_fma_f32 v7, v45, v201, v7
	v_fma_f32 v8, v45, v202, v8
	v_fma_f32 v9, v45, v203, v9
	v_lshlrev_b32_e32 v200, 16, v108
	v_and_b32_e32 v201, 0xffff0000, v108
	v_lshlrev_b32_e32 v202, 16, v109
	v_and_b32_e32 v203, 0xffff0000, v109
	v_fma_f32 v6, v44, v200, v6
	v_fma_f32 v7, v44, v201, v7
	v_fma_f32 v8, v44, v202, v8
	v_fma_f32 v9, v44, v203, v9
	v_lshlrev_b32_e32 v200, 16, v106
	v_and_b32_e32 v201, 0xffff0000, v106
	v_lshlrev_b32_e32 v202, 16, v107
	v_and_b32_e32 v203, 0xffff0000, v107
	v_fma_f32 v6, v43, v200, v6
	v_fma_f32 v7, v43, v201, v7
	v_fma_f32 v8, v43, v202, v8
	v_fma_f32 v9, v43, v203, v9
	v_lshlrev_b32_e32 v200, 16, v104
	v_and_b32_e32 v201, 0xffff0000, v104
	v_lshlrev_b32_e32 v202, 16, v105
	v_and_b32_e32 v203, 0xffff0000, v105
	v_fma_f32 v6, v42, v200, v6
	v_fma_f32 v7, v42, v201, v7
	v_fma_f32 v8, v42, v202, v8
	v_fma_f32 v9, v42, v203, v9
	v_lshlrev_b32_e32 v200, 16, v102
	v_and_b32_e32 v201, 0xffff0000, v102
	v_lshlrev_b32_e32 v202, 16, v103
	v_and_b32_e32 v203, 0xffff0000, v103
	v_fma_f32 v6, v41, v200, v6
	v_fma_f32 v7, v41, v201, v7
	v_fma_f32 v8, v41, v202, v8
	v_fma_f32 v9, v41, v203, v9
	v_lshlrev_b32_e32 v200, 16, v100
	v_and_b32_e32 v201, 0xffff0000, v100
	v_lshlrev_b32_e32 v202, 16, v101
	v_and_b32_e32 v203, 0xffff0000, v101
	v_fma_f32 v6, v40, v200, v6
	v_fma_f32 v7, v40, v201, v7
	v_fma_f32 v8, v40, v202, v8
	v_fma_f32 v9, v40, v203, v9
	s_waitcnt vmcnt(31)
	v_lshlrev_b32_e32 v200, 16, v116
	v_and_b32_e32 v201, 0xffff0000, v116
	v_lshlrev_b32_e32 v202, 16, v117
	v_and_b32_e32 v203, 0xffff0000, v117
	v_mul_f32_e32 v204, v48, v200
	v_mul_f32_e32 v205, v48, v201
	v_mul_f32_e32 v206, v48, v202
	v_mul_f32_e32 v207, v48, v203
	v_fma_f32 v6, v48, v200, v6
	v_fma_f32 v7, v48, v201, v7
	v_fma_f32 v8, v48, v202, v8
	v_fma_f32 v9, v48, v203, v9
	v_lshlrev_b32_e32 v88, 16, v100
	v_and_b32_e32 v89, 0xffff0000, v100
	v_lshlrev_b32_e32 v90, 16, v101
	v_and_b32_e32 v91, 0xffff0000, v101
	v_mul_f32_e32 v88, v40, v88
	v_mul_f32_e32 v89, v40, v89
	v_mul_f32_e32 v90, v40, v90
	v_mul_f32_e32 v91, v40, v91
	v_sub_f32_e32 v6, v6, v88
	v_sub_f32_e32 v7, v7, v89
	v_sub_f32_e32 v8, v8, v90
	v_sub_f32_e32 v9, v9, v91
	v_add_u32_e32 v92, 1, v20
	v_min_i32_e32 v92, v92, v32
	v_cvt_f32_i32_e32 v92, v92
	v_div_scale_f32 v26, s[0:1], v92, v92, 1.0
	v_rcp_f32_e32 v27, v26
	s_nop 0
	v_fma_f32 v28, -v26, v27, 1.0
	v_fmac_f32_e32 v27, v28, v27
	v_div_scale_f32 v28, vcc, 1.0, v92, 1.0
	v_mul_f32_e32 v29, v28, v27
	v_fma_f32 v30, -v26, v29, v28
	v_fmac_f32_e32 v29, v30, v27
	v_fma_f32 v26, -v26, v29, v28
	s_nop 1
	v_div_fmas_f32 v93, v26, v27, v29
	v_div_fixup_f32 v93, v93, v92, 1.0
	v_fma_f32 v214, v93, v6, -v204
	v_fma_f32 v215, v93, v7, -v205
	v_fma_f32 v216, v93, v8, -v206
	v_fma_f32 v217, v93, v9, -v207
	v_mul_f32_e32 v214, v2, v214
	v_mul_f32_e32 v215, v3, v215
	v_mul_f32_e32 v216, v4, v216
	v_mul_f32_e32 v217, v5, v217
	v_cvt_pk_bf16_f32 v218, v214, v215
	v_cvt_pk_bf16_f32 v219, v216, v217
	global_store_dwordx2 v[24:25], v[218:219], off sc1
	s_waitcnt vmcnt(31)
	v_lshlrev_b32_e32 v200, 16, v118
	v_and_b32_e32 v201, 0xffff0000, v118
	v_lshlrev_b32_e32 v202, 16, v119
	v_and_b32_e32 v203, 0xffff0000, v119
	v_mul_f32_e32 v204, v49, v200
	v_mul_f32_e32 v205, v49, v201
	v_mul_f32_e32 v206, v49, v202
	v_mul_f32_e32 v207, v49, v203
	v_fma_f32 v6, v49, v200, v6
	v_fma_f32 v7, v49, v201, v7
	v_fma_f32 v8, v49, v202, v8
	v_fma_f32 v9, v49, v203, v9
	v_lshlrev_b32_e32 v88, 16, v102
	v_and_b32_e32 v89, 0xffff0000, v102
	v_lshlrev_b32_e32 v90, 16, v103
	v_and_b32_e32 v91, 0xffff0000, v103
	v_mul_f32_e32 v88, v41, v88
	v_mul_f32_e32 v89, v41, v89
	v_mul_f32_e32 v90, v41, v90
	v_mul_f32_e32 v91, v41, v91
	v_sub_f32_e32 v6, v6, v88
	v_sub_f32_e32 v7, v7, v89
	v_sub_f32_e32 v8, v8, v90
	v_sub_f32_e32 v9, v9, v91
	v_add_u32_e32 v92, 2, v20
	v_min_i32_e32 v92, v92, v32
	v_cvt_f32_i32_e32 v92, v92
	v_div_scale_f32 v26, s[0:1], v92, v92, 1.0
	v_rcp_f32_e32 v27, v26
	s_nop 0
	v_fma_f32 v28, -v26, v27, 1.0
	v_fmac_f32_e32 v27, v28, v27
	v_div_scale_f32 v28, vcc, 1.0, v92, 1.0
	v_mul_f32_e32 v29, v28, v27
	v_fma_f32 v30, -v26, v29, v28
	v_fmac_f32_e32 v29, v30, v27
	v_fma_f32 v26, -v26, v29, v28
	s_nop 1
	v_div_fmas_f32 v93, v26, v27, v29
	v_div_fixup_f32 v93, v93, v92, 1.0
	v_fma_f32 v214, v93, v6, -v204
	v_fma_f32 v215, v93, v7, -v205
	v_fma_f32 v216, v93, v8, -v206
	v_fma_f32 v217, v93, v9, -v207
	v_mul_f32_e32 v214, v2, v214
	v_mul_f32_e32 v215, v3, v215
	v_mul_f32_e32 v216, v4, v216
	v_mul_f32_e32 v217, v5, v217
	v_cvt_pk_bf16_f32 v218, v214, v215
	v_cvt_pk_bf16_f32 v219, v216, v217
	global_store_dwordx2 v[24:25], v[218:219], off offset:2048 sc1
	s_mov_b64 s[0:1], 0x1000
	v_lshl_add_u64 v[24:25], v[24:25], 0, s[0:1]
	s_waitcnt vmcnt(31)
; __device__ __forceinline__ unsigned pk2(float lo, float hi) { return pg8::cvt_pk_bf16(lo, hi); }
; __device__ __forceinline__ f32x4 ld4bf(const bf16* p) { const v2u w = *(const v2u*)p; return (f32x4){bf_lo(w.x), bf_hi(w.x), bf_lo(w.y), bf_hi(w.y)}; }
; __device__ __forceinline__ void pool_prep(const bf16* X, const float* ss, const float* gain, bf16* PB, LAS unsigned char* lds, int vcu, int G, int tid) {
;     ...
;         for (int i = 0; i < 32; ++i) { const int row = ra + i, t = row - bstart;
;             const f32x4 xn = ld4bf(xp + (size_t)row * DM) * rsl[row - r0 + 16];
;             f32x4 old = {0.f, 0.f, 0.f, 0.f};
;             if (t >= w) old = ld4bf(xp + (size_t)(row - w) * DM) * rsl[row - w - r0 + 16];
;             S = S + xn - old;
;             const int cnt = (t + 1 < w) ? t + 1 : w;
;             const f32x4 p = (S * (1.0f / (float)cnt) - xn) * gn;
;             v2u o; o.x = pk2(p[0], p[1]); o.y = pk2(p[2], p[3]); *(v2u*)(PB + (size_t)row * DM + 4 * q) = o; }
	v_lshlrev_b32_e32 v200, 16, v120
	v_and_b32_e32 v201, 0xffff0000, v120
	v_lshlrev_b32_e32 v202, 16, v121
	v_and_b32_e32 v203, 0xffff0000, v121
	v_mul_f32_e32 v204, v50, v200
	v_mul_f32_e32 v205, v50, v201
	v_mul_f32_e32 v206, v50, v202
	v_mul_f32_e32 v207, v50, v203
	v_fma_f32 v6, v50, v200, v6
	v_fma_f32 v7, v50, v201, v7
	v_fma_f32 v8, v50, v202, v8
	v_fma_f32 v9, v50, v203, v9
	v_lshlrev_b32_e32 v88, 16, v104
	v_and_b32_e32 v89, 0xffff0000, v104
	v_lshlrev_b32_e32 v90, 16, v105
	v_and_b32_e32 v91, 0xffff0000, v105
	v_mul_f32_e32 v88, v42, v88
	v_mul_f32_e32 v89, v42, v89
	v_mul_f32_e32 v90, v42, v90
	v_mul_f32_e32 v91, v42, v91
	v_sub_f32_e32 v6, v6, v88
	v_sub_f32_e32 v7, v7, v89
	v_sub_f32_e32 v8, v8, v90
	v_sub_f32_e32 v9, v9, v91
	v_add_u32_e32 v92, 3, v20
	v_min_i32_e32 v92, v92, v32
	v_cvt_f32_i32_e32 v92, v92
	v_div_scale_f32 v26, s[0:1], v92, v92, 1.0
	v_rcp_f32_e32 v27, v26
	s_nop 0
	v_fma_f32 v28, -v26, v27, 1.0
	v_fmac_f32_e32 v27, v28, v27
	v_div_scale_f32 v28, vcc, 1.0, v92, 1.0
	v_mul_f32_e32 v29, v28, v27
	v_fma_f32 v30, -v26, v29, v28
	v_fmac_f32_e32 v29, v30, v27
	v_fma_f32 v26, -v26, v29, v28
	s_nop 1
	v_div_fmas_f32 v93, v26, v27, v29
	v_div_fixup_f32 v93, v93, v92, 1.0
	v_fma_f32 v214, v93, v6, -v204
	v_fma_f32 v215, v93, v7, -v205
	v_fma_f32 v216, v93, v8, -v206
	v_fma_f32 v217, v93, v9, -v207
	v_mul_f32_e32 v214, v2, v214
	v_mul_f32_e32 v215, v3, v215
	v_mul_f32_e32 v216, v4, v216
	v_mul_f32_e32 v217, v5, v217
	v_cvt_pk_bf16_f32 v218, v214, v215
	v_cvt_pk_bf16_f32 v219, v216, v217
	global_store_dwordx2 v[24:25], v[218:219], off sc1
	s_waitcnt vmcnt(31)
	v_lshlrev_b32_e32 v200, 16, v122
	v_and_b32_e32 v201, 0xffff0000, v122
	v_lshlrev_b32_e32 v202, 16, v123
	v_and_b32_e32 v203, 0xffff0000, v123
	v_mul_f32_e32 v204, v51, v200
	v_mul_f32_e32 v205, v51, v201
	v_mul_f32_e32 v206, v51, v202
	v_mul_f32_e32 v207, v51, v203
	v_fma_f32 v6, v51, v200, v6
	v_fma_f32 v7, v51, v201, v7
	v_fma_f32 v8, v51, v202, v8
	v_fma_f32 v9, v51, v203, v9
	v_lshlrev_b32_e32 v88, 16, v106
	v_and_b32_e32 v89, 0xffff0000, v106
	v_lshlrev_b32_e32 v90, 16, v107
	v_and_b32_e32 v91, 0xffff0000, v107
	v_mul_f32_e32 v88, v43, v88
	v_mul_f32_e32 v89, v43, v89
	v_mul_f32_e32 v90, v43, v90
	v_mul_f32_e32 v91, v43, v91
	v_sub_f32_e32 v6, v6, v88
	v_sub_f32_e32 v7, v7, v89
	v_sub_f32_e32 v8, v8, v90
	v_sub_f32_e32 v9, v9, v91
	v_add_u32_e32 v92, 4, v20
	v_min_i32_e32 v92, v92, v32
	v_cvt_f32_i32_e32 v92, v92
	v_div_scale_f32 v26, s[0:1], v92, v92, 1.0
	v_rcp_f32_e32 v27, v26
	s_nop 0
	v_fma_f32 v28, -v26, v27, 1.0
	v_fmac_f32_e32 v27, v28, v27
	v_div_scale_f32 v28, vcc, 1.0, v92, 1.0
	v_mul_f32_e32 v29, v28, v27
	v_fma_f32 v30, -v26, v29, v28
	v_fmac_f32_e32 v29, v30, v27
	v_fma_f32 v26, -v26, v29, v28
	s_nop 1
	v_div_fmas_f32 v93, v26, v27, v29
	v_div_fixup_f32 v93, v93, v92, 1.0
	v_fma_f32 v214, v93, v6, -v204
	v_fma_f32 v215, v93, v7, -v205
	v_fma_f32 v216, v93, v8, -v206
	v_fma_f32 v217, v93, v9, -v207
	v_mul_f32_e32 v214, v2, v214
	v_mul_f32_e32 v215, v3, v215
	v_mul_f32_e32 v216, v4, v216
	v_mul_f32_e32 v217, v5, v217
	v_cvt_pk_bf16_f32 v218, v214, v215
	v_cvt_pk_bf16_f32 v219, v216, v217
	global_store_dwordx2 v[24:25], v[218:219], off offset:2048 sc1
	s_mov_b64 s[0:1], 0x1000
	v_lshl_add_u64 v[24:25], v[24:25], 0, s[0:1]
	s_waitcnt vmcnt(31)
	v_lshlrev_b32_e32 v200, 16, v124
	v_and_b32_e32 v201, 0xffff0000, v124
	v_lshlrev_b32_e32 v202, 16, v125
	v_and_b32_e32 v203, 0xffff0000, v125
	v_mul_f32_e32 v204, v52, v200
	v_mul_f32_e32 v205, v52, v201
	v_mul_f32_e32 v206, v52, v202
	v_mul_f32_e32 v207, v52, v203
	v_fma_f32 v6, v52, v200, v6
	v_fma_f32 v7, v52, v201, v7
	v_fma_f32 v8, v52, v202, v8
	v_fma_f32 v9, v52, v203, v9
	v_lshlrev_b32_e32 v88, 16, v108
	v_and_b32_e32 v89, 0xffff0000, v108
	v_lshlrev_b32_e32 v90, 16, v109
	v_and_b32_e32 v91, 0xffff0000, v109
	v_mul_f32_e32 v88, v44, v88
	v_mul_f32_e32 v89, v44, v89
	v_mul_f32_e32 v90, v44, v90
	v_mul_f32_e32 v91, v44, v91
	v_sub_f32_e32 v6, v6, v88
	v_sub_f32_e32 v7, v7, v89
	v_sub_f32_e32 v8, v8, v90
	v_sub_f32_e32 v9, v9, v91
	v_add_u32_e32 v92, 5, v20
	v_min_i32_e32 v92, v92, v32
	v_cvt_f32_i32_e32 v92, v92
	v_div_scale_f32 v26, s[0:1], v92, v92, 1.0
	v_rcp_f32_e32 v27, v26
	s_nop 0
	v_fma_f32 v28, -v26, v27, 1.0
	v_fmac_f32_e32 v27, v28, v27
	v_div_scale_f32 v28, vcc, 1.0, v92, 1.0
	v_mul_f32_e32 v29, v28, v27
	v_fma_f32 v30, -v26, v29, v28
	v_fmac_f32_e32 v29, v30, v27
	v_fma_f32 v26, -v26, v29, v28
	s_nop 1
	v_div_fmas_f32 v93, v26, v27, v29
	v_div_fixup_f32 v93, v93, v92, 1.0
	v_fma_f32 v214, v93, v6, -v204
	v_fma_f32 v215, v93, v7, -v205
	v_fma_f32 v216, v93, v8, -v206
	v_fma_f32 v217, v93, v9, -v207
	v_mul_f32_e32 v214, v2, v214
	v_mul_f32_e32 v215, v3, v215
	v_mul_f32_e32 v216, v4, v216
	v_mul_f32_e32 v217, v5, v217
	v_cvt_pk_bf16_f32 v218, v214, v215
	v_cvt_pk_bf16_f32 v219, v216, v217
	global_store_dwordx2 v[24:25], v[218:219], off sc1
	s_waitcnt vmcnt(31)
; __device__ __forceinline__ unsigned pk2(float lo, float hi) { return pg8::cvt_pk_bf16(lo, hi); }
; __device__ __forceinline__ f32x4 ld4bf(const bf16* p) { const v2u w = *(const v2u*)p; return (f32x4){bf_lo(w.x), bf_hi(w.x), bf_lo(w.y), bf_hi(w.y)}; }
; __device__ __forceinline__ void pool_prep(const bf16* X, const float* ss, const float* gain, bf16* PB, LAS unsigned char* lds, int vcu, int G, int tid) {
;     ...
;         for (int i = 0; i < 32; ++i) { const int row = ra + i, t = row - bstart;
;             const f32x4 xn = ld4bf(xp + (size_t)row * DM) * rsl[row - r0 + 16];
;             f32x4 old = {0.f, 0.f, 0.f, 0.f};
;             if (t >= w) old = ld4bf(xp + (size_t)(row - w) * DM) * rsl[row - w - r0 + 16];
;             S = S + xn - old;
;             const int cnt = (t + 1 < w) ? t + 1 : w;
;             const f32x4 p = (S * (1.0f / (float)cnt) - xn) * gn;
;             v2u o; o.x = pk2(p[0], p[1]); o.y = pk2(p[2], p[3]); *(v2u*)(PB + (size_t)row * DM + 4 * q) = o; }
	v_lshlrev_b32_e32 v200, 16, v126
	v_and_b32_e32 v201, 0xffff0000, v126
	v_lshlrev_b32_e32 v202, 16, v127
	v_and_b32_e32 v203, 0xffff0000, v127
	v_mul_f32_e32 v204, v53, v200
	v_mul_f32_e32 v205, v53, v201
	v_mul_f32_e32 v206, v53, v202
	v_mul_f32_e32 v207, v53, v203
	v_fma_f32 v6, v53, v200, v6
	v_fma_f32 v7, v53, v201, v7
	v_fma_f32 v8, v53, v202, v8
	v_fma_f32 v9, v53, v203, v9
	v_lshlrev_b32_e32 v88, 16, v110
	v_and_b32_e32 v89, 0xffff0000, v110
	v_lshlrev_b32_e32 v90, 16, v111
	v_and_b32_e32 v91, 0xffff0000, v111
	v_mul_f32_e32 v88, v45, v88
	v_mul_f32_e32 v89, v45, v89
	v_mul_f32_e32 v90, v45, v90
	v_mul_f32_e32 v91, v45, v91
	v_sub_f32_e32 v6, v6, v88
	v_sub_f32_e32 v7, v7, v89
	v_sub_f32_e32 v8, v8, v90
	v_sub_f32_e32 v9, v9, v91
	v_add_u32_e32 v92, 6, v20
	v_min_i32_e32 v92, v92, v32
	v_cvt_f32_i32_e32 v92, v92
	v_div_scale_f32 v26, s[0:1], v92, v92, 1.0
	v_rcp_f32_e32 v27, v26
	s_nop 0
	v_fma_f32 v28, -v26, v27, 1.0
	v_fmac_f32_e32 v27, v28, v27
	v_div_scale_f32 v28, vcc, 1.0, v92, 1.0
	v_mul_f32_e32 v29, v28, v27
	v_fma_f32 v30, -v26, v29, v28
	v_fmac_f32_e32 v29, v30, v27
	v_fma_f32 v26, -v26, v29, v28
	s_nop 1
	v_div_fmas_f32 v93, v26, v27, v29
	v_div_fixup_f32 v93, v93, v92, 1.0
	v_fma_f32 v214, v93, v6, -v204
	v_fma_f32 v215, v93, v7, -v205
	v_fma_f32 v216, v93, v8, -v206
	v_fma_f32 v217, v93, v9, -v207
	v_mul_f32_e32 v214, v2, v214
	v_mul_f32_e32 v215, v3, v215
	v_mul_f32_e32 v216, v4, v216
	v_mul_f32_e32 v217, v5, v217
	v_cvt_pk_bf16_f32 v218, v214, v215
	v_cvt_pk_bf16_f32 v219, v216, v217
	global_store_dwordx2 v[24:25], v[218:219], off offset:2048 sc1
	s_mov_b64 s[0:1], 0x1000
	v_lshl_add_u64 v[24:25], v[24:25], 0, s[0:1]
	s_waitcnt vmcnt(31)
	v_lshlrev_b32_e32 v200, 16, v128
	v_and_b32_e32 v201, 0xffff0000, v128
	v_lshlrev_b32_e32 v202, 16, v129
	v_and_b32_e32 v203, 0xffff0000, v129
	v_mul_f32_e32 v204, v54, v200
	v_mul_f32_e32 v205, v54, v201
	v_mul_f32_e32 v206, v54, v202
	v_mul_f32_e32 v207, v54, v203
	v_fma_f32 v6, v54, v200, v6
	v_fma_f32 v7, v54, v201, v7
	v_fma_f32 v8, v54, v202, v8
	v_fma_f32 v9, v54, v203, v9
	v_lshlrev_b32_e32 v88, 16, v112
	v_and_b32_e32 v89, 0xffff0000, v112
	v_lshlrev_b32_e32 v90, 16, v113
	v_and_b32_e32 v91, 0xffff0000, v113
	v_mul_f32_e32 v88, v46, v88
	v_mul_f32_e32 v89, v46, v89
	v_mul_f32_e32 v90, v46, v90
	v_mul_f32_e32 v91, v46, v91
	v_sub_f32_e32 v6, v6, v88
	v_sub_f32_e32 v7, v7, v89
	v_sub_f32_e32 v8, v8, v90
	v_sub_f32_e32 v9, v9, v91
	v_add_u32_e32 v92, 7, v20
	v_min_i32_e32 v92, v92, v32
	v_cvt_f32_i32_e32 v92, v92
	v_div_scale_f32 v26, s[0:1], v92, v92, 1.0
	v_rcp_f32_e32 v27, v26
	s_nop 0
	v_fma_f32 v28, -v26, v27, 1.0
	v_fmac_f32_e32 v27, v28, v27
	v_div_scale_f32 v28, vcc, 1.0, v92, 1.0
	v_mul_f32_e32 v29, v28, v27
	v_fma_f32 v30, -v26, v29, v28
	v_fmac_f32_e32 v29, v30, v27
	v_fma_f32 v26, -v26, v29, v28
	s_nop 1
	v_div_fmas_f32 v93, v26, v27, v29
	v_div_fixup_f32 v93, v93, v92, 1.0
	v_fma_f32 v214, v93, v6, -v204
	v_fma_f32 v215, v93, v7, -v205
	v_fma_f32 v216, v93, v8, -v206
	v_fma_f32 v217, v93, v9, -v207
	v_mul_f32_e32 v214, v2, v214
	v_mul_f32_e32 v215, v3, v215
	v_mul_f32_e32 v216, v4, v216
	v_mul_f32_e32 v217, v5, v217
	v_cvt_pk_bf16_f32 v218, v214, v215
	v_cvt_pk_bf16_f32 v219, v216, v217
	global_store_dwordx2 v[24:25], v[218:219], off sc1
	s_waitcnt vmcnt(31)
	v_lshlrev_b32_e32 v200, 16, v130
	v_and_b32_e32 v201, 0xffff0000, v130
	v_lshlrev_b32_e32 v202, 16, v131
	v_and_b32_e32 v203, 0xffff0000, v131
	v_mul_f32_e32 v204, v55, v200
	v_mul_f32_e32 v205, v55, v201
	v_mul_f32_e32 v206, v55, v202
	v_mul_f32_e32 v207, v55, v203
	v_fma_f32 v6, v55, v200, v6
	v_fma_f32 v7, v55, v201, v7
	v_fma_f32 v8, v55, v202, v8
	v_fma_f32 v9, v55, v203, v9
	v_lshlrev_b32_e32 v88, 16, v114
	v_and_b32_e32 v89, 0xffff0000, v114
	v_lshlrev_b32_e32 v90, 16, v115
	v_and_b32_e32 v91, 0xffff0000, v115
	v_mul_f32_e32 v88, v47, v88
	v_mul_f32_e32 v89, v47, v89
	v_mul_f32_e32 v90, v47, v90
	v_mul_f32_e32 v91, v47, v91
	v_sub_f32_e32 v6, v6, v88
	v_sub_f32_e32 v7, v7, v89
	v_sub_f32_e32 v8, v8, v90
	v_sub_f32_e32 v9, v9, v91
	v_fma_f32 v214, v197, v6, -v204
	v_fma_f32 v215, v197, v7, -v205
	v_fma_f32 v216, v197, v8, -v206
	v_fma_f32 v217, v197, v9, -v207
	v_mul_f32_e32 v214, v2, v214
	v_mul_f32_e32 v215, v3, v215
	v_mul_f32_e32 v216, v4, v216
	v_mul_f32_e32 v217, v5, v217
	v_cvt_pk_bf16_f32 v218, v214, v215
	v_cvt_pk_bf16_f32 v219, v216, v217
	global_store_dwordx2 v[24:25], v[218:219], off offset:2048 sc1
	s_mov_b64 s[0:1], 0x1000
	v_lshl_add_u64 v[24:25], v[24:25], 0, s[0:1]
	s_waitcnt vmcnt(31)
	v_lshlrev_b32_e32 v200, 16, v132
	v_and_b32_e32 v201, 0xffff0000, v132
	v_lshlrev_b32_e32 v202, 16, v133
	v_and_b32_e32 v203, 0xffff0000, v133
	v_mul_f32_e32 v204, v56, v200
	v_mul_f32_e32 v205, v56, v201
	v_mul_f32_e32 v206, v56, v202
	v_mul_f32_e32 v207, v56, v203
	v_fma_f32 v6, v56, v200, v6
	v_fma_f32 v7, v56, v201, v7
	v_fma_f32 v8, v56, v202, v8
	v_fma_f32 v9, v56, v203, v9
	v_lshlrev_b32_e32 v88, 16, v116
	v_and_b32_e32 v89, 0xffff0000, v116
	v_lshlrev_b32_e32 v90, 16, v117
	v_and_b32_e32 v91, 0xffff0000, v117
	v_mul_f32_e32 v88, v48, v88
	v_mul_f32_e32 v89, v48, v89
	v_mul_f32_e32 v90, v48, v90
	v_mul_f32_e32 v91, v48, v91
	v_sub_f32_e32 v6, v6, v88
	v_sub_f32_e32 v7, v7, v89
	v_sub_f32_e32 v8, v8, v90
	v_sub_f32_e32 v9, v9, v91
	v_fma_f32 v214, v197, v6, -v204
	v_fma_f32 v215, v197, v7, -v205
	v_fma_f32 v216, v197, v8, -v206
	v_fma_f32 v217, v197, v9, -v207
	v_mul_f32_e32 v214, v2, v214
	v_mul_f32_e32 v215, v3, v215
	v_mul_f32_e32 v216, v4, v216
	v_mul_f32_e32 v217, v5, v217
	v_cvt_pk_bf16_f32 v218, v214, v215
	v_cvt_pk_bf16_f32 v219, v216, v217
	global_store_dwordx2 v[24:25], v[218:219], off sc1
	s_waitcnt vmcnt(31)
; __device__ __forceinline__ unsigned pk2(float lo, float hi) { return pg8::cvt_pk_bf16(lo, hi); }
; __device__ __forceinline__ f32x4 ld4bf(const bf16* p) { const v2u w = *(const v2u*)p; return (f32x4){bf_lo(w.x), bf_hi(w.x), bf_lo(w.y), bf_hi(w.y)}; }
; __device__ __forceinline__ void pool_prep(const bf16* X, const float* ss, const float* gain, bf16* PB, LAS unsigned char* lds, int vcu, int G, int tid) {
;     ...
;         for (int i = 0; i < 32; ++i) { const int row = ra + i, t = row - bstart;
;             const f32x4 xn = ld4bf(xp + (size_t)row * DM) * rsl[row - r0 + 16];
;             f32x4 old = {0.f, 0.f, 0.f, 0.f};
;             if (t >= w) old = ld4bf(xp + (size_t)(row - w) * DM) * rsl[row - w - r0 + 16];
;             S = S + xn - old;
;             const int cnt = (t + 1 < w) ? t + 1 : w;
;             const f32x4 p = (S * (1.0f / (float)cnt) - xn) * gn;
;             v2u o; o.x = pk2(p[0], p[1]); o.y = pk2(p[2], p[3]); *(v2u*)(PB + (size_t)row * DM + 4 * q) = o; }
	v_lshlrev_b32_e32 v200, 16, v134
	v_and_b32_e32 v201, 0xffff0000, v134
	v_lshlrev_b32_e32 v202, 16, v135
	v_and_b32_e32 v203, 0xffff0000, v135
	v_mul_f32_e32 v204, v57, v200
	v_mul_f32_e32 v205, v57, v201
	v_mul_f32_e32 v206, v57, v202
	v_mul_f32_e32 v207, v57, v203
	v_fma_f32 v6, v57, v200, v6
	v_fma_f32 v7, v57, v201, v7
	v_fma_f32 v8, v57, v202, v8
	v_fma_f32 v9, v57, v203, v9
	v_lshlrev_b32_e32 v88, 16, v118
	v_and_b32_e32 v89, 0xffff0000, v118
	v_lshlrev_b32_e32 v90, 16, v119
	v_and_b32_e32 v91, 0xffff0000, v119
	v_mul_f32_e32 v88, v49, v88
	v_mul_f32_e32 v89, v49, v89
	v_mul_f32_e32 v90, v49, v90
	v_mul_f32_e32 v91, v49, v91
	v_sub_f32_e32 v6, v6, v88
	v_sub_f32_e32 v7, v7, v89
	v_sub_f32_e32 v8, v8, v90
	v_sub_f32_e32 v9, v9, v91
	v_fma_f32 v214, v197, v6, -v204
	v_fma_f32 v215, v197, v7, -v205
	v_fma_f32 v216, v197, v8, -v206
	v_fma_f32 v217, v197, v9, -v207
	v_mul_f32_e32 v214, v2, v214
	v_mul_f32_e32 v215, v3, v215
	v_mul_f32_e32 v216, v4, v216
	v_mul_f32_e32 v217, v5, v217
	v_cvt_pk_bf16_f32 v218, v214, v215
	v_cvt_pk_bf16_f32 v219, v216, v217
	global_store_dwordx2 v[24:25], v[218:219], off offset:2048 sc1
	s_mov_b64 s[0:1], 0x1000
	v_lshl_add_u64 v[24:25], v[24:25], 0, s[0:1]
	s_waitcnt vmcnt(31)
	v_lshlrev_b32_e32 v200, 16, v136
	v_and_b32_e32 v201, 0xffff0000, v136
	v_lshlrev_b32_e32 v202, 16, v137
	v_and_b32_e32 v203, 0xffff0000, v137
	v_mul_f32_e32 v204, v58, v200
	v_mul_f32_e32 v205, v58, v201
	v_mul_f32_e32 v206, v58, v202
	v_mul_f32_e32 v207, v58, v203
	v_fma_f32 v6, v58, v200, v6
	v_fma_f32 v7, v58, v201, v7
	v_fma_f32 v8, v58, v202, v8
	v_fma_f32 v9, v58, v203, v9
	v_lshlrev_b32_e32 v88, 16, v120
	v_and_b32_e32 v89, 0xffff0000, v120
	v_lshlrev_b32_e32 v90, 16, v121
	v_and_b32_e32 v91, 0xffff0000, v121
	v_mul_f32_e32 v88, v50, v88
	v_mul_f32_e32 v89, v50, v89
	v_mul_f32_e32 v90, v50, v90
	v_mul_f32_e32 v91, v50, v91
	v_sub_f32_e32 v6, v6, v88
	v_sub_f32_e32 v7, v7, v89
	v_sub_f32_e32 v8, v8, v90
	v_sub_f32_e32 v9, v9, v91
	v_fma_f32 v214, v197, v6, -v204
	v_fma_f32 v215, v197, v7, -v205
	v_fma_f32 v216, v197, v8, -v206
	v_fma_f32 v217, v197, v9, -v207
	v_mul_f32_e32 v214, v2, v214
	v_mul_f32_e32 v215, v3, v215
	v_mul_f32_e32 v216, v4, v216
	v_mul_f32_e32 v217, v5, v217
	v_cvt_pk_bf16_f32 v218, v214, v215
	v_cvt_pk_bf16_f32 v219, v216, v217
	global_store_dwordx2 v[24:25], v[218:219], off sc1
	s_waitcnt vmcnt(31)
	v_lshlrev_b32_e32 v200, 16, v138
	v_and_b32_e32 v201, 0xffff0000, v138
	v_lshlrev_b32_e32 v202, 16, v139
	v_and_b32_e32 v203, 0xffff0000, v139
	v_mul_f32_e32 v204, v59, v200
	v_mul_f32_e32 v205, v59, v201
	v_mul_f32_e32 v206, v59, v202
	v_mul_f32_e32 v207, v59, v203
	v_fma_f32 v6, v59, v200, v6
	v_fma_f32 v7, v59, v201, v7
	v_fma_f32 v8, v59, v202, v8
	v_fma_f32 v9, v59, v203, v9
	v_lshlrev_b32_e32 v88, 16, v122
	v_and_b32_e32 v89, 0xffff0000, v122
	v_lshlrev_b32_e32 v90, 16, v123
	v_and_b32_e32 v91, 0xffff0000, v123
	v_mul_f32_e32 v88, v51, v88
	v_mul_f32_e32 v89, v51, v89
	v_mul_f32_e32 v90, v51, v90
	v_mul_f32_e32 v91, v51, v91
	v_sub_f32_e32 v6, v6, v88
	v_sub_f32_e32 v7, v7, v89
	v_sub_f32_e32 v8, v8, v90
	v_sub_f32_e32 v9, v9, v91
	v_fma_f32 v214, v197, v6, -v204
	v_fma_f32 v215, v197, v7, -v205
	v_fma_f32 v216, v197, v8, -v206
	v_fma_f32 v217, v197, v9, -v207
	v_mul_f32_e32 v214, v2, v214
	v_mul_f32_e32 v215, v3, v215
	v_mul_f32_e32 v216, v4, v216
	v_mul_f32_e32 v217, v5, v217
	v_cvt_pk_bf16_f32 v218, v214, v215
	v_cvt_pk_bf16_f32 v219, v216, v217
	global_store_dwordx2 v[24:25], v[218:219], off offset:2048 sc1
	s_mov_b64 s[0:1], 0x1000
	v_lshl_add_u64 v[24:25], v[24:25], 0, s[0:1]
	s_waitcnt vmcnt(31)
	v_lshlrev_b32_e32 v200, 16, v140
	v_and_b32_e32 v201, 0xffff0000, v140
	v_lshlrev_b32_e32 v202, 16, v141
	v_and_b32_e32 v203, 0xffff0000, v141
	v_mul_f32_e32 v204, v60, v200
	v_mul_f32_e32 v205, v60, v201
	v_mul_f32_e32 v206, v60, v202
	v_mul_f32_e32 v207, v60, v203
	v_fma_f32 v6, v60, v200, v6
	v_fma_f32 v7, v60, v201, v7
	v_fma_f32 v8, v60, v202, v8
	v_fma_f32 v9, v60, v203, v9
	v_lshlrev_b32_e32 v88, 16, v124
	v_and_b32_e32 v89, 0xffff0000, v124
	v_lshlrev_b32_e32 v90, 16, v125
	v_and_b32_e32 v91, 0xffff0000, v125
	v_mul_f32_e32 v88, v52, v88
	v_mul_f32_e32 v89, v52, v89
	v_mul_f32_e32 v90, v52, v90
	v_mul_f32_e32 v91, v52, v91
	v_sub_f32_e32 v6, v6, v88
	v_sub_f32_e32 v7, v7, v89
	v_sub_f32_e32 v8, v8, v90
	v_sub_f32_e32 v9, v9, v91
	v_fma_f32 v214, v197, v6, -v204
	v_fma_f32 v215, v197, v7, -v205
	v_fma_f32 v216, v197, v8, -v206
	v_fma_f32 v217, v197, v9, -v207
	v_mul_f32_e32 v214, v2, v214
	v_mul_f32_e32 v215, v3, v215
	v_mul_f32_e32 v216, v4, v216
	v_mul_f32_e32 v217, v5, v217
	v_cvt_pk_bf16_f32 v218, v214, v215
	v_cvt_pk_bf16_f32 v219, v216, v217
	global_store_dwordx2 v[24:25], v[218:219], off sc1
	s_waitcnt vmcnt(31)
	v_lshlrev_b32_e32 v200, 16, v142
	v_and_b32_e32 v201, 0xffff0000, v142
	v_lshlrev_b32_e32 v202, 16, v143
	v_and_b32_e32 v203, 0xffff0000, v143
	v_mul_f32_e32 v204, v61, v200
	v_mul_f32_e32 v205, v61, v201
	v_mul_f32_e32 v206, v61, v202
	v_mul_f32_e32 v207, v61, v203
	v_fma_f32 v6, v61, v200, v6
	v_fma_f32 v7, v61, v201, v7
	v_fma_f32 v8, v61, v202, v8
	v_fma_f32 v9, v61, v203, v9
	v_lshlrev_b32_e32 v88, 16, v126
	v_and_b32_e32 v89, 0xffff0000, v126
	v_lshlrev_b32_e32 v90, 16, v127
	v_and_b32_e32 v91, 0xffff0000, v127
	v_mul_f32_e32 v88, v53, v88
	v_mul_f32_e32 v89, v53, v89
	v_mul_f32_e32 v90, v53, v90
	v_mul_f32_e32 v91, v53, v91
	v_sub_f32_e32 v6, v6, v88
	v_sub_f32_e32 v7, v7, v89
	v_sub_f32_e32 v8, v8, v90
	v_sub_f32_e32 v9, v9, v91
	v_fma_f32 v214, v197, v6, -v204
	v_fma_f32 v215, v197, v7, -v205
	v_fma_f32 v216, v197, v8, -v206
	v_fma_f32 v217, v197, v9, -v207
	v_mul_f32_e32 v214, v2, v214
	v_mul_f32_e32 v215, v3, v215
	v_mul_f32_e32 v216, v4, v216
	v_mul_f32_e32 v217, v5, v217
	v_cvt_pk_bf16_f32 v218, v214, v215
	v_cvt_pk_bf16_f32 v219, v216, v217
	global_store_dwordx2 v[24:25], v[218:219], off offset:2048 sc1
	s_mov_b64 s[0:1], 0x1000
	v_lshl_add_u64 v[24:25], v[24:25], 0, s[0:1]
	s_waitcnt vmcnt(31)
; __device__ __forceinline__ unsigned pk2(float lo, float hi) { return pg8::cvt_pk_bf16(lo, hi); }
; __device__ __forceinline__ f32x4 ld4bf(const bf16* p) { const v2u w = *(const v2u*)p; return (f32x4){bf_lo(w.x), bf_hi(w.x), bf_lo(w.y), bf_hi(w.y)}; }
; __device__ __forceinline__ void pool_prep(const bf16* X, const float* ss, const float* gain, bf16* PB, LAS unsigned char* lds, int vcu, int G, int tid) {
;     ...
;         for (int i = 0; i < 32; ++i) { const int row = ra + i, t = row - bstart;
;             const f32x4 xn = ld4bf(xp + (size_t)row * DM) * rsl[row - r0 + 16];
;             f32x4 old = {0.f, 0.f, 0.f, 0.f};
;             if (t >= w) old = ld4bf(xp + (size_t)(row - w) * DM) * rsl[row - w - r0 + 16];
;             S = S + xn - old;
;             const int cnt = (t + 1 < w) ? t + 1 : w;
;             const f32x4 p = (S * (1.0f / (float)cnt) - xn) * gn;
;             v2u o; o.x = pk2(p[0], p[1]); o.y = pk2(p[2], p[3]); *(v2u*)(PB + (size_t)row * DM + 4 * q) = o; }
	v_lshlrev_b32_e32 v200, 16, v144
	v_and_b32_e32 v201, 0xffff0000, v144
	v_lshlrev_b32_e32 v202, 16, v145
	v_and_b32_e32 v203, 0xffff0000, v145
	v_mul_f32_e32 v204, v62, v200
	v_mul_f32_e32 v205, v62, v201
	v_mul_f32_e32 v206, v62, v202
	v_mul_f32_e32 v207, v62, v203
	v_fma_f32 v6, v62, v200, v6
	v_fma_f32 v7, v62, v201, v7
	v_fma_f32 v8, v62, v202, v8
	v_fma_f32 v9, v62, v203, v9
	v_lshlrev_b32_e32 v88, 16, v128
	v_and_b32_e32 v89, 0xffff0000, v128
	v_lshlrev_b32_e32 v90, 16, v129
	v_and_b32_e32 v91, 0xffff0000, v129
	v_mul_f32_e32 v88, v54, v88
	v_mul_f32_e32 v89, v54, v89
	v_mul_f32_e32 v90, v54, v90
	v_mul_f32_e32 v91, v54, v91
	v_sub_f32_e32 v6, v6, v88
	v_sub_f32_e32 v7, v7, v89
	v_sub_f32_e32 v8, v8, v90
	v_sub_f32_e32 v9, v9, v91
	v_fma_f32 v214, v197, v6, -v204
	v_fma_f32 v215, v197, v7, -v205
	v_fma_f32 v216, v197, v8, -v206
	v_fma_f32 v217, v197, v9, -v207
	v_mul_f32_e32 v214, v2, v214
	v_mul_f32_e32 v215, v3, v215
	v_mul_f32_e32 v216, v4, v216
	v_mul_f32_e32 v217, v5, v217
	v_cvt_pk_bf16_f32 v218, v214, v215
	v_cvt_pk_bf16_f32 v219, v216, v217
	global_store_dwordx2 v[24:25], v[218:219], off sc1
	s_waitcnt vmcnt(31)
	v_lshlrev_b32_e32 v200, 16, v146
	v_and_b32_e32 v201, 0xffff0000, v146
	v_lshlrev_b32_e32 v202, 16, v147
	v_and_b32_e32 v203, 0xffff0000, v147
	v_mul_f32_e32 v204, v63, v200
	v_mul_f32_e32 v205, v63, v201
	v_mul_f32_e32 v206, v63, v202
	v_mul_f32_e32 v207, v63, v203
	v_fma_f32 v6, v63, v200, v6
	v_fma_f32 v7, v63, v201, v7
	v_fma_f32 v8, v63, v202, v8
	v_fma_f32 v9, v63, v203, v9
	v_lshlrev_b32_e32 v88, 16, v130
	v_and_b32_e32 v89, 0xffff0000, v130
	v_lshlrev_b32_e32 v90, 16, v131
	v_and_b32_e32 v91, 0xffff0000, v131
	v_mul_f32_e32 v88, v55, v88
	v_mul_f32_e32 v89, v55, v89
	v_mul_f32_e32 v90, v55, v90
	v_mul_f32_e32 v91, v55, v91
	v_sub_f32_e32 v6, v6, v88
	v_sub_f32_e32 v7, v7, v89
	v_sub_f32_e32 v8, v8, v90
	v_sub_f32_e32 v9, v9, v91
	v_fma_f32 v214, v197, v6, -v204
	v_fma_f32 v215, v197, v7, -v205
	v_fma_f32 v216, v197, v8, -v206
	v_fma_f32 v217, v197, v9, -v207
	v_mul_f32_e32 v214, v2, v214
	v_mul_f32_e32 v215, v3, v215
	v_mul_f32_e32 v216, v4, v216
	v_mul_f32_e32 v217, v5, v217
	v_cvt_pk_bf16_f32 v218, v214, v215
	v_cvt_pk_bf16_f32 v219, v216, v217
	global_store_dwordx2 v[24:25], v[218:219], off offset:2048 sc1
	s_mov_b64 s[0:1], 0x1000
	v_lshl_add_u64 v[24:25], v[24:25], 0, s[0:1]
	s_waitcnt vmcnt(31)
	v_lshlrev_b32_e32 v200, 16, v148
	v_and_b32_e32 v201, 0xffff0000, v148
	v_lshlrev_b32_e32 v202, 16, v149
	v_and_b32_e32 v203, 0xffff0000, v149
	v_mul_f32_e32 v204, v64, v200
	v_mul_f32_e32 v205, v64, v201
	v_mul_f32_e32 v206, v64, v202
	v_mul_f32_e32 v207, v64, v203
	v_fma_f32 v6, v64, v200, v6
	v_fma_f32 v7, v64, v201, v7
	v_fma_f32 v8, v64, v202, v8
	v_fma_f32 v9, v64, v203, v9
	v_lshlrev_b32_e32 v88, 16, v132
	v_and_b32_e32 v89, 0xffff0000, v132
	v_lshlrev_b32_e32 v90, 16, v133
	v_and_b32_e32 v91, 0xffff0000, v133
	v_mul_f32_e32 v88, v56, v88
	v_mul_f32_e32 v89, v56, v89
	v_mul_f32_e32 v90, v56, v90
	v_mul_f32_e32 v91, v56, v91
	v_sub_f32_e32 v6, v6, v88
	v_sub_f32_e32 v7, v7, v89
	v_sub_f32_e32 v8, v8, v90
	v_sub_f32_e32 v9, v9, v91
	v_fma_f32 v214, v197, v6, -v204
	v_fma_f32 v215, v197, v7, -v205
	v_fma_f32 v216, v197, v8, -v206
	v_fma_f32 v217, v197, v9, -v207
	v_mul_f32_e32 v214, v2, v214
	v_mul_f32_e32 v215, v3, v215
	v_mul_f32_e32 v216, v4, v216
	v_mul_f32_e32 v217, v5, v217
	v_cvt_pk_bf16_f32 v218, v214, v215
	v_cvt_pk_bf16_f32 v219, v216, v217
	global_store_dwordx2 v[24:25], v[218:219], off sc1
	s_waitcnt vmcnt(31)
	v_lshlrev_b32_e32 v200, 16, v150
	v_and_b32_e32 v201, 0xffff0000, v150
	v_lshlrev_b32_e32 v202, 16, v151
	v_and_b32_e32 v203, 0xffff0000, v151
	v_mul_f32_e32 v204, v65, v200
	v_mul_f32_e32 v205, v65, v201
	v_mul_f32_e32 v206, v65, v202
	v_mul_f32_e32 v207, v65, v203
	v_fma_f32 v6, v65, v200, v6
	v_fma_f32 v7, v65, v201, v7
	v_fma_f32 v8, v65, v202, v8
	v_fma_f32 v9, v65, v203, v9
	v_lshlrev_b32_e32 v88, 16, v134
	v_and_b32_e32 v89, 0xffff0000, v134
	v_lshlrev_b32_e32 v90, 16, v135
	v_and_b32_e32 v91, 0xffff0000, v135
	v_mul_f32_e32 v88, v57, v88
	v_mul_f32_e32 v89, v57, v89
	v_mul_f32_e32 v90, v57, v90
	v_mul_f32_e32 v91, v57, v91
	v_sub_f32_e32 v6, v6, v88
	v_sub_f32_e32 v7, v7, v89
	v_sub_f32_e32 v8, v8, v90
	v_sub_f32_e32 v9, v9, v91
	v_fma_f32 v214, v197, v6, -v204
	v_fma_f32 v215, v197, v7, -v205
	v_fma_f32 v216, v197, v8, -v206
	v_fma_f32 v217, v197, v9, -v207
	v_mul_f32_e32 v214, v2, v214
	v_mul_f32_e32 v215, v3, v215
	v_mul_f32_e32 v216, v4, v216
	v_mul_f32_e32 v217, v5, v217
	v_cvt_pk_bf16_f32 v218, v214, v215
	v_cvt_pk_bf16_f32 v219, v216, v217
	global_store_dwordx2 v[24:25], v[218:219], off offset:2048 sc1
	s_mov_b64 s[0:1], 0x1000
	v_lshl_add_u64 v[24:25], v[24:25], 0, s[0:1]
	s_waitcnt vmcnt(31)
	v_lshlrev_b32_e32 v200, 16, v152
	v_and_b32_e32 v201, 0xffff0000, v152
	v_lshlrev_b32_e32 v202, 16, v153
	v_and_b32_e32 v203, 0xffff0000, v153
	v_mul_f32_e32 v204, v66, v200
	v_mul_f32_e32 v205, v66, v201
	v_mul_f32_e32 v206, v66, v202
	v_mul_f32_e32 v207, v66, v203
	v_fma_f32 v6, v66, v200, v6
	v_fma_f32 v7, v66, v201, v7
	v_fma_f32 v8, v66, v202, v8
	v_fma_f32 v9, v66, v203, v9
	v_lshlrev_b32_e32 v88, 16, v136
	v_and_b32_e32 v89, 0xffff0000, v136
	v_lshlrev_b32_e32 v90, 16, v137
	v_and_b32_e32 v91, 0xffff0000, v137
	v_mul_f32_e32 v88, v58, v88
	v_mul_f32_e32 v89, v58, v89
	v_mul_f32_e32 v90, v58, v90
	v_mul_f32_e32 v91, v58, v91
	v_sub_f32_e32 v6, v6, v88
	v_sub_f32_e32 v7, v7, v89
	v_sub_f32_e32 v8, v8, v90
	v_sub_f32_e32 v9, v9, v91
	v_fma_f32 v214, v197, v6, -v204
	v_fma_f32 v215, v197, v7, -v205
	v_fma_f32 v216, v197, v8, -v206
	v_fma_f32 v217, v197, v9, -v207
	v_mul_f32_e32 v214, v2, v214
	v_mul_f32_e32 v215, v3, v215
	v_mul_f32_e32 v216, v4, v216
	v_mul_f32_e32 v217, v5, v217
	v_cvt_pk_bf16_f32 v218, v214, v215
	v_cvt_pk_bf16_f32 v219, v216, v217
	global_store_dwordx2 v[24:25], v[218:219], off sc1
	s_waitcnt vmcnt(31)
; __device__ __forceinline__ unsigned pk2(float lo, float hi) { return pg8::cvt_pk_bf16(lo, hi); }
; __device__ __forceinline__ f32x4 ld4bf(const bf16* p) { const v2u w = *(const v2u*)p; return (f32x4){bf_lo(w.x), bf_hi(w.x), bf_lo(w.y), bf_hi(w.y)}; }
; __device__ __forceinline__ void pool_prep(const bf16* X, const float* ss, const float* gain, bf16* PB, LAS unsigned char* lds, int vcu, int G, int tid) {
;     ...
;         for (int i = 0; i < 32; ++i) { const int row = ra + i, t = row - bstart;
;             const f32x4 xn = ld4bf(xp + (size_t)row * DM) * rsl[row - r0 + 16];
;             f32x4 old = {0.f, 0.f, 0.f, 0.f};
;             if (t >= w) old = ld4bf(xp + (size_t)(row - w) * DM) * rsl[row - w - r0 + 16];
;             S = S + xn - old;
;             const int cnt = (t + 1 < w) ? t + 1 : w;
;             const f32x4 p = (S * (1.0f / (float)cnt) - xn) * gn;
;             v2u o; o.x = pk2(p[0], p[1]); o.y = pk2(p[2], p[3]); *(v2u*)(PB + (size_t)row * DM + 4 * q) = o; }
	v_lshlrev_b32_e32 v200, 16, v154
	v_and_b32_e32 v201, 0xffff0000, v154
	v_lshlrev_b32_e32 v202, 16, v155
	v_and_b32_e32 v203, 0xffff0000, v155
	v_mul_f32_e32 v204, v67, v200
	v_mul_f32_e32 v205, v67, v201
	v_mul_f32_e32 v206, v67, v202
	v_mul_f32_e32 v207, v67, v203
	v_fma_f32 v6, v67, v200, v6
	v_fma_f32 v7, v67, v201, v7
	v_fma_f32 v8, v67, v202, v8
	v_fma_f32 v9, v67, v203, v9
	v_lshlrev_b32_e32 v88, 16, v138
	v_and_b32_e32 v89, 0xffff0000, v138
	v_lshlrev_b32_e32 v90, 16, v139
	v_and_b32_e32 v91, 0xffff0000, v139
	v_mul_f32_e32 v88, v59, v88
	v_mul_f32_e32 v89, v59, v89
	v_mul_f32_e32 v90, v59, v90
	v_mul_f32_e32 v91, v59, v91
	v_sub_f32_e32 v6, v6, v88
	v_sub_f32_e32 v7, v7, v89
	v_sub_f32_e32 v8, v8, v90
	v_sub_f32_e32 v9, v9, v91
	v_fma_f32 v214, v197, v6, -v204
	v_fma_f32 v215, v197, v7, -v205
	v_fma_f32 v216, v197, v8, -v206
	v_fma_f32 v217, v197, v9, -v207
	v_mul_f32_e32 v214, v2, v214
	v_mul_f32_e32 v215, v3, v215
	v_mul_f32_e32 v216, v4, v216
	v_mul_f32_e32 v217, v5, v217
	v_cvt_pk_bf16_f32 v218, v214, v215
	v_cvt_pk_bf16_f32 v219, v216, v217
	global_store_dwordx2 v[24:25], v[218:219], off offset:2048 sc1
	s_mov_b64 s[0:1], 0x1000
	v_lshl_add_u64 v[24:25], v[24:25], 0, s[0:1]
	s_waitcnt vmcnt(31)
	v_lshlrev_b32_e32 v200, 16, v156
	v_and_b32_e32 v201, 0xffff0000, v156
	v_lshlrev_b32_e32 v202, 16, v157
	v_and_b32_e32 v203, 0xffff0000, v157
	v_mul_f32_e32 v204, v68, v200
	v_mul_f32_e32 v205, v68, v201
	v_mul_f32_e32 v206, v68, v202
	v_mul_f32_e32 v207, v68, v203
	v_fma_f32 v6, v68, v200, v6
	v_fma_f32 v7, v68, v201, v7
	v_fma_f32 v8, v68, v202, v8
	v_fma_f32 v9, v68, v203, v9
	v_lshlrev_b32_e32 v88, 16, v140
	v_and_b32_e32 v89, 0xffff0000, v140
	v_lshlrev_b32_e32 v90, 16, v141
	v_and_b32_e32 v91, 0xffff0000, v141
	v_mul_f32_e32 v88, v60, v88
	v_mul_f32_e32 v89, v60, v89
	v_mul_f32_e32 v90, v60, v90
	v_mul_f32_e32 v91, v60, v91
	v_sub_f32_e32 v6, v6, v88
	v_sub_f32_e32 v7, v7, v89
	v_sub_f32_e32 v8, v8, v90
	v_sub_f32_e32 v9, v9, v91
	v_fma_f32 v214, v197, v6, -v204
	v_fma_f32 v215, v197, v7, -v205
	v_fma_f32 v216, v197, v8, -v206
	v_fma_f32 v217, v197, v9, -v207
	v_mul_f32_e32 v214, v2, v214
	v_mul_f32_e32 v215, v3, v215
	v_mul_f32_e32 v216, v4, v216
	v_mul_f32_e32 v217, v5, v217
	v_cvt_pk_bf16_f32 v218, v214, v215
	v_cvt_pk_bf16_f32 v219, v216, v217
	global_store_dwordx2 v[24:25], v[218:219], off sc1
	s_waitcnt vmcnt(31)
	v_lshlrev_b32_e32 v200, 16, v158
	v_and_b32_e32 v201, 0xffff0000, v158
	v_lshlrev_b32_e32 v202, 16, v159
	v_and_b32_e32 v203, 0xffff0000, v159
	v_mul_f32_e32 v204, v69, v200
	v_mul_f32_e32 v205, v69, v201
	v_mul_f32_e32 v206, v69, v202
	v_mul_f32_e32 v207, v69, v203
	v_fma_f32 v6, v69, v200, v6
	v_fma_f32 v7, v69, v201, v7
	v_fma_f32 v8, v69, v202, v8
	v_fma_f32 v9, v69, v203, v9
	v_lshlrev_b32_e32 v88, 16, v142
	v_and_b32_e32 v89, 0xffff0000, v142
	v_lshlrev_b32_e32 v90, 16, v143
	v_and_b32_e32 v91, 0xffff0000, v143
	v_mul_f32_e32 v88, v61, v88
	v_mul_f32_e32 v89, v61, v89
	v_mul_f32_e32 v90, v61, v90
	v_mul_f32_e32 v91, v61, v91
	v_sub_f32_e32 v6, v6, v88
	v_sub_f32_e32 v7, v7, v89
	v_sub_f32_e32 v8, v8, v90
	v_sub_f32_e32 v9, v9, v91
	v_fma_f32 v214, v197, v6, -v204
	v_fma_f32 v215, v197, v7, -v205
	v_fma_f32 v216, v197, v8, -v206
	v_fma_f32 v217, v197, v9, -v207
	v_mul_f32_e32 v214, v2, v214
	v_mul_f32_e32 v215, v3, v215
	v_mul_f32_e32 v216, v4, v216
	v_mul_f32_e32 v217, v5, v217
	v_cvt_pk_bf16_f32 v218, v214, v215
	v_cvt_pk_bf16_f32 v219, v216, v217
	global_store_dwordx2 v[24:25], v[218:219], off offset:2048 sc1
	s_mov_b64 s[0:1], 0x1000
	v_lshl_add_u64 v[24:25], v[24:25], 0, s[0:1]
	s_waitcnt vmcnt(31)
	v_lshlrev_b32_e32 v200, 16, v160
	v_and_b32_e32 v201, 0xffff0000, v160
	v_lshlrev_b32_e32 v202, 16, v161
	v_and_b32_e32 v203, 0xffff0000, v161
	v_mul_f32_e32 v204, v70, v200
	v_mul_f32_e32 v205, v70, v201
	v_mul_f32_e32 v206, v70, v202
	v_mul_f32_e32 v207, v70, v203
	v_fma_f32 v6, v70, v200, v6
	v_fma_f32 v7, v70, v201, v7
	v_fma_f32 v8, v70, v202, v8
	v_fma_f32 v9, v70, v203, v9
	v_lshlrev_b32_e32 v88, 16, v144
	v_and_b32_e32 v89, 0xffff0000, v144
	v_lshlrev_b32_e32 v90, 16, v145
	v_and_b32_e32 v91, 0xffff0000, v145
	v_mul_f32_e32 v88, v62, v88
	v_mul_f32_e32 v89, v62, v89
	v_mul_f32_e32 v90, v62, v90
	v_mul_f32_e32 v91, v62, v91
	v_sub_f32_e32 v6, v6, v88
	v_sub_f32_e32 v7, v7, v89
	v_sub_f32_e32 v8, v8, v90
	v_sub_f32_e32 v9, v9, v91
	v_fma_f32 v214, v197, v6, -v204
	v_fma_f32 v215, v197, v7, -v205
	v_fma_f32 v216, v197, v8, -v206
	v_fma_f32 v217, v197, v9, -v207
	v_mul_f32_e32 v214, v2, v214
	v_mul_f32_e32 v215, v3, v215
	v_mul_f32_e32 v216, v4, v216
	v_mul_f32_e32 v217, v5, v217
	v_cvt_pk_bf16_f32 v218, v214, v215
	v_cvt_pk_bf16_f32 v219, v216, v217
	global_store_dwordx2 v[24:25], v[218:219], off sc1
	s_waitcnt vmcnt(31)
	v_lshlrev_b32_e32 v200, 16, v162
	v_and_b32_e32 v201, 0xffff0000, v162
	v_lshlrev_b32_e32 v202, 16, v163
	v_and_b32_e32 v203, 0xffff0000, v163
	v_mul_f32_e32 v204, v71, v200
	v_mul_f32_e32 v205, v71, v201
	v_mul_f32_e32 v206, v71, v202
	v_mul_f32_e32 v207, v71, v203
	v_fma_f32 v6, v71, v200, v6
	v_fma_f32 v7, v71, v201, v7
	v_fma_f32 v8, v71, v202, v8
	v_fma_f32 v9, v71, v203, v9
	v_lshlrev_b32_e32 v88, 16, v146
	v_and_b32_e32 v89, 0xffff0000, v146
	v_lshlrev_b32_e32 v90, 16, v147
	v_and_b32_e32 v91, 0xffff0000, v147
	v_mul_f32_e32 v88, v63, v88
	v_mul_f32_e32 v89, v63, v89
	v_mul_f32_e32 v90, v63, v90
	v_mul_f32_e32 v91, v63, v91
	v_sub_f32_e32 v6, v6, v88
	v_sub_f32_e32 v7, v7, v89
	v_sub_f32_e32 v8, v8, v90
	v_sub_f32_e32 v9, v9, v91
	v_fma_f32 v214, v197, v6, -v204
	v_fma_f32 v215, v197, v7, -v205
	v_fma_f32 v216, v197, v8, -v206
	v_fma_f32 v217, v197, v9, -v207
	v_mul_f32_e32 v214, v2, v214
	v_mul_f32_e32 v215, v3, v215
	v_mul_f32_e32 v216, v4, v216
	v_mul_f32_e32 v217, v5, v217
	v_cvt_pk_bf16_f32 v218, v214, v215
	v_cvt_pk_bf16_f32 v219, v216, v217
	global_store_dwordx2 v[24:25], v[218:219], off offset:2048 sc1
	s_mov_b64 s[0:1], 0x1000
	v_lshl_add_u64 v[24:25], v[24:25], 0, s[0:1]
	s_waitcnt vmcnt(31)
; __device__ __forceinline__ unsigned pk2(float lo, float hi) { return pg8::cvt_pk_bf16(lo, hi); }
; __device__ __forceinline__ f32x4 ld4bf(const bf16* p) { const v2u w = *(const v2u*)p; return (f32x4){bf_lo(w.x), bf_hi(w.x), bf_lo(w.y), bf_hi(w.y)}; }
; __device__ __forceinline__ void pool_prep(const bf16* X, const float* ss, const float* gain, bf16* PB, LAS unsigned char* lds, int vcu, int G, int tid) {
;     ...
;         for (int i = 0; i < 32; ++i) { const int row = ra + i, t = row - bstart;
;             const f32x4 xn = ld4bf(xp + (size_t)row * DM) * rsl[row - r0 + 16];
;             f32x4 old = {0.f, 0.f, 0.f, 0.f};
;             if (t >= w) old = ld4bf(xp + (size_t)(row - w) * DM) * rsl[row - w - r0 + 16];
;             S = S + xn - old;
;             const int cnt = (t + 1 < w) ? t + 1 : w;
;             const f32x4 p = (S * (1.0f / (float)cnt) - xn) * gn;
;             v2u o; o.x = pk2(p[0], p[1]); o.y = pk2(p[2], p[3]); *(v2u*)(PB + (size_t)row * DM + 4 * q) = o; }
	v_lshlrev_b32_e32 v200, 16, v164
	v_and_b32_e32 v201, 0xffff0000, v164
	v_lshlrev_b32_e32 v202, 16, v165
	v_and_b32_e32 v203, 0xffff0000, v165
	v_mul_f32_e32 v204, v72, v200
	v_mul_f32_e32 v205, v72, v201
	v_mul_f32_e32 v206, v72, v202
	v_mul_f32_e32 v207, v72, v203
	v_fma_f32 v6, v72, v200, v6
	v_fma_f32 v7, v72, v201, v7
	v_fma_f32 v8, v72, v202, v8
	v_fma_f32 v9, v72, v203, v9
	v_lshlrev_b32_e32 v88, 16, v148
	v_and_b32_e32 v89, 0xffff0000, v148
	v_lshlrev_b32_e32 v90, 16, v149
	v_and_b32_e32 v91, 0xffff0000, v149
	v_mul_f32_e32 v88, v64, v88
	v_mul_f32_e32 v89, v64, v89
	v_mul_f32_e32 v90, v64, v90
	v_mul_f32_e32 v91, v64, v91
	v_sub_f32_e32 v6, v6, v88
	v_sub_f32_e32 v7, v7, v89
	v_sub_f32_e32 v8, v8, v90
	v_sub_f32_e32 v9, v9, v91
	v_fma_f32 v214, v197, v6, -v204
	v_fma_f32 v215, v197, v7, -v205
	v_fma_f32 v216, v197, v8, -v206
	v_fma_f32 v217, v197, v9, -v207
	v_mul_f32_e32 v214, v2, v214
	v_mul_f32_e32 v215, v3, v215
	v_mul_f32_e32 v216, v4, v216
	v_mul_f32_e32 v217, v5, v217
	v_cvt_pk_bf16_f32 v218, v214, v215
	v_cvt_pk_bf16_f32 v219, v216, v217
	global_store_dwordx2 v[24:25], v[218:219], off sc1
	s_waitcnt vmcnt(31)
	v_lshlrev_b32_e32 v200, 16, v166
	v_and_b32_e32 v201, 0xffff0000, v166
	v_lshlrev_b32_e32 v202, 16, v167
	v_and_b32_e32 v203, 0xffff0000, v167
	v_mul_f32_e32 v204, v73, v200
	v_mul_f32_e32 v205, v73, v201
	v_mul_f32_e32 v206, v73, v202
	v_mul_f32_e32 v207, v73, v203
	v_fma_f32 v6, v73, v200, v6
	v_fma_f32 v7, v73, v201, v7
	v_fma_f32 v8, v73, v202, v8
	v_fma_f32 v9, v73, v203, v9
	v_lshlrev_b32_e32 v88, 16, v150
	v_and_b32_e32 v89, 0xffff0000, v150
	v_lshlrev_b32_e32 v90, 16, v151
	v_and_b32_e32 v91, 0xffff0000, v151
	v_mul_f32_e32 v88, v65, v88
	v_mul_f32_e32 v89, v65, v89
	v_mul_f32_e32 v90, v65, v90
	v_mul_f32_e32 v91, v65, v91
	v_sub_f32_e32 v6, v6, v88
	v_sub_f32_e32 v7, v7, v89
	v_sub_f32_e32 v8, v8, v90
	v_sub_f32_e32 v9, v9, v91
	v_fma_f32 v214, v197, v6, -v204
	v_fma_f32 v215, v197, v7, -v205
	v_fma_f32 v216, v197, v8, -v206
	v_fma_f32 v217, v197, v9, -v207
	v_mul_f32_e32 v214, v2, v214
	v_mul_f32_e32 v215, v3, v215
	v_mul_f32_e32 v216, v4, v216
	v_mul_f32_e32 v217, v5, v217
	v_cvt_pk_bf16_f32 v218, v214, v215
	v_cvt_pk_bf16_f32 v219, v216, v217
	global_store_dwordx2 v[24:25], v[218:219], off offset:2048 sc1
	s_mov_b64 s[0:1], 0x1000
	v_lshl_add_u64 v[24:25], v[24:25], 0, s[0:1]
	s_waitcnt vmcnt(31)
	v_lshlrev_b32_e32 v200, 16, v168
	v_and_b32_e32 v201, 0xffff0000, v168
	v_lshlrev_b32_e32 v202, 16, v169
	v_and_b32_e32 v203, 0xffff0000, v169
	v_mul_f32_e32 v204, v74, v200
	v_mul_f32_e32 v205, v74, v201
	v_mul_f32_e32 v206, v74, v202
	v_mul_f32_e32 v207, v74, v203
	v_fma_f32 v6, v74, v200, v6
	v_fma_f32 v7, v74, v201, v7
	v_fma_f32 v8, v74, v202, v8
	v_fma_f32 v9, v74, v203, v9
	v_lshlrev_b32_e32 v88, 16, v152
	v_and_b32_e32 v89, 0xffff0000, v152
	v_lshlrev_b32_e32 v90, 16, v153
	v_and_b32_e32 v91, 0xffff0000, v153
	v_mul_f32_e32 v88, v66, v88
	v_mul_f32_e32 v89, v66, v89
	v_mul_f32_e32 v90, v66, v90
	v_mul_f32_e32 v91, v66, v91
	v_sub_f32_e32 v6, v6, v88
	v_sub_f32_e32 v7, v7, v89
	v_sub_f32_e32 v8, v8, v90
	v_sub_f32_e32 v9, v9, v91
	v_fma_f32 v214, v197, v6, -v204
	v_fma_f32 v215, v197, v7, -v205
	v_fma_f32 v216, v197, v8, -v206
	v_fma_f32 v217, v197, v9, -v207
	v_mul_f32_e32 v214, v2, v214
	v_mul_f32_e32 v215, v3, v215
	v_mul_f32_e32 v216, v4, v216
	v_mul_f32_e32 v217, v5, v217
	v_cvt_pk_bf16_f32 v218, v214, v215
	v_cvt_pk_bf16_f32 v219, v216, v217
	global_store_dwordx2 v[24:25], v[218:219], off sc1
	s_waitcnt vmcnt(31)
	v_lshlrev_b32_e32 v200, 16, v170
	v_and_b32_e32 v201, 0xffff0000, v170
	v_lshlrev_b32_e32 v202, 16, v171
	v_and_b32_e32 v203, 0xffff0000, v171
	v_mul_f32_e32 v204, v75, v200
	v_mul_f32_e32 v205, v75, v201
	v_mul_f32_e32 v206, v75, v202
	v_mul_f32_e32 v207, v75, v203
	v_fma_f32 v6, v75, v200, v6
	v_fma_f32 v7, v75, v201, v7
	v_fma_f32 v8, v75, v202, v8
	v_fma_f32 v9, v75, v203, v9
	v_lshlrev_b32_e32 v88, 16, v154
	v_and_b32_e32 v89, 0xffff0000, v154
	v_lshlrev_b32_e32 v90, 16, v155
	v_and_b32_e32 v91, 0xffff0000, v155
	v_mul_f32_e32 v88, v67, v88
	v_mul_f32_e32 v89, v67, v89
	v_mul_f32_e32 v90, v67, v90
	v_mul_f32_e32 v91, v67, v91
	v_sub_f32_e32 v6, v6, v88
	v_sub_f32_e32 v7, v7, v89
	v_sub_f32_e32 v8, v8, v90
	v_sub_f32_e32 v9, v9, v91
	v_fma_f32 v214, v197, v6, -v204
	v_fma_f32 v215, v197, v7, -v205
	v_fma_f32 v216, v197, v8, -v206
	v_fma_f32 v217, v197, v9, -v207
	v_mul_f32_e32 v214, v2, v214
	v_mul_f32_e32 v215, v3, v215
	v_mul_f32_e32 v216, v4, v216
	v_mul_f32_e32 v217, v5, v217
	v_cvt_pk_bf16_f32 v218, v214, v215
	v_cvt_pk_bf16_f32 v219, v216, v217
	global_store_dwordx2 v[24:25], v[218:219], off offset:2048 sc1
	s_mov_b64 s[0:1], 0x1000
	v_lshl_add_u64 v[24:25], v[24:25], 0, s[0:1]
	s_waitcnt vmcnt(31)
	v_lshlrev_b32_e32 v200, 16, v172
	v_and_b32_e32 v201, 0xffff0000, v172
	v_lshlrev_b32_e32 v202, 16, v173
	v_and_b32_e32 v203, 0xffff0000, v173
	v_mul_f32_e32 v204, v76, v200
	v_mul_f32_e32 v205, v76, v201
	v_mul_f32_e32 v206, v76, v202
	v_mul_f32_e32 v207, v76, v203
	v_fma_f32 v6, v76, v200, v6
	v_fma_f32 v7, v76, v201, v7
	v_fma_f32 v8, v76, v202, v8
	v_fma_f32 v9, v76, v203, v9
	v_lshlrev_b32_e32 v88, 16, v156
	v_and_b32_e32 v89, 0xffff0000, v156
	v_lshlrev_b32_e32 v90, 16, v157
	v_and_b32_e32 v91, 0xffff0000, v157
	v_mul_f32_e32 v88, v68, v88
	v_mul_f32_e32 v89, v68, v89
	v_mul_f32_e32 v90, v68, v90
	v_mul_f32_e32 v91, v68, v91
	v_sub_f32_e32 v6, v6, v88
	v_sub_f32_e32 v7, v7, v89
	v_sub_f32_e32 v8, v8, v90
	v_sub_f32_e32 v9, v9, v91
	v_fma_f32 v214, v197, v6, -v204
	v_fma_f32 v215, v197, v7, -v205
	v_fma_f32 v216, v197, v8, -v206
	v_fma_f32 v217, v197, v9, -v207
	v_mul_f32_e32 v214, v2, v214
	v_mul_f32_e32 v215, v3, v215
	v_mul_f32_e32 v216, v4, v216
	v_mul_f32_e32 v217, v5, v217
	v_cvt_pk_bf16_f32 v218, v214, v215
	v_cvt_pk_bf16_f32 v219, v216, v217
	global_store_dwordx2 v[24:25], v[218:219], off sc1
	s_waitcnt vmcnt(31)
; __device__ __forceinline__ unsigned pk2(float lo, float hi) { return pg8::cvt_pk_bf16(lo, hi); }
; __device__ __forceinline__ f32x4 ld4bf(const bf16* p) { const v2u w = *(const v2u*)p; return (f32x4){bf_lo(w.x), bf_hi(w.x), bf_lo(w.y), bf_hi(w.y)}; }
; __device__ __forceinline__ void pool_prep(const bf16* X, const float* ss, const float* gain, bf16* PB, LAS unsigned char* lds, int vcu, int G, int tid) {
;     ...
;         const int q = tid & 255, half = tid >> 8, w = 2 << (q >> 6);
;         const f32x4 gn = *(const f32x4*)(gain + 4 * q);
;         const int ra = r0 + 32 * half;
;         const bf16* xp = X + 4 * q;
;         f32x4 S = {0.f, 0.f, 0.f, 0.f};
; #pragma unroll
;         for (int j = 1; j <= 16; ++j) { const int row = ra - j; if (j <= w && row >= bstart) S += ld4bf(xp + (size_t)row * DM) * rsl[row - r0 + 16]; }
;     ...
;         for (int i = 0; i < 32; ++i) { const int row = ra + i, t = row - bstart;
;             const f32x4 xn = ld4bf(xp + (size_t)row * DM) * rsl[row - r0 + 16];
;             f32x4 old = {0.f, 0.f, 0.f, 0.f};
;             if (t >= w) old = ld4bf(xp + (size_t)(row - w) * DM) * rsl[row - w - r0 + 16];
;             S = S + xn - old;
;             const int cnt = (t + 1 < w) ? t + 1 : w;
;             const f32x4 p = (S * (1.0f / (float)cnt) - xn) * gn;
;             v2u o; o.x = pk2(p[0], p[1]); o.y = pk2(p[2], p[3]); *(v2u*)(PB + (size_t)row * DM + 4 * q) = o; }
	v_lshlrev_b32_e32 v200, 16, v174
	v_and_b32_e32 v201, 0xffff0000, v174
	v_lshlrev_b32_e32 v202, 16, v175
	v_and_b32_e32 v203, 0xffff0000, v175
	v_mul_f32_e32 v204, v77, v200
	v_mul_f32_e32 v205, v77, v201
	v_mul_f32_e32 v206, v77, v202
	v_mul_f32_e32 v207, v77, v203
	v_fma_f32 v6, v77, v200, v6
	v_fma_f32 v7, v77, v201, v7
	v_fma_f32 v8, v77, v202, v8
	v_fma_f32 v9, v77, v203, v9
	v_lshlrev_b32_e32 v88, 16, v158
	v_and_b32_e32 v89, 0xffff0000, v158
	v_lshlrev_b32_e32 v90, 16, v159
	v_and_b32_e32 v91, 0xffff0000, v159
	v_mul_f32_e32 v88, v69, v88
	v_mul_f32_e32 v89, v69, v89
	v_mul_f32_e32 v90, v69, v90
	v_mul_f32_e32 v91, v69, v91
	v_sub_f32_e32 v6, v6, v88
	v_sub_f32_e32 v7, v7, v89
	v_sub_f32_e32 v8, v8, v90
	v_sub_f32_e32 v9, v9, v91
	v_fma_f32 v214, v197, v6, -v204
	v_fma_f32 v215, v197, v7, -v205
	v_fma_f32 v216, v197, v8, -v206
	v_fma_f32 v217, v197, v9, -v207
	v_mul_f32_e32 v214, v2, v214
	v_mul_f32_e32 v215, v3, v215
	v_mul_f32_e32 v216, v4, v216
	v_mul_f32_e32 v217, v5, v217
	v_cvt_pk_bf16_f32 v218, v214, v215
	v_cvt_pk_bf16_f32 v219, v216, v217
	global_store_dwordx2 v[24:25], v[218:219], off offset:2048 sc1
	s_mov_b64 s[0:1], 0x1000
	v_lshl_add_u64 v[24:25], v[24:25], 0, s[0:1]
	s_waitcnt vmcnt(31)
	v_lshlrev_b32_e32 v200, 16, v176
	v_and_b32_e32 v201, 0xffff0000, v176
	v_lshlrev_b32_e32 v202, 16, v177
	v_and_b32_e32 v203, 0xffff0000, v177
	v_mul_f32_e32 v204, v78, v200
	v_mul_f32_e32 v205, v78, v201
	v_mul_f32_e32 v206, v78, v202
	v_mul_f32_e32 v207, v78, v203
	v_fma_f32 v6, v78, v200, v6
	v_fma_f32 v7, v78, v201, v7
	v_fma_f32 v8, v78, v202, v8
	v_fma_f32 v9, v78, v203, v9
	v_lshlrev_b32_e32 v88, 16, v160
	v_and_b32_e32 v89, 0xffff0000, v160
	v_lshlrev_b32_e32 v90, 16, v161
	v_and_b32_e32 v91, 0xffff0000, v161
	v_mul_f32_e32 v88, v70, v88
	v_mul_f32_e32 v89, v70, v89
	v_mul_f32_e32 v90, v70, v90
	v_mul_f32_e32 v91, v70, v91
	v_sub_f32_e32 v6, v6, v88
	v_sub_f32_e32 v7, v7, v89
	v_sub_f32_e32 v8, v8, v90
	v_sub_f32_e32 v9, v9, v91
	v_fma_f32 v214, v197, v6, -v204
	v_fma_f32 v215, v197, v7, -v205
	v_fma_f32 v216, v197, v8, -v206
	v_fma_f32 v217, v197, v9, -v207
	v_mul_f32_e32 v214, v2, v214
	v_mul_f32_e32 v215, v3, v215
	v_mul_f32_e32 v216, v4, v216
	v_mul_f32_e32 v217, v5, v217
	v_cvt_pk_bf16_f32 v218, v214, v215
	v_cvt_pk_bf16_f32 v219, v216, v217
	global_store_dwordx2 v[24:25], v[218:219], off sc1
	s_waitcnt vmcnt(31)
	v_lshlrev_b32_e32 v200, 16, v178
	v_and_b32_e32 v201, 0xffff0000, v178
	v_lshlrev_b32_e32 v202, 16, v179
	v_and_b32_e32 v203, 0xffff0000, v179
	v_mul_f32_e32 v204, v79, v200
	v_mul_f32_e32 v205, v79, v201
	v_mul_f32_e32 v206, v79, v202
	v_mul_f32_e32 v207, v79, v203
	v_fma_f32 v6, v79, v200, v6
	v_fma_f32 v7, v79, v201, v7
	v_fma_f32 v8, v79, v202, v8
	v_fma_f32 v9, v79, v203, v9
	v_lshlrev_b32_e32 v88, 16, v162
	v_and_b32_e32 v89, 0xffff0000, v162
	v_lshlrev_b32_e32 v90, 16, v163
	v_and_b32_e32 v91, 0xffff0000, v163
	v_mul_f32_e32 v88, v71, v88
	v_mul_f32_e32 v89, v71, v89
	v_mul_f32_e32 v90, v71, v90
	v_mul_f32_e32 v91, v71, v91
	v_sub_f32_e32 v6, v6, v88
	v_sub_f32_e32 v7, v7, v89
	v_sub_f32_e32 v8, v8, v90
	v_sub_f32_e32 v9, v9, v91
	v_fma_f32 v214, v197, v6, -v204
	v_fma_f32 v215, v197, v7, -v205
	v_fma_f32 v216, v197, v8, -v206
	v_fma_f32 v217, v197, v9, -v207
	v_mul_f32_e32 v214, v2, v214
	v_mul_f32_e32 v215, v3, v215
	v_mul_f32_e32 v216, v4, v216
	v_mul_f32_e32 v217, v5, v217
	v_cvt_pk_bf16_f32 v218, v214, v215
	v_cvt_pk_bf16_f32 v219, v216, v217
	global_store_dwordx2 v[24:25], v[218:219], off offset:2048 sc1
	s_branch .LBB0_308
.Lmy_pool_w4:
	s_mov_b32 s0, 8192
	v_subrev_co_u32_e32 v198, vcc, s0, v22
	s_nop 1
	v_subbrev_co_u32_e32 v199, vcc, 0, v23, vcc
	s_mov_b64 s[0:1], 0x1000
	global_load_dwordx2 v[100:101], v[198:199], off
	global_load_dwordx2 v[102:103], v[198:199], off offset:2048
	v_lshl_add_u64 v[198:199], v[198:199], 0, s[0:1]
	global_load_dwordx2 v[104:105], v[198:199], off
	global_load_dwordx2 v[106:107], v[198:199], off offset:2048
	v_lshl_add_u64 v[198:199], v[198:199], 0, s[0:1]
	global_load_dwordx2 v[108:109], v[198:199], off
	global_load_dwordx2 v[110:111], v[198:199], off offset:2048
	v_lshl_add_u64 v[198:199], v[198:199], 0, s[0:1]
	global_load_dwordx2 v[112:113], v[198:199], off
	global_load_dwordx2 v[114:115], v[198:199], off offset:2048
	v_lshl_add_u64 v[198:199], v[198:199], 0, s[0:1]
	global_load_dwordx2 v[116:117], v[198:199], off
	global_load_dwordx2 v[118:119], v[198:199], off offset:2048
	v_lshl_add_u64 v[198:199], v[198:199], 0, s[0:1]
	global_load_dwordx2 v[120:121], v[198:199], off
	global_load_dwordx2 v[122:123], v[198:199], off offset:2048
	v_lshl_add_u64 v[198:199], v[198:199], 0, s[0:1]
	global_load_dwordx2 v[124:125], v[198:199], off
	global_load_dwordx2 v[126:127], v[198:199], off offset:2048
	v_lshl_add_u64 v[198:199], v[198:199], 0, s[0:1]
	global_load_dwordx2 v[128:129], v[198:199], off
	global_load_dwordx2 v[130:131], v[198:199], off offset:2048
	v_lshl_add_u64 v[198:199], v[198:199], 0, s[0:1]
	global_load_dwordx2 v[132:133], v[198:199], off
	global_load_dwordx2 v[134:135], v[198:199], off offset:2048
	v_lshl_add_u64 v[198:199], v[198:199], 0, s[0:1]
	global_load_dwordx2 v[136:137], v[198:199], off
	global_load_dwordx2 v[138:139], v[198:199], off offset:2048
	v_lshl_add_u64 v[198:199], v[198:199], 0, s[0:1]
	global_load_dwordx2 v[140:141], v[198:199], off
	global_load_dwordx2 v[142:143], v[198:199], off offset:2048
	v_lshl_add_u64 v[198:199], v[198:199], 0, s[0:1]
	global_load_dwordx2 v[144:145], v[198:199], off
	global_load_dwordx2 v[146:147], v[198:199], off offset:2048
	v_lshl_add_u64 v[198:199], v[198:199], 0, s[0:1]
	global_load_dwordx2 v[148:149], v[198:199], off
	global_load_dwordx2 v[150:151], v[198:199], off offset:2048
	v_lshl_add_u64 v[198:199], v[198:199], 0, s[0:1]
	global_load_dwordx2 v[152:153], v[198:199], off
	global_load_dwordx2 v[154:155], v[198:199], off offset:2048
	v_lshl_add_u64 v[198:199], v[198:199], 0, s[0:1]
	global_load_dwordx2 v[156:157], v[198:199], off
	global_load_dwordx2 v[158:159], v[198:199], off offset:2048
	v_lshl_add_u64 v[198:199], v[198:199], 0, s[0:1]
	global_load_dwordx2 v[160:161], v[198:199], off
	global_load_dwordx2 v[162:163], v[198:199], off offset:2048
	v_lshl_add_u64 v[198:199], v[198:199], 0, s[0:1]
	global_load_dwordx2 v[164:165], v[198:199], off
	global_load_dwordx2 v[166:167], v[198:199], off offset:2048
	v_lshl_add_u64 v[198:199], v[198:199], 0, s[0:1]
	global_load_dwordx2 v[168:169], v[198:199], off
	global_load_dwordx2 v[170:171], v[198:199], off offset:2048
	ds_read_b32 v40, v21 offset:48
	ds_read_b32 v41, v21 offset:52
	ds_read_b32 v42, v21 offset:56
	ds_read_b32 v43, v21 offset:60
	ds_read_b32 v44, v21 offset:64
	ds_read_b32 v45, v21 offset:68
	ds_read_b32 v46, v21 offset:72
	ds_read_b32 v47, v21 offset:76
	ds_read_b32 v48, v21 offset:80
	ds_read_b32 v49, v21 offset:84
	ds_read_b32 v50, v21 offset:88
	ds_read_b32 v51, v21 offset:92
	s_waitcnt lgkmcnt(0)
; __device__ __forceinline__ unsigned pk2(float lo, float hi) { return pg8::cvt_pk_bf16(lo, hi); }
; __device__ __forceinline__ f32x4 ld4bf(const bf16* p) { const v2u w = *(const v2u*)p; return (f32x4){bf_lo(w.x), bf_hi(w.x), bf_lo(w.y), bf_hi(w.y)}; }
; __device__ __forceinline__ void pool_prep(const bf16* X, const float* ss, const float* gain, bf16* PB, LAS unsigned char* lds, int vcu, int G, int tid) {
;     ...
;         const int q = tid & 255, half = tid >> 8, w = 2 << (q >> 6);
;         const f32x4 gn = *(const f32x4*)(gain + 4 * q);
;         const int ra = r0 + 32 * half;
;         const bf16* xp = X + 4 * q;
;         f32x4 S = {0.f, 0.f, 0.f, 0.f};
; #pragma unroll
;         for (int j = 1; j <= 16; ++j) { const int row = ra - j; if (j <= w && row >= bstart) S += ld4bf(xp + (size_t)row * DM) * rsl[row - r0 + 16]; }
; #pragma unroll 8
;         for (int i = 0; i < 32; ++i) { const int row = ra + i, t = row - bstart;
;             const f32x4 xn = ld4bf(xp + (size_t)row * DM) * rsl[row - r0 + 16];
;             f32x4 old = {0.f, 0.f, 0.f, 0.f};
;             if (t >= w) old = ld4bf(xp + (size_t)(row - w) * DM) * rsl[row - w - r0 + 16];
;             S = S + xn - old;
;             const int cnt = (t + 1 < w) ? t + 1 : w;
;             const f32x4 p = (S * (1.0f / (float)cnt) - xn) * gn;
;             v2u o; o.x = pk2(p[0], p[1]); o.y = pk2(p[2], p[3]); *(v2u*)(PB + (size_t)row * DM + 4 * q) = o; }
	ds_read_b32 v52, v21 offset:96
	ds_read_b32 v53, v21 offset:100
	ds_read_b32 v54, v21 offset:104
	ds_read_b32 v55, v21 offset:108
	ds_read_b32 v56, v21 offset:112
	ds_read_b32 v57, v21 offset:116
	ds_read_b32 v58, v21 offset:120
	ds_read_b32 v59, v21 offset:124
	ds_read_b32 v60, v21 offset:128
	ds_read_b32 v61, v21 offset:132
	ds_read_b32 v62, v21 offset:136
	ds_read_b32 v63, v21 offset:140
	s_waitcnt lgkmcnt(0)
	ds_read_b32 v64, v21 offset:144
	ds_read_b32 v65, v21 offset:148
	ds_read_b32 v66, v21 offset:152
	ds_read_b32 v67, v21 offset:156
	ds_read_b32 v68, v21 offset:160
	ds_read_b32 v69, v21 offset:164
	ds_read_b32 v70, v21 offset:168
	ds_read_b32 v71, v21 offset:172
	ds_read_b32 v72, v21 offset:176
	ds_read_b32 v73, v21 offset:180
	ds_read_b32 v74, v21 offset:184
	ds_read_b32 v75, v21 offset:188
	s_waitcnt lgkmcnt(0)
	v_div_scale_f32 v26, s[0:1], v196, v196, 1.0
	v_rcp_f32_e32 v27, v26
	s_nop 0
	v_fma_f32 v28, -v26, v27, 1.0
	v_fmac_f32_e32 v27, v28, v27
	v_div_scale_f32 v28, vcc, 1.0, v196, 1.0
	v_mul_f32_e32 v29, v28, v27
	v_fma_f32 v30, -v26, v29, v28
	v_fmac_f32_e32 v29, v30, v27
	v_fma_f32 v26, -v26, v29, v28
	s_nop 1
	v_div_fmas_f32 v197, v26, v27, v29
	v_div_fixup_f32 v197, v197, v196, 1.0
	v_mov_b32_e32 v6, 0
	v_mov_b32_e32 v7, 0
	v_mov_b32_e32 v8, 0
	v_mov_b32_e32 v9, 0
	s_waitcnt lgkmcnt(0)
	s_waitcnt vmcnt(32)
	v_cndmask_b32_e64 v100, v100, 0, s[6:7]
	v_cndmask_b32_e64 v101, v101, 0, s[6:7]
	v_cndmask_b32_e64 v102, v102, 0, s[6:7]
	v_cndmask_b32_e64 v103, v103, 0, s[6:7]
	v_cndmask_b32_e64 v104, v104, 0, s[6:7]
	v_cndmask_b32_e64 v105, v105, 0, s[6:7]
	v_cndmask_b32_e64 v106, v106, 0, s[6:7]
	v_cndmask_b32_e64 v107, v107, 0, s[6:7]
	v_lshlrev_b32_e32 v200, 16, v106
	v_and_b32_e32 v201, 0xffff0000, v106
	v_lshlrev_b32_e32 v202, 16, v107
	v_and_b32_e32 v203, 0xffff0000, v107
	v_fma_f32 v6, v43, v200, v6
	v_fma_f32 v7, v43, v201, v7
	v_fma_f32 v8, v43, v202, v8
	v_fma_f32 v9, v43, v203, v9
	v_lshlrev_b32_e32 v200, 16, v104
	v_and_b32_e32 v201, 0xffff0000, v104
	v_lshlrev_b32_e32 v202, 16, v105
	v_and_b32_e32 v203, 0xffff0000, v105
	v_fma_f32 v6, v42, v200, v6
	v_fma_f32 v7, v42, v201, v7
	v_fma_f32 v8, v42, v202, v8
	v_fma_f32 v9, v42, v203, v9
	v_lshlrev_b32_e32 v200, 16, v102
	v_and_b32_e32 v201, 0xffff0000, v102
	v_lshlrev_b32_e32 v202, 16, v103
	v_and_b32_e32 v203, 0xffff0000, v103
	v_fma_f32 v6, v41, v200, v6
	v_fma_f32 v7, v41, v201, v7
	v_fma_f32 v8, v41, v202, v8
	v_fma_f32 v9, v41, v203, v9
	v_lshlrev_b32_e32 v200, 16, v100
	v_and_b32_e32 v201, 0xffff0000, v100
	v_lshlrev_b32_e32 v202, 16, v101
	v_and_b32_e32 v203, 0xffff0000, v101
	v_fma_f32 v6, v40, v200, v6
	v_fma_f32 v7, v40, v201, v7
	v_fma_f32 v8, v40, v202, v8
	v_fma_f32 v9, v40, v203, v9
	s_waitcnt vmcnt(31)
	v_lshlrev_b32_e32 v200, 16, v108
	v_and_b32_e32 v201, 0xffff0000, v108
	v_lshlrev_b32_e32 v202, 16, v109
	v_and_b32_e32 v203, 0xffff0000, v109
	v_mul_f32_e32 v204, v44, v200
	v_mul_f32_e32 v205, v44, v201
	v_mul_f32_e32 v206, v44, v202
	v_mul_f32_e32 v207, v44, v203
	v_fma_f32 v6, v44, v200, v6
	v_fma_f32 v7, v44, v201, v7
	v_fma_f32 v8, v44, v202, v8
	v_fma_f32 v9, v44, v203, v9
	v_lshlrev_b32_e32 v88, 16, v100
	v_and_b32_e32 v89, 0xffff0000, v100
	v_lshlrev_b32_e32 v90, 16, v101
	v_and_b32_e32 v91, 0xffff0000, v101
	v_mul_f32_e32 v88, v40, v88
	v_mul_f32_e32 v89, v40, v89
	v_mul_f32_e32 v90, v40, v90
	v_mul_f32_e32 v91, v40, v91
	v_sub_f32_e32 v6, v6, v88
	v_sub_f32_e32 v7, v7, v89
	v_sub_f32_e32 v8, v8, v90
	v_sub_f32_e32 v9, v9, v91
	v_add_u32_e32 v92, 1, v20
	v_min_i32_e32 v92, v92, v32
	v_cvt_f32_i32_e32 v92, v92
	v_div_scale_f32 v26, s[0:1], v92, v92, 1.0
	v_rcp_f32_e32 v27, v26
	s_nop 0
	v_fma_f32 v28, -v26, v27, 1.0
	v_fmac_f32_e32 v27, v28, v27
	v_div_scale_f32 v28, vcc, 1.0, v92, 1.0
	v_mul_f32_e32 v29, v28, v27
	v_fma_f32 v30, -v26, v29, v28
	v_fmac_f32_e32 v29, v30, v27
	v_fma_f32 v26, -v26, v29, v28
	s_nop 1
	v_div_fmas_f32 v93, v26, v27, v29
	v_div_fixup_f32 v93, v93, v92, 1.0
	v_fma_f32 v214, v93, v6, -v204
	v_fma_f32 v215, v93, v7, -v205
	v_fma_f32 v216, v93, v8, -v206
	v_fma_f32 v217, v93, v9, -v207
	v_mul_f32_e32 v214, v2, v214
	v_mul_f32_e32 v215, v3, v215
	v_mul_f32_e32 v216, v4, v216
	v_mul_f32_e32 v217, v5, v217
	v_cvt_pk_bf16_f32 v218, v214, v215
	v_cvt_pk_bf16_f32 v219, v216, v217
	global_store_dwordx2 v[24:25], v[218:219], off sc1
	s_waitcnt vmcnt(31)
	v_lshlrev_b32_e32 v200, 16, v110
	v_and_b32_e32 v201, 0xffff0000, v110
	v_lshlrev_b32_e32 v202, 16, v111
	v_and_b32_e32 v203, 0xffff0000, v111
	v_mul_f32_e32 v204, v45, v200
	v_mul_f32_e32 v205, v45, v201
	v_mul_f32_e32 v206, v45, v202
	v_mul_f32_e32 v207, v45, v203
	v_fma_f32 v6, v45, v200, v6
	v_fma_f32 v7, v45, v201, v7
	v_fma_f32 v8, v45, v202, v8
	v_fma_f32 v9, v45, v203, v9
	v_lshlrev_b32_e32 v88, 16, v102
	v_and_b32_e32 v89, 0xffff0000, v102
	v_lshlrev_b32_e32 v90, 16, v103
	v_and_b32_e32 v91, 0xffff0000, v103
	v_mul_f32_e32 v88, v41, v88
	v_mul_f32_e32 v89, v41, v89
	v_mul_f32_e32 v90, v41, v90
	v_mul_f32_e32 v91, v41, v91
	v_sub_f32_e32 v6, v6, v88
	v_sub_f32_e32 v7, v7, v89
	v_sub_f32_e32 v8, v8, v90
	v_sub_f32_e32 v9, v9, v91
	v_add_u32_e32 v92, 2, v20
	v_min_i32_e32 v92, v92, v32
	v_cvt_f32_i32_e32 v92, v92
	v_div_scale_f32 v26, s[0:1], v92, v92, 1.0
	v_rcp_f32_e32 v27, v26
	s_nop 0
	v_fma_f32 v28, -v26, v27, 1.0
	v_fmac_f32_e32 v27, v28, v27
	v_div_scale_f32 v28, vcc, 1.0, v92, 1.0
	v_mul_f32_e32 v29, v28, v27
	v_fma_f32 v30, -v26, v29, v28
	v_fmac_f32_e32 v29, v30, v27
	v_fma_f32 v26, -v26, v29, v28
	s_nop 1
	v_div_fmas_f32 v93, v26, v27, v29
	v_div_fixup_f32 v93, v93, v92, 1.0
	v_fma_f32 v214, v93, v6, -v204
	v_fma_f32 v215, v93, v7, -v205
	v_fma_f32 v216, v93, v8, -v206
	v_fma_f32 v217, v93, v9, -v207
	v_mul_f32_e32 v214, v2, v214
	v_mul_f32_e32 v215, v3, v215
	v_mul_f32_e32 v216, v4, v216
	v_mul_f32_e32 v217, v5, v217
	v_cvt_pk_bf16_f32 v218, v214, v215
	v_cvt_pk_bf16_f32 v219, v216, v217
	global_store_dwordx2 v[24:25], v[218:219], off offset:2048 sc1
	s_mov_b64 s[0:1], 0x1000
	v_lshl_add_u64 v[24:25], v[24:25], 0, s[0:1]
	s_waitcnt vmcnt(31)
; __device__ __forceinline__ unsigned pk2(float lo, float hi) { return pg8::cvt_pk_bf16(lo, hi); }
; __device__ __forceinline__ f32x4 ld4bf(const bf16* p) { const v2u w = *(const v2u*)p; return (f32x4){bf_lo(w.x), bf_hi(w.x), bf_lo(w.y), bf_hi(w.y)}; }
; __device__ __forceinline__ void pool_prep(const bf16* X, const float* ss, const float* gain, bf16* PB, LAS unsigned char* lds, int vcu, int G, int tid) {
;     ...
;         for (int i = 0; i < 32; ++i) { const int row = ra + i, t = row - bstart;
;             const f32x4 xn = ld4bf(xp + (size_t)row * DM) * rsl[row - r0 + 16];
;             f32x4 old = {0.f, 0.f, 0.f, 0.f};
;             if (t >= w) old = ld4bf(xp + (size_t)(row - w) * DM) * rsl[row - w - r0 + 16];
;             S = S + xn - old;
;             const int cnt = (t + 1 < w) ? t + 1 : w;
;             const f32x4 p = (S * (1.0f / (float)cnt) - xn) * gn;
;             v2u o; o.x = pk2(p[0], p[1]); o.y = pk2(p[2], p[3]); *(v2u*)(PB + (size_t)row * DM + 4 * q) = o; }
	v_lshlrev_b32_e32 v200, 16, v112
	v_and_b32_e32 v201, 0xffff0000, v112
	v_lshlrev_b32_e32 v202, 16, v113
	v_and_b32_e32 v203, 0xffff0000, v113
	v_mul_f32_e32 v204, v46, v200
	v_mul_f32_e32 v205, v46, v201
	v_mul_f32_e32 v206, v46, v202
	v_mul_f32_e32 v207, v46, v203
	v_fma_f32 v6, v46, v200, v6
	v_fma_f32 v7, v46, v201, v7
	v_fma_f32 v8, v46, v202, v8
	v_fma_f32 v9, v46, v203, v9
	v_lshlrev_b32_e32 v88, 16, v104
	v_and_b32_e32 v89, 0xffff0000, v104
	v_lshlrev_b32_e32 v90, 16, v105
	v_and_b32_e32 v91, 0xffff0000, v105
	v_mul_f32_e32 v88, v42, v88
	v_mul_f32_e32 v89, v42, v89
	v_mul_f32_e32 v90, v42, v90
	v_mul_f32_e32 v91, v42, v91
	v_sub_f32_e32 v6, v6, v88
	v_sub_f32_e32 v7, v7, v89
	v_sub_f32_e32 v8, v8, v90
	v_sub_f32_e32 v9, v9, v91
	v_add_u32_e32 v92, 3, v20
	v_min_i32_e32 v92, v92, v32
	v_cvt_f32_i32_e32 v92, v92
	v_div_scale_f32 v26, s[0:1], v92, v92, 1.0
	v_rcp_f32_e32 v27, v26
	s_nop 0
	v_fma_f32 v28, -v26, v27, 1.0
	v_fmac_f32_e32 v27, v28, v27
	v_div_scale_f32 v28, vcc, 1.0, v92, 1.0
	v_mul_f32_e32 v29, v28, v27
	v_fma_f32 v30, -v26, v29, v28
	v_fmac_f32_e32 v29, v30, v27
	v_fma_f32 v26, -v26, v29, v28
	s_nop 1
	v_div_fmas_f32 v93, v26, v27, v29
	v_div_fixup_f32 v93, v93, v92, 1.0
	v_fma_f32 v214, v93, v6, -v204
	v_fma_f32 v215, v93, v7, -v205
	v_fma_f32 v216, v93, v8, -v206
	v_fma_f32 v217, v93, v9, -v207
	v_mul_f32_e32 v214, v2, v214
	v_mul_f32_e32 v215, v3, v215
	v_mul_f32_e32 v216, v4, v216
	v_mul_f32_e32 v217, v5, v217
	v_cvt_pk_bf16_f32 v218, v214, v215
	v_cvt_pk_bf16_f32 v219, v216, v217
	global_store_dwordx2 v[24:25], v[218:219], off sc1
	s_waitcnt vmcnt(31)
	v_lshlrev_b32_e32 v200, 16, v114
	v_and_b32_e32 v201, 0xffff0000, v114
	v_lshlrev_b32_e32 v202, 16, v115
	v_and_b32_e32 v203, 0xffff0000, v115
	v_mul_f32_e32 v204, v47, v200
	v_mul_f32_e32 v205, v47, v201
	v_mul_f32_e32 v206, v47, v202
	v_mul_f32_e32 v207, v47, v203
	v_fma_f32 v6, v47, v200, v6
	v_fma_f32 v7, v47, v201, v7
	v_fma_f32 v8, v47, v202, v8
	v_fma_f32 v9, v47, v203, v9
	v_lshlrev_b32_e32 v88, 16, v106
	v_and_b32_e32 v89, 0xffff0000, v106
	v_lshlrev_b32_e32 v90, 16, v107
	v_and_b32_e32 v91, 0xffff0000, v107
	v_mul_f32_e32 v88, v43, v88
	v_mul_f32_e32 v89, v43, v89
	v_mul_f32_e32 v90, v43, v90
	v_mul_f32_e32 v91, v43, v91
	v_sub_f32_e32 v6, v6, v88
	v_sub_f32_e32 v7, v7, v89
	v_sub_f32_e32 v8, v8, v90
	v_sub_f32_e32 v9, v9, v91
	v_fma_f32 v214, v197, v6, -v204
	v_fma_f32 v215, v197, v7, -v205
	v_fma_f32 v216, v197, v8, -v206
	v_fma_f32 v217, v197, v9, -v207
	v_mul_f32_e32 v214, v2, v214
	v_mul_f32_e32 v215, v3, v215
	v_mul_f32_e32 v216, v4, v216
	v_mul_f32_e32 v217, v5, v217
	v_cvt_pk_bf16_f32 v218, v214, v215
	v_cvt_pk_bf16_f32 v219, v216, v217
	global_store_dwordx2 v[24:25], v[218:219], off offset:2048 sc1
	s_mov_b64 s[0:1], 0x1000
	v_lshl_add_u64 v[24:25], v[24:25], 0, s[0:1]
	s_waitcnt vmcnt(31)
	v_lshlrev_b32_e32 v200, 16, v116
	v_and_b32_e32 v201, 0xffff0000, v116
	v_lshlrev_b32_e32 v202, 16, v117
	v_and_b32_e32 v203, 0xffff0000, v117
	v_mul_f32_e32 v204, v48, v200
	v_mul_f32_e32 v205, v48, v201
	v_mul_f32_e32 v206, v48, v202
	v_mul_f32_e32 v207, v48, v203
	v_fma_f32 v6, v48, v200, v6
	v_fma_f32 v7, v48, v201, v7
	v_fma_f32 v8, v48, v202, v8
	v_fma_f32 v9, v48, v203, v9
	v_lshlrev_b32_e32 v88, 16, v108
	v_and_b32_e32 v89, 0xffff0000, v108
	v_lshlrev_b32_e32 v90, 16, v109
	v_and_b32_e32 v91, 0xffff0000, v109
	v_mul_f32_e32 v88, v44, v88
	v_mul_f32_e32 v89, v44, v89
	v_mul_f32_e32 v90, v44, v90
	v_mul_f32_e32 v91, v44, v91
	v_sub_f32_e32 v6, v6, v88
	v_sub_f32_e32 v7, v7, v89
	v_sub_f32_e32 v8, v8, v90
	v_sub_f32_e32 v9, v9, v91
	v_fma_f32 v214, v197, v6, -v204
	v_fma_f32 v215, v197, v7, -v205
	v_fma_f32 v216, v197, v8, -v206
	v_fma_f32 v217, v197, v9, -v207
	v_mul_f32_e32 v214, v2, v214
	v_mul_f32_e32 v215, v3, v215
	v_mul_f32_e32 v216, v4, v216
	v_mul_f32_e32 v217, v5, v217
	v_cvt_pk_bf16_f32 v218, v214, v215
	v_cvt_pk_bf16_f32 v219, v216, v217
	global_store_dwordx2 v[24:25], v[218:219], off sc1
	s_waitcnt vmcnt(31)
	v_lshlrev_b32_e32 v200, 16, v118
	v_and_b32_e32 v201, 0xffff0000, v118
	v_lshlrev_b32_e32 v202, 16, v119
	v_and_b32_e32 v203, 0xffff0000, v119
	v_mul_f32_e32 v204, v49, v200
	v_mul_f32_e32 v205, v49, v201
	v_mul_f32_e32 v206, v49, v202
	v_mul_f32_e32 v207, v49, v203
	v_fma_f32 v6, v49, v200, v6
	v_fma_f32 v7, v49, v201, v7
	v_fma_f32 v8, v49, v202, v8
	v_fma_f32 v9, v49, v203, v9
	v_lshlrev_b32_e32 v88, 16, v110
	v_and_b32_e32 v89, 0xffff0000, v110
	v_lshlrev_b32_e32 v90, 16, v111
	v_and_b32_e32 v91, 0xffff0000, v111
	v_mul_f32_e32 v88, v45, v88
	v_mul_f32_e32 v89, v45, v89
	v_mul_f32_e32 v90, v45, v90
	v_mul_f32_e32 v91, v45, v91
	v_sub_f32_e32 v6, v6, v88
	v_sub_f32_e32 v7, v7, v89
	v_sub_f32_e32 v8, v8, v90
	v_sub_f32_e32 v9, v9, v91
	v_fma_f32 v214, v197, v6, -v204
	v_fma_f32 v215, v197, v7, -v205
	v_fma_f32 v216, v197, v8, -v206
	v_fma_f32 v217, v197, v9, -v207
	v_mul_f32_e32 v214, v2, v214
	v_mul_f32_e32 v215, v3, v215
	v_mul_f32_e32 v216, v4, v216
	v_mul_f32_e32 v217, v5, v217
	v_cvt_pk_bf16_f32 v218, v214, v215
	v_cvt_pk_bf16_f32 v219, v216, v217
	global_store_dwordx2 v[24:25], v[218:219], off offset:2048 sc1
	s_mov_b64 s[0:1], 0x1000
	v_lshl_add_u64 v[24:25], v[24:25], 0, s[0:1]
	s_waitcnt vmcnt(31)
; __device__ __forceinline__ unsigned pk2(float lo, float hi) { return pg8::cvt_pk_bf16(lo, hi); }
; __device__ __forceinline__ f32x4 ld4bf(const bf16* p) { const v2u w = *(const v2u*)p; return (f32x4){bf_lo(w.x), bf_hi(w.x), bf_lo(w.y), bf_hi(w.y)}; }
; __device__ __forceinline__ void pool_prep(const bf16* X, const float* ss, const float* gain, bf16* PB, LAS unsigned char* lds, int vcu, int G, int tid) {
;     ...
;         for (int i = 0; i < 32; ++i) { const int row = ra + i, t = row - bstart;
;             const f32x4 xn = ld4bf(xp + (size_t)row * DM) * rsl[row - r0 + 16];
;             f32x4 old = {0.f, 0.f, 0.f, 0.f};
;             if (t >= w) old = ld4bf(xp + (size_t)(row - w) * DM) * rsl[row - w - r0 + 16];
;             S = S + xn - old;
;             const int cnt = (t + 1 < w) ? t + 1 : w;
;             const f32x4 p = (S * (1.0f / (float)cnt) - xn) * gn;
;             v2u o; o.x = pk2(p[0], p[1]); o.y = pk2(p[2], p[3]); *(v2u*)(PB + (size_t)row * DM + 4 * q) = o; }
	v_lshlrev_b32_e32 v200, 16, v120
	v_and_b32_e32 v201, 0xffff0000, v120
	v_lshlrev_b32_e32 v202, 16, v121
	v_and_b32_e32 v203, 0xffff0000, v121
	v_mul_f32_e32 v204, v50, v200
	v_mul_f32_e32 v205, v50, v201
	v_mul_f32_e32 v206, v50, v202
	v_mul_f32_e32 v207, v50, v203
	v_fma_f32 v6, v50, v200, v6
	v_fma_f32 v7, v50, v201, v7
	v_fma_f32 v8, v50, v202, v8
	v_fma_f32 v9, v50, v203, v9
	v_lshlrev_b32_e32 v88, 16, v112
	v_and_b32_e32 v89, 0xffff0000, v112
	v_lshlrev_b32_e32 v90, 16, v113
	v_and_b32_e32 v91, 0xffff0000, v113
	v_mul_f32_e32 v88, v46, v88
	v_mul_f32_e32 v89, v46, v89
	v_mul_f32_e32 v90, v46, v90
	v_mul_f32_e32 v91, v46, v91
	v_sub_f32_e32 v6, v6, v88
	v_sub_f32_e32 v7, v7, v89
	v_sub_f32_e32 v8, v8, v90
	v_sub_f32_e32 v9, v9, v91
	v_fma_f32 v214, v197, v6, -v204
	v_fma_f32 v215, v197, v7, -v205
	v_fma_f32 v216, v197, v8, -v206
	v_fma_f32 v217, v197, v9, -v207
	v_mul_f32_e32 v214, v2, v214
	v_mul_f32_e32 v215, v3, v215
	v_mul_f32_e32 v216, v4, v216
	v_mul_f32_e32 v217, v5, v217
	v_cvt_pk_bf16_f32 v218, v214, v215
	v_cvt_pk_bf16_f32 v219, v216, v217
	global_store_dwordx2 v[24:25], v[218:219], off sc1
	s_waitcnt vmcnt(31)
	v_lshlrev_b32_e32 v200, 16, v122
	v_and_b32_e32 v201, 0xffff0000, v122
	v_lshlrev_b32_e32 v202, 16, v123
	v_and_b32_e32 v203, 0xffff0000, v123
	v_mul_f32_e32 v204, v51, v200
	v_mul_f32_e32 v205, v51, v201
	v_mul_f32_e32 v206, v51, v202
	v_mul_f32_e32 v207, v51, v203
	v_fma_f32 v6, v51, v200, v6
	v_fma_f32 v7, v51, v201, v7
	v_fma_f32 v8, v51, v202, v8
	v_fma_f32 v9, v51, v203, v9
	v_lshlrev_b32_e32 v88, 16, v114
	v_and_b32_e32 v89, 0xffff0000, v114
	v_lshlrev_b32_e32 v90, 16, v115
	v_and_b32_e32 v91, 0xffff0000, v115
	v_mul_f32_e32 v88, v47, v88
	v_mul_f32_e32 v89, v47, v89
	v_mul_f32_e32 v90, v47, v90
	v_mul_f32_e32 v91, v47, v91
	v_sub_f32_e32 v6, v6, v88
	v_sub_f32_e32 v7, v7, v89
	v_sub_f32_e32 v8, v8, v90
	v_sub_f32_e32 v9, v9, v91
	v_fma_f32 v214, v197, v6, -v204
	v_fma_f32 v215, v197, v7, -v205
	v_fma_f32 v216, v197, v8, -v206
	v_fma_f32 v217, v197, v9, -v207
	v_mul_f32_e32 v214, v2, v214
	v_mul_f32_e32 v215, v3, v215
	v_mul_f32_e32 v216, v4, v216
	v_mul_f32_e32 v217, v5, v217
	v_cvt_pk_bf16_f32 v218, v214, v215
	v_cvt_pk_bf16_f32 v219, v216, v217
	global_store_dwordx2 v[24:25], v[218:219], off offset:2048 sc1
	s_mov_b64 s[0:1], 0x1000
	v_lshl_add_u64 v[24:25], v[24:25], 0, s[0:1]
	s_waitcnt vmcnt(31)
	v_lshlrev_b32_e32 v200, 16, v124
	v_and_b32_e32 v201, 0xffff0000, v124
	v_lshlrev_b32_e32 v202, 16, v125
	v_and_b32_e32 v203, 0xffff0000, v125
	v_mul_f32_e32 v204, v52, v200
	v_mul_f32_e32 v205, v52, v201
	v_mul_f32_e32 v206, v52, v202
	v_mul_f32_e32 v207, v52, v203
	v_fma_f32 v6, v52, v200, v6
	v_fma_f32 v7, v52, v201, v7
	v_fma_f32 v8, v52, v202, v8
	v_fma_f32 v9, v52, v203, v9
	v_lshlrev_b32_e32 v88, 16, v116
	v_and_b32_e32 v89, 0xffff0000, v116
	v_lshlrev_b32_e32 v90, 16, v117
	v_and_b32_e32 v91, 0xffff0000, v117
	v_mul_f32_e32 v88, v48, v88
	v_mul_f32_e32 v89, v48, v89
	v_mul_f32_e32 v90, v48, v90
	v_mul_f32_e32 v91, v48, v91
	v_sub_f32_e32 v6, v6, v88
	v_sub_f32_e32 v7, v7, v89
	v_sub_f32_e32 v8, v8, v90
	v_sub_f32_e32 v9, v9, v91
	v_fma_f32 v214, v197, v6, -v204
	v_fma_f32 v215, v197, v7, -v205
	v_fma_f32 v216, v197, v8, -v206
	v_fma_f32 v217, v197, v9, -v207
	v_mul_f32_e32 v214, v2, v214
	v_mul_f32_e32 v215, v3, v215
	v_mul_f32_e32 v216, v4, v216
	v_mul_f32_e32 v217, v5, v217
	v_cvt_pk_bf16_f32 v218, v214, v215
	v_cvt_pk_bf16_f32 v219, v216, v217
	global_store_dwordx2 v[24:25], v[218:219], off sc1
	s_waitcnt vmcnt(31)
	v_lshlrev_b32_e32 v200, 16, v126
	v_and_b32_e32 v201, 0xffff0000, v126
	v_lshlrev_b32_e32 v202, 16, v127
	v_and_b32_e32 v203, 0xffff0000, v127
	v_mul_f32_e32 v204, v53, v200
	v_mul_f32_e32 v205, v53, v201
	v_mul_f32_e32 v206, v53, v202
	v_mul_f32_e32 v207, v53, v203
	v_fma_f32 v6, v53, v200, v6
	v_fma_f32 v7, v53, v201, v7
	v_fma_f32 v8, v53, v202, v8
	v_fma_f32 v9, v53, v203, v9
	v_lshlrev_b32_e32 v88, 16, v118
	v_and_b32_e32 v89, 0xffff0000, v118
	v_lshlrev_b32_e32 v90, 16, v119
	v_and_b32_e32 v91, 0xffff0000, v119
	v_mul_f32_e32 v88, v49, v88
	v_mul_f32_e32 v89, v49, v89
	v_mul_f32_e32 v90, v49, v90
	v_mul_f32_e32 v91, v49, v91
	v_sub_f32_e32 v6, v6, v88
	v_sub_f32_e32 v7, v7, v89
	v_sub_f32_e32 v8, v8, v90
	v_sub_f32_e32 v9, v9, v91
	v_fma_f32 v214, v197, v6, -v204
	v_fma_f32 v215, v197, v7, -v205
	v_fma_f32 v216, v197, v8, -v206
	v_fma_f32 v217, v197, v9, -v207
	v_mul_f32_e32 v214, v2, v214
	v_mul_f32_e32 v215, v3, v215
	v_mul_f32_e32 v216, v4, v216
	v_mul_f32_e32 v217, v5, v217
	v_cvt_pk_bf16_f32 v218, v214, v215
	v_cvt_pk_bf16_f32 v219, v216, v217
	global_store_dwordx2 v[24:25], v[218:219], off offset:2048 sc1
	s_mov_b64 s[0:1], 0x1000
	v_lshl_add_u64 v[24:25], v[24:25], 0, s[0:1]
	s_waitcnt vmcnt(31)
	v_lshlrev_b32_e32 v200, 16, v128
	v_and_b32_e32 v201, 0xffff0000, v128
	v_lshlrev_b32_e32 v202, 16, v129
	v_and_b32_e32 v203, 0xffff0000, v129
	v_mul_f32_e32 v204, v54, v200
	v_mul_f32_e32 v205, v54, v201
	v_mul_f32_e32 v206, v54, v202
	v_mul_f32_e32 v207, v54, v203
	v_fma_f32 v6, v54, v200, v6
	v_fma_f32 v7, v54, v201, v7
	v_fma_f32 v8, v54, v202, v8
	v_fma_f32 v9, v54, v203, v9
	v_lshlrev_b32_e32 v88, 16, v120
	v_and_b32_e32 v89, 0xffff0000, v120
	v_lshlrev_b32_e32 v90, 16, v121
	v_and_b32_e32 v91, 0xffff0000, v121
	v_mul_f32_e32 v88, v50, v88
	v_mul_f32_e32 v89, v50, v89
	v_mul_f32_e32 v90, v50, v90
	v_mul_f32_e32 v91, v50, v91
	v_sub_f32_e32 v6, v6, v88
	v_sub_f32_e32 v7, v7, v89
	v_sub_f32_e32 v8, v8, v90
	v_sub_f32_e32 v9, v9, v91
	v_fma_f32 v214, v197, v6, -v204
	v_fma_f32 v215, v197, v7, -v205
	v_fma_f32 v216, v197, v8, -v206
	v_fma_f32 v217, v197, v9, -v207
	v_mul_f32_e32 v214, v2, v214
	v_mul_f32_e32 v215, v3, v215
	v_mul_f32_e32 v216, v4, v216
	v_mul_f32_e32 v217, v5, v217
	v_cvt_pk_bf16_f32 v218, v214, v215
	v_cvt_pk_bf16_f32 v219, v216, v217
	global_store_dwordx2 v[24:25], v[218:219], off sc1
	s_waitcnt vmcnt(31)
; __device__ __forceinline__ unsigned pk2(float lo, float hi) { return pg8::cvt_pk_bf16(lo, hi); }
; __device__ __forceinline__ f32x4 ld4bf(const bf16* p) { const v2u w = *(const v2u*)p; return (f32x4){bf_lo(w.x), bf_hi(w.x), bf_lo(w.y), bf_hi(w.y)}; }
; __device__ __forceinline__ void pool_prep(const bf16* X, const float* ss, const float* gain, bf16* PB, LAS unsigned char* lds, int vcu, int G, int tid) {
;     ...
;         for (int i = 0; i < 32; ++i) { const int row = ra + i, t = row - bstart;
;             const f32x4 xn = ld4bf(xp + (size_t)row * DM) * rsl[row - r0 + 16];
;             f32x4 old = {0.f, 0.f, 0.f, 0.f};
;             if (t >= w) old = ld4bf(xp + (size_t)(row - w) * DM) * rsl[row - w - r0 + 16];
;             S = S + xn - old;
;             const int cnt = (t + 1 < w) ? t + 1 : w;
;             const f32x4 p = (S * (1.0f / (float)cnt) - xn) * gn;
;             v2u o; o.x = pk2(p[0], p[1]); o.y = pk2(p[2], p[3]); *(v2u*)(PB + (size_t)row * DM + 4 * q) = o; }
	v_lshlrev_b32_e32 v200, 16, v130
	v_and_b32_e32 v201, 0xffff0000, v130
	v_lshlrev_b32_e32 v202, 16, v131
	v_and_b32_e32 v203, 0xffff0000, v131
	v_mul_f32_e32 v204, v55, v200
	v_mul_f32_e32 v205, v55, v201
	v_mul_f32_e32 v206, v55, v202
	v_mul_f32_e32 v207, v55, v203
	v_fma_f32 v6, v55, v200, v6
	v_fma_f32 v7, v55, v201, v7
	v_fma_f32 v8, v55, v202, v8
	v_fma_f32 v9, v55, v203, v9
	v_lshlrev_b32_e32 v88, 16, v122
	v_and_b32_e32 v89, 0xffff0000, v122
	v_lshlrev_b32_e32 v90, 16, v123
	v_and_b32_e32 v91, 0xffff0000, v123
	v_mul_f32_e32 v88, v51, v88
	v_mul_f32_e32 v89, v51, v89
	v_mul_f32_e32 v90, v51, v90
	v_mul_f32_e32 v91, v51, v91
	v_sub_f32_e32 v6, v6, v88
	v_sub_f32_e32 v7, v7, v89
	v_sub_f32_e32 v8, v8, v90
	v_sub_f32_e32 v9, v9, v91
	v_fma_f32 v214, v197, v6, -v204
	v_fma_f32 v215, v197, v7, -v205
	v_fma_f32 v216, v197, v8, -v206
	v_fma_f32 v217, v197, v9, -v207
	v_mul_f32_e32 v214, v2, v214
	v_mul_f32_e32 v215, v3, v215
	v_mul_f32_e32 v216, v4, v216
	v_mul_f32_e32 v217, v5, v217
	v_cvt_pk_bf16_f32 v218, v214, v215
	v_cvt_pk_bf16_f32 v219, v216, v217
	global_store_dwordx2 v[24:25], v[218:219], off offset:2048 sc1
	s_mov_b64 s[0:1], 0x1000
	v_lshl_add_u64 v[24:25], v[24:25], 0, s[0:1]
	s_waitcnt vmcnt(31)
	v_lshlrev_b32_e32 v200, 16, v132
	v_and_b32_e32 v201, 0xffff0000, v132
	v_lshlrev_b32_e32 v202, 16, v133
	v_and_b32_e32 v203, 0xffff0000, v133
	v_mul_f32_e32 v204, v56, v200
	v_mul_f32_e32 v205, v56, v201
	v_mul_f32_e32 v206, v56, v202
	v_mul_f32_e32 v207, v56, v203
	v_fma_f32 v6, v56, v200, v6
	v_fma_f32 v7, v56, v201, v7
	v_fma_f32 v8, v56, v202, v8
	v_fma_f32 v9, v56, v203, v9
	v_lshlrev_b32_e32 v88, 16, v124
	v_and_b32_e32 v89, 0xffff0000, v124
	v_lshlrev_b32_e32 v90, 16, v125
	v_and_b32_e32 v91, 0xffff0000, v125
	v_mul_f32_e32 v88, v52, v88
	v_mul_f32_e32 v89, v52, v89
	v_mul_f32_e32 v90, v52, v90
	v_mul_f32_e32 v91, v52, v91
	v_sub_f32_e32 v6, v6, v88
	v_sub_f32_e32 v7, v7, v89
	v_sub_f32_e32 v8, v8, v90
	v_sub_f32_e32 v9, v9, v91
	v_fma_f32 v214, v197, v6, -v204
	v_fma_f32 v215, v197, v7, -v205
	v_fma_f32 v216, v197, v8, -v206
	v_fma_f32 v217, v197, v9, -v207
	v_mul_f32_e32 v214, v2, v214
	v_mul_f32_e32 v215, v3, v215
	v_mul_f32_e32 v216, v4, v216
	v_mul_f32_e32 v217, v5, v217
	v_cvt_pk_bf16_f32 v218, v214, v215
	v_cvt_pk_bf16_f32 v219, v216, v217
	global_store_dwordx2 v[24:25], v[218:219], off sc1
	s_waitcnt vmcnt(31)
	v_lshlrev_b32_e32 v200, 16, v134
	v_and_b32_e32 v201, 0xffff0000, v134
	v_lshlrev_b32_e32 v202, 16, v135
	v_and_b32_e32 v203, 0xffff0000, v135
	v_mul_f32_e32 v204, v57, v200
	v_mul_f32_e32 v205, v57, v201
	v_mul_f32_e32 v206, v57, v202
	v_mul_f32_e32 v207, v57, v203
	v_fma_f32 v6, v57, v200, v6
	v_fma_f32 v7, v57, v201, v7
	v_fma_f32 v8, v57, v202, v8
	v_fma_f32 v9, v57, v203, v9
	v_lshlrev_b32_e32 v88, 16, v126
	v_and_b32_e32 v89, 0xffff0000, v126
	v_lshlrev_b32_e32 v90, 16, v127
	v_and_b32_e32 v91, 0xffff0000, v127
	v_mul_f32_e32 v88, v53, v88
	v_mul_f32_e32 v89, v53, v89
	v_mul_f32_e32 v90, v53, v90
	v_mul_f32_e32 v91, v53, v91
	v_sub_f32_e32 v6, v6, v88
	v_sub_f32_e32 v7, v7, v89
	v_sub_f32_e32 v8, v8, v90
	v_sub_f32_e32 v9, v9, v91
	v_fma_f32 v214, v197, v6, -v204
	v_fma_f32 v215, v197, v7, -v205
	v_fma_f32 v216, v197, v8, -v206
	v_fma_f32 v217, v197, v9, -v207
	v_mul_f32_e32 v214, v2, v214
	v_mul_f32_e32 v215, v3, v215
	v_mul_f32_e32 v216, v4, v216
	v_mul_f32_e32 v217, v5, v217
	v_cvt_pk_bf16_f32 v218, v214, v215
	v_cvt_pk_bf16_f32 v219, v216, v217
	global_store_dwordx2 v[24:25], v[218:219], off offset:2048 sc1
	s_mov_b64 s[0:1], 0x1000
	v_lshl_add_u64 v[24:25], v[24:25], 0, s[0:1]
	s_waitcnt vmcnt(31)
	v_lshlrev_b32_e32 v200, 16, v136
	v_and_b32_e32 v201, 0xffff0000, v136
	v_lshlrev_b32_e32 v202, 16, v137
	v_and_b32_e32 v203, 0xffff0000, v137
	v_mul_f32_e32 v204, v58, v200
	v_mul_f32_e32 v205, v58, v201
	v_mul_f32_e32 v206, v58, v202
	v_mul_f32_e32 v207, v58, v203
	v_fma_f32 v6, v58, v200, v6
	v_fma_f32 v7, v58, v201, v7
	v_fma_f32 v8, v58, v202, v8
	v_fma_f32 v9, v58, v203, v9
	v_lshlrev_b32_e32 v88, 16, v128
	v_and_b32_e32 v89, 0xffff0000, v128
	v_lshlrev_b32_e32 v90, 16, v129
	v_and_b32_e32 v91, 0xffff0000, v129
	v_mul_f32_e32 v88, v54, v88
	v_mul_f32_e32 v89, v54, v89
	v_mul_f32_e32 v90, v54, v90
	v_mul_f32_e32 v91, v54, v91
	v_sub_f32_e32 v6, v6, v88
	v_sub_f32_e32 v7, v7, v89
	v_sub_f32_e32 v8, v8, v90
	v_sub_f32_e32 v9, v9, v91
	v_fma_f32 v214, v197, v6, -v204
	v_fma_f32 v215, v197, v7, -v205
	v_fma_f32 v216, v197, v8, -v206
	v_fma_f32 v217, v197, v9, -v207
	v_mul_f32_e32 v214, v2, v214
	v_mul_f32_e32 v215, v3, v215
	v_mul_f32_e32 v216, v4, v216
	v_mul_f32_e32 v217, v5, v217
	v_cvt_pk_bf16_f32 v218, v214, v215
	v_cvt_pk_bf16_f32 v219, v216, v217
	global_store_dwordx2 v[24:25], v[218:219], off sc1
	s_waitcnt vmcnt(31)
	v_lshlrev_b32_e32 v200, 16, v138
	v_and_b32_e32 v201, 0xffff0000, v138
	v_lshlrev_b32_e32 v202, 16, v139
	v_and_b32_e32 v203, 0xffff0000, v139
	v_mul_f32_e32 v204, v59, v200
	v_mul_f32_e32 v205, v59, v201
	v_mul_f32_e32 v206, v59, v202
	v_mul_f32_e32 v207, v59, v203
	v_fma_f32 v6, v59, v200, v6
	v_fma_f32 v7, v59, v201, v7
	v_fma_f32 v8, v59, v202, v8
	v_fma_f32 v9, v59, v203, v9
	v_lshlrev_b32_e32 v88, 16, v130
	v_and_b32_e32 v89, 0xffff0000, v130
	v_lshlrev_b32_e32 v90, 16, v131
	v_and_b32_e32 v91, 0xffff0000, v131
	v_mul_f32_e32 v88, v55, v88
	v_mul_f32_e32 v89, v55, v89
	v_mul_f32_e32 v90, v55, v90
	v_mul_f32_e32 v91, v55, v91
	v_sub_f32_e32 v6, v6, v88
	v_sub_f32_e32 v7, v7, v89
	v_sub_f32_e32 v8, v8, v90
	v_sub_f32_e32 v9, v9, v91
	v_fma_f32 v214, v197, v6, -v204
	v_fma_f32 v215, v197, v7, -v205
	v_fma_f32 v216, v197, v8, -v206
	v_fma_f32 v217, v197, v9, -v207
	v_mul_f32_e32 v214, v2, v214
	v_mul_f32_e32 v215, v3, v215
	v_mul_f32_e32 v216, v4, v216
	v_mul_f32_e32 v217, v5, v217
	v_cvt_pk_bf16_f32 v218, v214, v215
	v_cvt_pk_bf16_f32 v219, v216, v217
	global_store_dwordx2 v[24:25], v[218:219], off offset:2048 sc1
	s_mov_b64 s[0:1], 0x1000
	v_lshl_add_u64 v[24:25], v[24:25], 0, s[0:1]
	s_waitcnt vmcnt(31)
; __device__ __forceinline__ unsigned pk2(float lo, float hi) { return pg8::cvt_pk_bf16(lo, hi); }
; __device__ __forceinline__ f32x4 ld4bf(const bf16* p) { const v2u w = *(const v2u*)p; return (f32x4){bf_lo(w.x), bf_hi(w.x), bf_lo(w.y), bf_hi(w.y)}; }
; __device__ __forceinline__ void pool_prep(const bf16* X, const float* ss, const float* gain, bf16* PB, LAS unsigned char* lds, int vcu, int G, int tid) {
;     ...
;         for (int i = 0; i < 32; ++i) { const int row = ra + i, t = row - bstart;
;             const f32x4 xn = ld4bf(xp + (size_t)row * DM) * rsl[row - r0 + 16];
;             f32x4 old = {0.f, 0.f, 0.f, 0.f};
;             if (t >= w) old = ld4bf(xp + (size_t)(row - w) * DM) * rsl[row - w - r0 + 16];
;             S = S + xn - old;
;             const int cnt = (t + 1 < w) ? t + 1 : w;
;             const f32x4 p = (S * (1.0f / (float)cnt) - xn) * gn;
;             v2u o; o.x = pk2(p[0], p[1]); o.y = pk2(p[2], p[3]); *(v2u*)(PB + (size_t)row * DM + 4 * q) = o; }
	v_lshlrev_b32_e32 v200, 16, v140
	v_and_b32_e32 v201, 0xffff0000, v140
	v_lshlrev_b32_e32 v202, 16, v141
	v_and_b32_e32 v203, 0xffff0000, v141
	v_mul_f32_e32 v204, v60, v200
	v_mul_f32_e32 v205, v60, v201
	v_mul_f32_e32 v206, v60, v202
	v_mul_f32_e32 v207, v60, v203
	v_fma_f32 v6, v60, v200, v6
	v_fma_f32 v7, v60, v201, v7
	v_fma_f32 v8, v60, v202, v8
	v_fma_f32 v9, v60, v203, v9
	v_lshlrev_b32_e32 v88, 16, v132
	v_and_b32_e32 v89, 0xffff0000, v132
	v_lshlrev_b32_e32 v90, 16, v133
	v_and_b32_e32 v91, 0xffff0000, v133
	v_mul_f32_e32 v88, v56, v88
	v_mul_f32_e32 v89, v56, v89
	v_mul_f32_e32 v90, v56, v90
	v_mul_f32_e32 v91, v56, v91
	v_sub_f32_e32 v6, v6, v88
	v_sub_f32_e32 v7, v7, v89
	v_sub_f32_e32 v8, v8, v90
	v_sub_f32_e32 v9, v9, v91
	v_fma_f32 v214, v197, v6, -v204
	v_fma_f32 v215, v197, v7, -v205
	v_fma_f32 v216, v197, v8, -v206
	v_fma_f32 v217, v197, v9, -v207
	v_mul_f32_e32 v214, v2, v214
	v_mul_f32_e32 v215, v3, v215
	v_mul_f32_e32 v216, v4, v216
	v_mul_f32_e32 v217, v5, v217
	v_cvt_pk_bf16_f32 v218, v214, v215
	v_cvt_pk_bf16_f32 v219, v216, v217
	global_store_dwordx2 v[24:25], v[218:219], off sc1
	s_waitcnt vmcnt(31)
	v_lshlrev_b32_e32 v200, 16, v142
	v_and_b32_e32 v201, 0xffff0000, v142
	v_lshlrev_b32_e32 v202, 16, v143
	v_and_b32_e32 v203, 0xffff0000, v143
	v_mul_f32_e32 v204, v61, v200
	v_mul_f32_e32 v205, v61, v201
	v_mul_f32_e32 v206, v61, v202
	v_mul_f32_e32 v207, v61, v203
	v_fma_f32 v6, v61, v200, v6
	v_fma_f32 v7, v61, v201, v7
	v_fma_f32 v8, v61, v202, v8
	v_fma_f32 v9, v61, v203, v9
	v_lshlrev_b32_e32 v88, 16, v134
	v_and_b32_e32 v89, 0xffff0000, v134
	v_lshlrev_b32_e32 v90, 16, v135
	v_and_b32_e32 v91, 0xffff0000, v135
	v_mul_f32_e32 v88, v57, v88
	v_mul_f32_e32 v89, v57, v89
	v_mul_f32_e32 v90, v57, v90
	v_mul_f32_e32 v91, v57, v91
	v_sub_f32_e32 v6, v6, v88
	v_sub_f32_e32 v7, v7, v89
	v_sub_f32_e32 v8, v8, v90
	v_sub_f32_e32 v9, v9, v91
	v_fma_f32 v214, v197, v6, -v204
	v_fma_f32 v215, v197, v7, -v205
	v_fma_f32 v216, v197, v8, -v206
	v_fma_f32 v217, v197, v9, -v207
	v_mul_f32_e32 v214, v2, v214
	v_mul_f32_e32 v215, v3, v215
	v_mul_f32_e32 v216, v4, v216
	v_mul_f32_e32 v217, v5, v217
	v_cvt_pk_bf16_f32 v218, v214, v215
	v_cvt_pk_bf16_f32 v219, v216, v217
	global_store_dwordx2 v[24:25], v[218:219], off offset:2048 sc1
	s_mov_b64 s[0:1], 0x1000
	v_lshl_add_u64 v[24:25], v[24:25], 0, s[0:1]
	s_waitcnt vmcnt(31)
	v_lshlrev_b32_e32 v200, 16, v144
	v_and_b32_e32 v201, 0xffff0000, v144
	v_lshlrev_b32_e32 v202, 16, v145
	v_and_b32_e32 v203, 0xffff0000, v145
	v_mul_f32_e32 v204, v62, v200
	v_mul_f32_e32 v205, v62, v201
	v_mul_f32_e32 v206, v62, v202
	v_mul_f32_e32 v207, v62, v203
	v_fma_f32 v6, v62, v200, v6
	v_fma_f32 v7, v62, v201, v7
	v_fma_f32 v8, v62, v202, v8
	v_fma_f32 v9, v62, v203, v9
	v_lshlrev_b32_e32 v88, 16, v136
	v_and_b32_e32 v89, 0xffff0000, v136
	v_lshlrev_b32_e32 v90, 16, v137
	v_and_b32_e32 v91, 0xffff0000, v137
	v_mul_f32_e32 v88, v58, v88
	v_mul_f32_e32 v89, v58, v89
	v_mul_f32_e32 v90, v58, v90
	v_mul_f32_e32 v91, v58, v91
	v_sub_f32_e32 v6, v6, v88
	v_sub_f32_e32 v7, v7, v89
	v_sub_f32_e32 v8, v8, v90
	v_sub_f32_e32 v9, v9, v91
	v_fma_f32 v214, v197, v6, -v204
	v_fma_f32 v215, v197, v7, -v205
	v_fma_f32 v216, v197, v8, -v206
	v_fma_f32 v217, v197, v9, -v207
	v_mul_f32_e32 v214, v2, v214
	v_mul_f32_e32 v215, v3, v215
	v_mul_f32_e32 v216, v4, v216
	v_mul_f32_e32 v217, v5, v217
	v_cvt_pk_bf16_f32 v218, v214, v215
	v_cvt_pk_bf16_f32 v219, v216, v217
	global_store_dwordx2 v[24:25], v[218:219], off sc1
	s_waitcnt vmcnt(31)
	v_lshlrev_b32_e32 v200, 16, v146
	v_and_b32_e32 v201, 0xffff0000, v146
	v_lshlrev_b32_e32 v202, 16, v147
	v_and_b32_e32 v203, 0xffff0000, v147
	v_mul_f32_e32 v204, v63, v200
	v_mul_f32_e32 v205, v63, v201
	v_mul_f32_e32 v206, v63, v202
	v_mul_f32_e32 v207, v63, v203
	v_fma_f32 v6, v63, v200, v6
	v_fma_f32 v7, v63, v201, v7
	v_fma_f32 v8, v63, v202, v8
	v_fma_f32 v9, v63, v203, v9
	v_lshlrev_b32_e32 v88, 16, v138
	v_and_b32_e32 v89, 0xffff0000, v138
	v_lshlrev_b32_e32 v90, 16, v139
	v_and_b32_e32 v91, 0xffff0000, v139
	v_mul_f32_e32 v88, v59, v88
	v_mul_f32_e32 v89, v59, v89
	v_mul_f32_e32 v90, v59, v90
	v_mul_f32_e32 v91, v59, v91
	v_sub_f32_e32 v6, v6, v88
	v_sub_f32_e32 v7, v7, v89
	v_sub_f32_e32 v8, v8, v90
	v_sub_f32_e32 v9, v9, v91
	v_fma_f32 v214, v197, v6, -v204
	v_fma_f32 v215, v197, v7, -v205
	v_fma_f32 v216, v197, v8, -v206
	v_fma_f32 v217, v197, v9, -v207
	v_mul_f32_e32 v214, v2, v214
	v_mul_f32_e32 v215, v3, v215
	v_mul_f32_e32 v216, v4, v216
	v_mul_f32_e32 v217, v5, v217
	v_cvt_pk_bf16_f32 v218, v214, v215
	v_cvt_pk_bf16_f32 v219, v216, v217
	global_store_dwordx2 v[24:25], v[218:219], off offset:2048 sc1
	s_mov_b64 s[0:1], 0x1000
	v_lshl_add_u64 v[24:25], v[24:25], 0, s[0:1]
	s_waitcnt vmcnt(31)
	v_lshlrev_b32_e32 v200, 16, v148
	v_and_b32_e32 v201, 0xffff0000, v148
	v_lshlrev_b32_e32 v202, 16, v149
	v_and_b32_e32 v203, 0xffff0000, v149
	v_mul_f32_e32 v204, v64, v200
	v_mul_f32_e32 v205, v64, v201
	v_mul_f32_e32 v206, v64, v202
	v_mul_f32_e32 v207, v64, v203
	v_fma_f32 v6, v64, v200, v6
	v_fma_f32 v7, v64, v201, v7
	v_fma_f32 v8, v64, v202, v8
	v_fma_f32 v9, v64, v203, v9
	v_lshlrev_b32_e32 v88, 16, v140
	v_and_b32_e32 v89, 0xffff0000, v140
	v_lshlrev_b32_e32 v90, 16, v141
	v_and_b32_e32 v91, 0xffff0000, v141
	v_mul_f32_e32 v88, v60, v88
	v_mul_f32_e32 v89, v60, v89
	v_mul_f32_e32 v90, v60, v90
	v_mul_f32_e32 v91, v60, v91
	v_sub_f32_e32 v6, v6, v88
	v_sub_f32_e32 v7, v7, v89
	v_sub_f32_e32 v8, v8, v90
	v_sub_f32_e32 v9, v9, v91
	v_fma_f32 v214, v197, v6, -v204
	v_fma_f32 v215, v197, v7, -v205
	v_fma_f32 v216, v197, v8, -v206
	v_fma_f32 v217, v197, v9, -v207
	v_mul_f32_e32 v214, v2, v214
	v_mul_f32_e32 v215, v3, v215
	v_mul_f32_e32 v216, v4, v216
	v_mul_f32_e32 v217, v5, v217
	v_cvt_pk_bf16_f32 v218, v214, v215
	v_cvt_pk_bf16_f32 v219, v216, v217
	global_store_dwordx2 v[24:25], v[218:219], off sc1
	s_waitcnt vmcnt(31)
; __device__ __forceinline__ unsigned pk2(float lo, float hi) { return pg8::cvt_pk_bf16(lo, hi); }
; __device__ __forceinline__ f32x4 ld4bf(const bf16* p) { const v2u w = *(const v2u*)p; return (f32x4){bf_lo(w.x), bf_hi(w.x), bf_lo(w.y), bf_hi(w.y)}; }
; __device__ __forceinline__ void pool_prep(const bf16* X, const float* ss, const float* gain, bf16* PB, LAS unsigned char* lds, int vcu, int G, int tid) {
;     ...
;         for (int i = 0; i < 32; ++i) { const int row = ra + i, t = row - bstart;
;             const f32x4 xn = ld4bf(xp + (size_t)row * DM) * rsl[row - r0 + 16];
;             f32x4 old = {0.f, 0.f, 0.f, 0.f};
;             if (t >= w) old = ld4bf(xp + (size_t)(row - w) * DM) * rsl[row - w - r0 + 16];
;             S = S + xn - old;
;             const int cnt = (t + 1 < w) ? t + 1 : w;
;             const f32x4 p = (S * (1.0f / (float)cnt) - xn) * gn;
;             v2u o; o.x = pk2(p[0], p[1]); o.y = pk2(p[2], p[3]); *(v2u*)(PB + (size_t)row * DM + 4 * q) = o; }
	v_lshlrev_b32_e32 v200, 16, v150
	v_and_b32_e32 v201, 0xffff0000, v150
	v_lshlrev_b32_e32 v202, 16, v151
	v_and_b32_e32 v203, 0xffff0000, v151
	v_mul_f32_e32 v204, v65, v200
	v_mul_f32_e32 v205, v65, v201
	v_mul_f32_e32 v206, v65, v202
	v_mul_f32_e32 v207, v65, v203
	v_fma_f32 v6, v65, v200, v6
	v_fma_f32 v7, v65, v201, v7
	v_fma_f32 v8, v65, v202, v8
	v_fma_f32 v9, v65, v203, v9
	v_lshlrev_b32_e32 v88, 16, v142
	v_and_b32_e32 v89, 0xffff0000, v142
	v_lshlrev_b32_e32 v90, 16, v143
	v_and_b32_e32 v91, 0xffff0000, v143
	v_mul_f32_e32 v88, v61, v88
	v_mul_f32_e32 v89, v61, v89
	v_mul_f32_e32 v90, v61, v90
	v_mul_f32_e32 v91, v61, v91
	v_sub_f32_e32 v6, v6, v88
	v_sub_f32_e32 v7, v7, v89
	v_sub_f32_e32 v8, v8, v90
	v_sub_f32_e32 v9, v9, v91
	v_fma_f32 v214, v197, v6, -v204
	v_fma_f32 v215, v197, v7, -v205
	v_fma_f32 v216, v197, v8, -v206
	v_fma_f32 v217, v197, v9, -v207
	v_mul_f32_e32 v214, v2, v214
	v_mul_f32_e32 v215, v3, v215
	v_mul_f32_e32 v216, v4, v216
	v_mul_f32_e32 v217, v5, v217
	v_cvt_pk_bf16_f32 v218, v214, v215
	v_cvt_pk_bf16_f32 v219, v216, v217
	global_store_dwordx2 v[24:25], v[218:219], off offset:2048 sc1
	s_mov_b64 s[0:1], 0x1000
	v_lshl_add_u64 v[24:25], v[24:25], 0, s[0:1]
	s_waitcnt vmcnt(31)
	v_lshlrev_b32_e32 v200, 16, v152
	v_and_b32_e32 v201, 0xffff0000, v152
	v_lshlrev_b32_e32 v202, 16, v153
	v_and_b32_e32 v203, 0xffff0000, v153
	v_mul_f32_e32 v204, v66, v200
	v_mul_f32_e32 v205, v66, v201
	v_mul_f32_e32 v206, v66, v202
	v_mul_f32_e32 v207, v66, v203
	v_fma_f32 v6, v66, v200, v6
	v_fma_f32 v7, v66, v201, v7
	v_fma_f32 v8, v66, v202, v8
	v_fma_f32 v9, v66, v203, v9
	v_lshlrev_b32_e32 v88, 16, v144
	v_and_b32_e32 v89, 0xffff0000, v144
	v_lshlrev_b32_e32 v90, 16, v145
	v_and_b32_e32 v91, 0xffff0000, v145
	v_mul_f32_e32 v88, v62, v88
	v_mul_f32_e32 v89, v62, v89
	v_mul_f32_e32 v90, v62, v90
	v_mul_f32_e32 v91, v62, v91
	v_sub_f32_e32 v6, v6, v88
	v_sub_f32_e32 v7, v7, v89
	v_sub_f32_e32 v8, v8, v90
	v_sub_f32_e32 v9, v9, v91
	v_fma_f32 v214, v197, v6, -v204
	v_fma_f32 v215, v197, v7, -v205
	v_fma_f32 v216, v197, v8, -v206
	v_fma_f32 v217, v197, v9, -v207
	v_mul_f32_e32 v214, v2, v214
	v_mul_f32_e32 v215, v3, v215
	v_mul_f32_e32 v216, v4, v216
	v_mul_f32_e32 v217, v5, v217
	v_cvt_pk_bf16_f32 v218, v214, v215
	v_cvt_pk_bf16_f32 v219, v216, v217
	global_store_dwordx2 v[24:25], v[218:219], off sc1
	s_waitcnt vmcnt(31)
	v_lshlrev_b32_e32 v200, 16, v154
	v_and_b32_e32 v201, 0xffff0000, v154
	v_lshlrev_b32_e32 v202, 16, v155
	v_and_b32_e32 v203, 0xffff0000, v155
	v_mul_f32_e32 v204, v67, v200
	v_mul_f32_e32 v205, v67, v201
	v_mul_f32_e32 v206, v67, v202
	v_mul_f32_e32 v207, v67, v203
	v_fma_f32 v6, v67, v200, v6
	v_fma_f32 v7, v67, v201, v7
	v_fma_f32 v8, v67, v202, v8
	v_fma_f32 v9, v67, v203, v9
	v_lshlrev_b32_e32 v88, 16, v146
	v_and_b32_e32 v89, 0xffff0000, v146
	v_lshlrev_b32_e32 v90, 16, v147
	v_and_b32_e32 v91, 0xffff0000, v147
	v_mul_f32_e32 v88, v63, v88
	v_mul_f32_e32 v89, v63, v89
	v_mul_f32_e32 v90, v63, v90
	v_mul_f32_e32 v91, v63, v91
	v_sub_f32_e32 v6, v6, v88
	v_sub_f32_e32 v7, v7, v89
	v_sub_f32_e32 v8, v8, v90
	v_sub_f32_e32 v9, v9, v91
	v_fma_f32 v214, v197, v6, -v204
	v_fma_f32 v215, v197, v7, -v205
	v_fma_f32 v216, v197, v8, -v206
	v_fma_f32 v217, v197, v9, -v207
	v_mul_f32_e32 v214, v2, v214
	v_mul_f32_e32 v215, v3, v215
	v_mul_f32_e32 v216, v4, v216
	v_mul_f32_e32 v217, v5, v217
	v_cvt_pk_bf16_f32 v218, v214, v215
	v_cvt_pk_bf16_f32 v219, v216, v217
	global_store_dwordx2 v[24:25], v[218:219], off offset:2048 sc1
	s_mov_b64 s[0:1], 0x1000
	v_lshl_add_u64 v[24:25], v[24:25], 0, s[0:1]
	s_waitcnt vmcnt(31)
	v_lshlrev_b32_e32 v200, 16, v156
	v_and_b32_e32 v201, 0xffff0000, v156
	v_lshlrev_b32_e32 v202, 16, v157
	v_and_b32_e32 v203, 0xffff0000, v157
	v_mul_f32_e32 v204, v68, v200
	v_mul_f32_e32 v205, v68, v201
	v_mul_f32_e32 v206, v68, v202
	v_mul_f32_e32 v207, v68, v203
	v_fma_f32 v6, v68, v200, v6
	v_fma_f32 v7, v68, v201, v7
	v_fma_f32 v8, v68, v202, v8
	v_fma_f32 v9, v68, v203, v9
	v_lshlrev_b32_e32 v88, 16, v148
	v_and_b32_e32 v89, 0xffff0000, v148
	v_lshlrev_b32_e32 v90, 16, v149
	v_and_b32_e32 v91, 0xffff0000, v149
	v_mul_f32_e32 v88, v64, v88
	v_mul_f32_e32 v89, v64, v89
	v_mul_f32_e32 v90, v64, v90
	v_mul_f32_e32 v91, v64, v91
	v_sub_f32_e32 v6, v6, v88
	v_sub_f32_e32 v7, v7, v89
	v_sub_f32_e32 v8, v8, v90
	v_sub_f32_e32 v9, v9, v91
	v_fma_f32 v214, v197, v6, -v204
	v_fma_f32 v215, v197, v7, -v205
	v_fma_f32 v216, v197, v8, -v206
	v_fma_f32 v217, v197, v9, -v207
	v_mul_f32_e32 v214, v2, v214
	v_mul_f32_e32 v215, v3, v215
	v_mul_f32_e32 v216, v4, v216
	v_mul_f32_e32 v217, v5, v217
	v_cvt_pk_bf16_f32 v218, v214, v215
	v_cvt_pk_bf16_f32 v219, v216, v217
	global_store_dwordx2 v[24:25], v[218:219], off sc1
	s_waitcnt vmcnt(31)
	v_lshlrev_b32_e32 v200, 16, v158
	v_and_b32_e32 v201, 0xffff0000, v158
	v_lshlrev_b32_e32 v202, 16, v159
	v_and_b32_e32 v203, 0xffff0000, v159
	v_mul_f32_e32 v204, v69, v200
	v_mul_f32_e32 v205, v69, v201
	v_mul_f32_e32 v206, v69, v202
	v_mul_f32_e32 v207, v69, v203
	v_fma_f32 v6, v69, v200, v6
	v_fma_f32 v7, v69, v201, v7
	v_fma_f32 v8, v69, v202, v8
	v_fma_f32 v9, v69, v203, v9
	v_lshlrev_b32_e32 v88, 16, v150
	v_and_b32_e32 v89, 0xffff0000, v150
	v_lshlrev_b32_e32 v90, 16, v151
	v_and_b32_e32 v91, 0xffff0000, v151
	v_mul_f32_e32 v88, v65, v88
	v_mul_f32_e32 v89, v65, v89
	v_mul_f32_e32 v90, v65, v90
	v_mul_f32_e32 v91, v65, v91
	v_sub_f32_e32 v6, v6, v88
	v_sub_f32_e32 v7, v7, v89
	v_sub_f32_e32 v8, v8, v90
	v_sub_f32_e32 v9, v9, v91
	v_fma_f32 v214, v197, v6, -v204
	v_fma_f32 v215, v197, v7, -v205
	v_fma_f32 v216, v197, v8, -v206
	v_fma_f32 v217, v197, v9, -v207
	v_mul_f32_e32 v214, v2, v214
	v_mul_f32_e32 v215, v3, v215
	v_mul_f32_e32 v216, v4, v216
	v_mul_f32_e32 v217, v5, v217
	v_cvt_pk_bf16_f32 v218, v214, v215
	v_cvt_pk_bf16_f32 v219, v216, v217
	global_store_dwordx2 v[24:25], v[218:219], off offset:2048 sc1
	s_mov_b64 s[0:1], 0x1000
	v_lshl_add_u64 v[24:25], v[24:25], 0, s[0:1]
	s_waitcnt vmcnt(31)
; __device__ __forceinline__ unsigned pk2(float lo, float hi) { return pg8::cvt_pk_bf16(lo, hi); }
; __device__ __forceinline__ f32x4 ld4bf(const bf16* p) { const v2u w = *(const v2u*)p; return (f32x4){bf_lo(w.x), bf_hi(w.x), bf_lo(w.y), bf_hi(w.y)}; }
; __device__ __forceinline__ void pool_prep(const bf16* X, const float* ss, const float* gain, bf16* PB, LAS unsigned char* lds, int vcu, int G, int tid) {
;     ...
;         for (int i = 0; i < 32; ++i) { const int row = ra + i, t = row - bstart;
;             const f32x4 xn = ld4bf(xp + (size_t)row * DM) * rsl[row - r0 + 16];
;             f32x4 old = {0.f, 0.f, 0.f, 0.f};
;             if (t >= w) old = ld4bf(xp + (size_t)(row - w) * DM) * rsl[row - w - r0 + 16];
;             S = S + xn - old;
;             const int cnt = (t + 1 < w) ? t + 1 : w;
;             const f32x4 p = (S * (1.0f / (float)cnt) - xn) * gn;
;             v2u o; o.x = pk2(p[0], p[1]); o.y = pk2(p[2], p[3]); *(v2u*)(PB + (size_t)row * DM + 4 * q) = o; }
	v_lshlrev_b32_e32 v200, 16, v160
	v_and_b32_e32 v201, 0xffff0000, v160
	v_lshlrev_b32_e32 v202, 16, v161
	v_and_b32_e32 v203, 0xffff0000, v161
	v_mul_f32_e32 v204, v70, v200
	v_mul_f32_e32 v205, v70, v201
	v_mul_f32_e32 v206, v70, v202
	v_mul_f32_e32 v207, v70, v203
	v_fma_f32 v6, v70, v200, v6
	v_fma_f32 v7, v70, v201, v7
	v_fma_f32 v8, v70, v202, v8
	v_fma_f32 v9, v70, v203, v9
	v_lshlrev_b32_e32 v88, 16, v152
	v_and_b32_e32 v89, 0xffff0000, v152
	v_lshlrev_b32_e32 v90, 16, v153
	v_and_b32_e32 v91, 0xffff0000, v153
	v_mul_f32_e32 v88, v66, v88
	v_mul_f32_e32 v89, v66, v89
	v_mul_f32_e32 v90, v66, v90
	v_mul_f32_e32 v91, v66, v91
	v_sub_f32_e32 v6, v6, v88
	v_sub_f32_e32 v7, v7, v89
	v_sub_f32_e32 v8, v8, v90
	v_sub_f32_e32 v9, v9, v91
	v_fma_f32 v214, v197, v6, -v204
	v_fma_f32 v215, v197, v7, -v205
	v_fma_f32 v216, v197, v8, -v206
	v_fma_f32 v217, v197, v9, -v207
	v_mul_f32_e32 v214, v2, v214
	v_mul_f32_e32 v215, v3, v215
	v_mul_f32_e32 v216, v4, v216
	v_mul_f32_e32 v217, v5, v217
	v_cvt_pk_bf16_f32 v218, v214, v215
	v_cvt_pk_bf16_f32 v219, v216, v217
	global_store_dwordx2 v[24:25], v[218:219], off sc1
	s_waitcnt vmcnt(31)
	v_lshlrev_b32_e32 v200, 16, v162
	v_and_b32_e32 v201, 0xffff0000, v162
	v_lshlrev_b32_e32 v202, 16, v163
	v_and_b32_e32 v203, 0xffff0000, v163
	v_mul_f32_e32 v204, v71, v200
	v_mul_f32_e32 v205, v71, v201
	v_mul_f32_e32 v206, v71, v202
	v_mul_f32_e32 v207, v71, v203
	v_fma_f32 v6, v71, v200, v6
	v_fma_f32 v7, v71, v201, v7
	v_fma_f32 v8, v71, v202, v8
	v_fma_f32 v9, v71, v203, v9
	v_lshlrev_b32_e32 v88, 16, v154
	v_and_b32_e32 v89, 0xffff0000, v154
	v_lshlrev_b32_e32 v90, 16, v155
	v_and_b32_e32 v91, 0xffff0000, v155
	v_mul_f32_e32 v88, v67, v88
	v_mul_f32_e32 v89, v67, v89
	v_mul_f32_e32 v90, v67, v90
	v_mul_f32_e32 v91, v67, v91
	v_sub_f32_e32 v6, v6, v88
	v_sub_f32_e32 v7, v7, v89
	v_sub_f32_e32 v8, v8, v90
	v_sub_f32_e32 v9, v9, v91
	v_fma_f32 v214, v197, v6, -v204
	v_fma_f32 v215, v197, v7, -v205
	v_fma_f32 v216, v197, v8, -v206
	v_fma_f32 v217, v197, v9, -v207
	v_mul_f32_e32 v214, v2, v214
	v_mul_f32_e32 v215, v3, v215
	v_mul_f32_e32 v216, v4, v216
	v_mul_f32_e32 v217, v5, v217
	v_cvt_pk_bf16_f32 v218, v214, v215
	v_cvt_pk_bf16_f32 v219, v216, v217
	global_store_dwordx2 v[24:25], v[218:219], off offset:2048 sc1
	s_mov_b64 s[0:1], 0x1000
	v_lshl_add_u64 v[24:25], v[24:25], 0, s[0:1]
	s_waitcnt vmcnt(31)
	v_lshlrev_b32_e32 v200, 16, v164
	v_and_b32_e32 v201, 0xffff0000, v164
	v_lshlrev_b32_e32 v202, 16, v165
	v_and_b32_e32 v203, 0xffff0000, v165
	v_mul_f32_e32 v204, v72, v200
	v_mul_f32_e32 v205, v72, v201
	v_mul_f32_e32 v206, v72, v202
	v_mul_f32_e32 v207, v72, v203
	v_fma_f32 v6, v72, v200, v6
	v_fma_f32 v7, v72, v201, v7
	v_fma_f32 v8, v72, v202, v8
	v_fma_f32 v9, v72, v203, v9
	v_lshlrev_b32_e32 v88, 16, v156
	v_and_b32_e32 v89, 0xffff0000, v156
	v_lshlrev_b32_e32 v90, 16, v157
	v_and_b32_e32 v91, 0xffff0000, v157
	v_mul_f32_e32 v88, v68, v88
	v_mul_f32_e32 v89, v68, v89
	v_mul_f32_e32 v90, v68, v90
	v_mul_f32_e32 v91, v68, v91
	v_sub_f32_e32 v6, v6, v88
	v_sub_f32_e32 v7, v7, v89
	v_sub_f32_e32 v8, v8, v90
	v_sub_f32_e32 v9, v9, v91
	v_fma_f32 v214, v197, v6, -v204
	v_fma_f32 v215, v197, v7, -v205
	v_fma_f32 v216, v197, v8, -v206
	v_fma_f32 v217, v197, v9, -v207
	v_mul_f32_e32 v214, v2, v214
	v_mul_f32_e32 v215, v3, v215
	v_mul_f32_e32 v216, v4, v216
	v_mul_f32_e32 v217, v5, v217
	v_cvt_pk_bf16_f32 v218, v214, v215
	v_cvt_pk_bf16_f32 v219, v216, v217
	global_store_dwordx2 v[24:25], v[218:219], off sc1
	s_waitcnt vmcnt(31)
	v_lshlrev_b32_e32 v200, 16, v166
	v_and_b32_e32 v201, 0xffff0000, v166
	v_lshlrev_b32_e32 v202, 16, v167
	v_and_b32_e32 v203, 0xffff0000, v167
	v_mul_f32_e32 v204, v73, v200
	v_mul_f32_e32 v205, v73, v201
	v_mul_f32_e32 v206, v73, v202
	v_mul_f32_e32 v207, v73, v203
	v_fma_f32 v6, v73, v200, v6
	v_fma_f32 v7, v73, v201, v7
	v_fma_f32 v8, v73, v202, v8
	v_fma_f32 v9, v73, v203, v9
	v_lshlrev_b32_e32 v88, 16, v158
	v_and_b32_e32 v89, 0xffff0000, v158
	v_lshlrev_b32_e32 v90, 16, v159
	v_and_b32_e32 v91, 0xffff0000, v159
	v_mul_f32_e32 v88, v69, v88
	v_mul_f32_e32 v89, v69, v89
	v_mul_f32_e32 v90, v69, v90
	v_mul_f32_e32 v91, v69, v91
	v_sub_f32_e32 v6, v6, v88
	v_sub_f32_e32 v7, v7, v89
	v_sub_f32_e32 v8, v8, v90
	v_sub_f32_e32 v9, v9, v91
	v_fma_f32 v214, v197, v6, -v204
	v_fma_f32 v215, v197, v7, -v205
	v_fma_f32 v216, v197, v8, -v206
	v_fma_f32 v217, v197, v9, -v207
	v_mul_f32_e32 v214, v2, v214
	v_mul_f32_e32 v215, v3, v215
	v_mul_f32_e32 v216, v4, v216
	v_mul_f32_e32 v217, v5, v217
	v_cvt_pk_bf16_f32 v218, v214, v215
	v_cvt_pk_bf16_f32 v219, v216, v217
	global_store_dwordx2 v[24:25], v[218:219], off offset:2048 sc1
	s_mov_b64 s[0:1], 0x1000
	v_lshl_add_u64 v[24:25], v[24:25], 0, s[0:1]
	s_waitcnt vmcnt(31)
	v_lshlrev_b32_e32 v200, 16, v168
	v_and_b32_e32 v201, 0xffff0000, v168
	v_lshlrev_b32_e32 v202, 16, v169
	v_and_b32_e32 v203, 0xffff0000, v169
	v_mul_f32_e32 v204, v74, v200
	v_mul_f32_e32 v205, v74, v201
	v_mul_f32_e32 v206, v74, v202
	v_mul_f32_e32 v207, v74, v203
	v_fma_f32 v6, v74, v200, v6
	v_fma_f32 v7, v74, v201, v7
	v_fma_f32 v8, v74, v202, v8
	v_fma_f32 v9, v74, v203, v9
	v_lshlrev_b32_e32 v88, 16, v160
	v_and_b32_e32 v89, 0xffff0000, v160
	v_lshlrev_b32_e32 v90, 16, v161
	v_and_b32_e32 v91, 0xffff0000, v161
	v_mul_f32_e32 v88, v70, v88
	v_mul_f32_e32 v89, v70, v89
	v_mul_f32_e32 v90, v70, v90
	v_mul_f32_e32 v91, v70, v91
	v_sub_f32_e32 v6, v6, v88
	v_sub_f32_e32 v7, v7, v89
	v_sub_f32_e32 v8, v8, v90
	v_sub_f32_e32 v9, v9, v91
	v_fma_f32 v214, v197, v6, -v204
	v_fma_f32 v215, v197, v7, -v205
	v_fma_f32 v216, v197, v8, -v206
	v_fma_f32 v217, v197, v9, -v207
	v_mul_f32_e32 v214, v2, v214
	v_mul_f32_e32 v215, v3, v215
	v_mul_f32_e32 v216, v4, v216
	v_mul_f32_e32 v217, v5, v217
	v_cvt_pk_bf16_f32 v218, v214, v215
	v_cvt_pk_bf16_f32 v219, v216, v217
	global_store_dwordx2 v[24:25], v[218:219], off sc1
	s_waitcnt vmcnt(31)
	v_lshlrev_b32_e32 v200, 16, v170
	v_and_b32_e32 v201, 0xffff0000, v170
	v_lshlrev_b32_e32 v202, 16, v171
	v_and_b32_e32 v203, 0xffff0000, v171
	v_mul_f32_e32 v204, v75, v200
	v_mul_f32_e32 v205, v75, v201
	v_mul_f32_e32 v206, v75, v202
	v_mul_f32_e32 v207, v75, v203
	v_fma_f32 v6, v75, v200, v6
	v_fma_f32 v7, v75, v201, v7
	v_fma_f32 v8, v75, v202, v8
	v_fma_f32 v9, v75, v203, v9
	v_lshlrev_b32_e32 v88, 16, v162
	v_and_b32_e32 v89, 0xffff0000, v162
	v_lshlrev_b32_e32 v90, 16, v163
	v_and_b32_e32 v91, 0xffff0000, v163
	v_mul_f32_e32 v88, v71, v88
	v_mul_f32_e32 v89, v71, v89
	v_mul_f32_e32 v90, v71, v90
	v_mul_f32_e32 v91, v71, v91
	v_sub_f32_e32 v6, v6, v88
	v_sub_f32_e32 v7, v7, v89
	v_sub_f32_e32 v8, v8, v90
	v_sub_f32_e32 v9, v9, v91
	v_fma_f32 v214, v197, v6, -v204
	v_fma_f32 v215, v197, v7, -v205
	v_fma_f32 v216, v197, v8, -v206
	v_fma_f32 v217, v197, v9, -v207
	v_mul_f32_e32 v214, v2, v214
	v_mul_f32_e32 v215, v3, v215
	v_mul_f32_e32 v216, v4, v216
	v_mul_f32_e32 v217, v5, v217
	v_cvt_pk_bf16_f32 v218, v214, v215
	v_cvt_pk_bf16_f32 v219, v216, v217
	global_store_dwordx2 v[24:25], v[218:219], off offset:2048 sc1
	s_branch .LBB0_308
; __device__ __forceinline__ f32x4 ld4bf(const bf16* p) { const v2u w = *(const v2u*)p; return (f32x4){bf_lo(w.x), bf_hi(w.x), bf_lo(w.y), bf_hi(w.y)}; }
; __device__ __forceinline__ void pool_prep(const bf16* X, const float* ss, const float* gain, bf16* PB, LAS unsigned char* lds, int vcu, int G, int tid) {
;     ...
;         if (tid < 80) { const int row = r0 - 16 + tid; rsl[tid] = (row >= bstart) ? pg8::row_rstd(ss, row) : 0.f; }
;         __syncthreads();
;         const int q = tid & 255, half = tid >> 8, w = 2 << (q >> 6);
;         const f32x4 gn = *(const f32x4*)(gain + 4 * q);
;         const int ra = r0 + 32 * half;
;         const bf16* xp = X + 4 * q;
;         f32x4 S = {0.f, 0.f, 0.f, 0.f};
; #pragma unroll
;         for (int j = 1; j <= 16; ++j) { const int row = ra - j; if (j <= w && row >= bstart) S += ld4bf(xp + (size_t)row * DM) * rsl[row - r0 + 16]; }
.Lmy_pool_w2:
	s_mov_b32 s0, 4096
	v_subrev_co_u32_e32 v198, vcc, s0, v22
	s_nop 1
	v_subbrev_co_u32_e32 v199, vcc, 0, v23, vcc
	s_mov_b64 s[0:1], 0x1000
	global_load_dwordx2 v[100:101], v[198:199], off
	global_load_dwordx2 v[102:103], v[198:199], off offset:2048
	v_lshl_add_u64 v[198:199], v[198:199], 0, s[0:1]
	global_load_dwordx2 v[104:105], v[198:199], off
	global_load_dwordx2 v[106:107], v[198:199], off offset:2048
	v_lshl_add_u64 v[198:199], v[198:199], 0, s[0:1]
	global_load_dwordx2 v[108:109], v[198:199], off
	global_load_dwordx2 v[110:111], v[198:199], off offset:2048
	v_lshl_add_u64 v[198:199], v[198:199], 0, s[0:1]
	global_load_dwordx2 v[112:113], v[198:199], off
	global_load_dwordx2 v[114:115], v[198:199], off offset:2048
	v_lshl_add_u64 v[198:199], v[198:199], 0, s[0:1]
	global_load_dwordx2 v[116:117], v[198:199], off
	global_load_dwordx2 v[118:119], v[198:199], off offset:2048
	v_lshl_add_u64 v[198:199], v[198:199], 0, s[0:1]
	global_load_dwordx2 v[120:121], v[198:199], off
	global_load_dwordx2 v[122:123], v[198:199], off offset:2048
	v_lshl_add_u64 v[198:199], v[198:199], 0, s[0:1]
	global_load_dwordx2 v[124:125], v[198:199], off
	global_load_dwordx2 v[126:127], v[198:199], off offset:2048
	v_lshl_add_u64 v[198:199], v[198:199], 0, s[0:1]
	global_load_dwordx2 v[128:129], v[198:199], off
	global_load_dwordx2 v[130:131], v[198:199], off offset:2048
	v_lshl_add_u64 v[198:199], v[198:199], 0, s[0:1]
	global_load_dwordx2 v[132:133], v[198:199], off
	global_load_dwordx2 v[134:135], v[198:199], off offset:2048
	v_lshl_add_u64 v[198:199], v[198:199], 0, s[0:1]
	global_load_dwordx2 v[136:137], v[198:199], off
	global_load_dwordx2 v[138:139], v[198:199], off offset:2048
	v_lshl_add_u64 v[198:199], v[198:199], 0, s[0:1]
	global_load_dwordx2 v[140:141], v[198:199], off
	global_load_dwordx2 v[142:143], v[198:199], off offset:2048
	v_lshl_add_u64 v[198:199], v[198:199], 0, s[0:1]
	global_load_dwordx2 v[144:145], v[198:199], off
	global_load_dwordx2 v[146:147], v[198:199], off offset:2048
	v_lshl_add_u64 v[198:199], v[198:199], 0, s[0:1]
	global_load_dwordx2 v[148:149], v[198:199], off
	global_load_dwordx2 v[150:151], v[198:199], off offset:2048
	v_lshl_add_u64 v[198:199], v[198:199], 0, s[0:1]
	global_load_dwordx2 v[152:153], v[198:199], off
	global_load_dwordx2 v[154:155], v[198:199], off offset:2048
	v_lshl_add_u64 v[198:199], v[198:199], 0, s[0:1]
	global_load_dwordx2 v[156:157], v[198:199], off
	global_load_dwordx2 v[158:159], v[198:199], off offset:2048
	v_lshl_add_u64 v[198:199], v[198:199], 0, s[0:1]
	global_load_dwordx2 v[160:161], v[198:199], off
	global_load_dwordx2 v[162:163], v[198:199], off offset:2048
	v_lshl_add_u64 v[198:199], v[198:199], 0, s[0:1]
	global_load_dwordx2 v[164:165], v[198:199], off
	global_load_dwordx2 v[166:167], v[198:199], off offset:2048
	ds_read_b32 v40, v21 offset:56
	ds_read_b32 v41, v21 offset:60
	ds_read_b32 v42, v21 offset:64
	ds_read_b32 v43, v21 offset:68
	ds_read_b32 v44, v21 offset:72
	ds_read_b32 v45, v21 offset:76
	ds_read_b32 v46, v21 offset:80
	ds_read_b32 v47, v21 offset:84
	ds_read_b32 v48, v21 offset:88
	ds_read_b32 v49, v21 offset:92
	ds_read_b32 v50, v21 offset:96
	ds_read_b32 v51, v21 offset:100
	s_waitcnt lgkmcnt(0)
	ds_read_b32 v52, v21 offset:104
	ds_read_b32 v53, v21 offset:108
	ds_read_b32 v54, v21 offset:112
	ds_read_b32 v55, v21 offset:116
	ds_read_b32 v56, v21 offset:120
	ds_read_b32 v57, v21 offset:124
	ds_read_b32 v58, v21 offset:128
	ds_read_b32 v59, v21 offset:132
	ds_read_b32 v60, v21 offset:136
	ds_read_b32 v61, v21 offset:140
	ds_read_b32 v62, v21 offset:144
	ds_read_b32 v63, v21 offset:148
	s_waitcnt lgkmcnt(0)
	ds_read_b32 v64, v21 offset:152
	ds_read_b32 v65, v21 offset:156
	ds_read_b32 v66, v21 offset:160
	ds_read_b32 v67, v21 offset:164
	ds_read_b32 v68, v21 offset:168
	ds_read_b32 v69, v21 offset:172
	ds_read_b32 v70, v21 offset:176
	ds_read_b32 v71, v21 offset:180
	ds_read_b32 v72, v21 offset:184
	ds_read_b32 v73, v21 offset:188
	v_div_scale_f32 v26, s[0:1], v196, v196, 1.0
	v_rcp_f32_e32 v27, v26
	s_nop 0
	v_fma_f32 v28, -v26, v27, 1.0
	v_fmac_f32_e32 v27, v28, v27
	v_div_scale_f32 v28, vcc, 1.0, v196, 1.0
	v_mul_f32_e32 v29, v28, v27
	v_fma_f32 v30, -v26, v29, v28
	v_fmac_f32_e32 v29, v30, v27
	v_fma_f32 v26, -v26, v29, v28
	s_nop 1
	v_div_fmas_f32 v197, v26, v27, v29
	v_div_fixup_f32 v197, v197, v196, 1.0
	v_mov_b32_e32 v6, 0
	v_mov_b32_e32 v7, 0
	v_mov_b32_e32 v8, 0
	v_mov_b32_e32 v9, 0
	s_waitcnt lgkmcnt(0)
	s_waitcnt vmcnt(32)
	v_cndmask_b32_e64 v100, v100, 0, s[6:7]
	v_cndmask_b32_e64 v101, v101, 0, s[6:7]
	v_cndmask_b32_e64 v102, v102, 0, s[6:7]
	v_cndmask_b32_e64 v103, v103, 0, s[6:7]
	v_lshlrev_b32_e32 v200, 16, v102
	v_and_b32_e32 v201, 0xffff0000, v102
	v_lshlrev_b32_e32 v202, 16, v103
	v_and_b32_e32 v203, 0xffff0000, v103
	v_fma_f32 v6, v41, v200, v6
	v_fma_f32 v7, v41, v201, v7
	v_fma_f32 v8, v41, v202, v8
	v_fma_f32 v9, v41, v203, v9
	v_lshlrev_b32_e32 v200, 16, v100
	v_and_b32_e32 v201, 0xffff0000, v100
	v_lshlrev_b32_e32 v202, 16, v101
	v_and_b32_e32 v203, 0xffff0000, v101
	v_fma_f32 v6, v40, v200, v6
	v_fma_f32 v7, v40, v201, v7
	v_fma_f32 v8, v40, v202, v8
	v_fma_f32 v9, v40, v203, v9
	s_waitcnt vmcnt(31)
; __device__ __forceinline__ unsigned pk2(float lo, float hi) { return pg8::cvt_pk_bf16(lo, hi); }
; __device__ __forceinline__ f32x4 ld4bf(const bf16* p) { const v2u w = *(const v2u*)p; return (f32x4){bf_lo(w.x), bf_hi(w.x), bf_lo(w.y), bf_hi(w.y)}; }
; __device__ __forceinline__ void pool_prep(const bf16* X, const float* ss, const float* gain, bf16* PB, LAS unsigned char* lds, int vcu, int G, int tid) {
;     ...
;         for (int i = 0; i < 32; ++i) { const int row = ra + i, t = row - bstart;
;             const f32x4 xn = ld4bf(xp + (size_t)row * DM) * rsl[row - r0 + 16];
;             f32x4 old = {0.f, 0.f, 0.f, 0.f};
;             if (t >= w) old = ld4bf(xp + (size_t)(row - w) * DM) * rsl[row - w - r0 + 16];
;             S = S + xn - old;
;             const int cnt = (t + 1 < w) ? t + 1 : w;
;             const f32x4 p = (S * (1.0f / (float)cnt) - xn) * gn;
;             v2u o; o.x = pk2(p[0], p[1]); o.y = pk2(p[2], p[3]); *(v2u*)(PB + (size_t)row * DM + 4 * q) = o; }
	v_lshlrev_b32_e32 v200, 16, v104
	v_and_b32_e32 v201, 0xffff0000, v104
	v_lshlrev_b32_e32 v202, 16, v105
	v_and_b32_e32 v203, 0xffff0000, v105
	v_mul_f32_e32 v204, v42, v200
	v_mul_f32_e32 v205, v42, v201
	v_mul_f32_e32 v206, v42, v202
	v_mul_f32_e32 v207, v42, v203
	v_fma_f32 v6, v42, v200, v6
	v_fma_f32 v7, v42, v201, v7
	v_fma_f32 v8, v42, v202, v8
	v_fma_f32 v9, v42, v203, v9
	v_lshlrev_b32_e32 v88, 16, v100
	v_and_b32_e32 v89, 0xffff0000, v100
	v_lshlrev_b32_e32 v90, 16, v101
	v_and_b32_e32 v91, 0xffff0000, v101
	v_mul_f32_e32 v88, v40, v88
	v_mul_f32_e32 v89, v40, v89
	v_mul_f32_e32 v90, v40, v90
	v_mul_f32_e32 v91, v40, v91
	v_sub_f32_e32 v6, v6, v88
	v_sub_f32_e32 v7, v7, v89
	v_sub_f32_e32 v8, v8, v90
	v_sub_f32_e32 v9, v9, v91
	v_add_u32_e32 v92, 1, v20
	v_min_i32_e32 v92, v92, v32
	v_cvt_f32_i32_e32 v92, v92
	v_div_scale_f32 v26, s[0:1], v92, v92, 1.0
	v_rcp_f32_e32 v27, v26
	s_nop 0
	v_fma_f32 v28, -v26, v27, 1.0
	v_fmac_f32_e32 v27, v28, v27
	v_div_scale_f32 v28, vcc, 1.0, v92, 1.0
	v_mul_f32_e32 v29, v28, v27
	v_fma_f32 v30, -v26, v29, v28
	v_fmac_f32_e32 v29, v30, v27
	v_fma_f32 v26, -v26, v29, v28
	s_nop 1
	v_div_fmas_f32 v93, v26, v27, v29
	v_div_fixup_f32 v93, v93, v92, 1.0
	v_fma_f32 v214, v93, v6, -v204
	v_fma_f32 v215, v93, v7, -v205
	v_fma_f32 v216, v93, v8, -v206
	v_fma_f32 v217, v93, v9, -v207
	v_mul_f32_e32 v214, v2, v214
	v_mul_f32_e32 v215, v3, v215
	v_mul_f32_e32 v216, v4, v216
	v_mul_f32_e32 v217, v5, v217
	v_cvt_pk_bf16_f32 v218, v214, v215
	v_cvt_pk_bf16_f32 v219, v216, v217
	global_store_dwordx2 v[24:25], v[218:219], off sc1
	s_waitcnt vmcnt(31)
	v_lshlrev_b32_e32 v200, 16, v106
	v_and_b32_e32 v201, 0xffff0000, v106
	v_lshlrev_b32_e32 v202, 16, v107
	v_and_b32_e32 v203, 0xffff0000, v107
	v_mul_f32_e32 v204, v43, v200
	v_mul_f32_e32 v205, v43, v201
	v_mul_f32_e32 v206, v43, v202
	v_mul_f32_e32 v207, v43, v203
	v_fma_f32 v6, v43, v200, v6
	v_fma_f32 v7, v43, v201, v7
	v_fma_f32 v8, v43, v202, v8
	v_fma_f32 v9, v43, v203, v9
	v_lshlrev_b32_e32 v88, 16, v102
	v_and_b32_e32 v89, 0xffff0000, v102
	v_lshlrev_b32_e32 v90, 16, v103
	v_and_b32_e32 v91, 0xffff0000, v103
	v_mul_f32_e32 v88, v41, v88
	v_mul_f32_e32 v89, v41, v89
	v_mul_f32_e32 v90, v41, v90
	v_mul_f32_e32 v91, v41, v91
	v_sub_f32_e32 v6, v6, v88
	v_sub_f32_e32 v7, v7, v89
	v_sub_f32_e32 v8, v8, v90
	v_sub_f32_e32 v9, v9, v91
	v_fma_f32 v214, v197, v6, -v204
	v_fma_f32 v215, v197, v7, -v205
	v_fma_f32 v216, v197, v8, -v206
	v_fma_f32 v217, v197, v9, -v207
	v_mul_f32_e32 v214, v2, v214
	v_mul_f32_e32 v215, v3, v215
	v_mul_f32_e32 v216, v4, v216
	v_mul_f32_e32 v217, v5, v217
	v_cvt_pk_bf16_f32 v218, v214, v215
	v_cvt_pk_bf16_f32 v219, v216, v217
	global_store_dwordx2 v[24:25], v[218:219], off offset:2048 sc1
	s_mov_b64 s[0:1], 0x1000
	v_lshl_add_u64 v[24:25], v[24:25], 0, s[0:1]
	s_waitcnt vmcnt(31)
	v_lshlrev_b32_e32 v200, 16, v108
	v_and_b32_e32 v201, 0xffff0000, v108
	v_lshlrev_b32_e32 v202, 16, v109
	v_and_b32_e32 v203, 0xffff0000, v109
	v_mul_f32_e32 v204, v44, v200
	v_mul_f32_e32 v205, v44, v201
	v_mul_f32_e32 v206, v44, v202
	v_mul_f32_e32 v207, v44, v203
	v_fma_f32 v6, v44, v200, v6
	v_fma_f32 v7, v44, v201, v7
	v_fma_f32 v8, v44, v202, v8
	v_fma_f32 v9, v44, v203, v9
	v_lshlrev_b32_e32 v88, 16, v104
	v_and_b32_e32 v89, 0xffff0000, v104
	v_lshlrev_b32_e32 v90, 16, v105
	v_and_b32_e32 v91, 0xffff0000, v105
	v_mul_f32_e32 v88, v42, v88
	v_mul_f32_e32 v89, v42, v89
	v_mul_f32_e32 v90, v42, v90
	v_mul_f32_e32 v91, v42, v91
	v_sub_f32_e32 v6, v6, v88
	v_sub_f32_e32 v7, v7, v89
	v_sub_f32_e32 v8, v8, v90
	v_sub_f32_e32 v9, v9, v91
	v_fma_f32 v214, v197, v6, -v204
	v_fma_f32 v215, v197, v7, -v205
	v_fma_f32 v216, v197, v8, -v206
	v_fma_f32 v217, v197, v9, -v207
	v_mul_f32_e32 v214, v2, v214
	v_mul_f32_e32 v215, v3, v215
	v_mul_f32_e32 v216, v4, v216
	v_mul_f32_e32 v217, v5, v217
	v_cvt_pk_bf16_f32 v218, v214, v215
	v_cvt_pk_bf16_f32 v219, v216, v217
	global_store_dwordx2 v[24:25], v[218:219], off sc1
	s_waitcnt vmcnt(31)
	v_lshlrev_b32_e32 v200, 16, v110
	v_and_b32_e32 v201, 0xffff0000, v110
	v_lshlrev_b32_e32 v202, 16, v111
	v_and_b32_e32 v203, 0xffff0000, v111
	v_mul_f32_e32 v204, v45, v200
	v_mul_f32_e32 v205, v45, v201
	v_mul_f32_e32 v206, v45, v202
	v_mul_f32_e32 v207, v45, v203
	v_fma_f32 v6, v45, v200, v6
	v_fma_f32 v7, v45, v201, v7
	v_fma_f32 v8, v45, v202, v8
	v_fma_f32 v9, v45, v203, v9
	v_lshlrev_b32_e32 v88, 16, v106
	v_and_b32_e32 v89, 0xffff0000, v106
	v_lshlrev_b32_e32 v90, 16, v107
	v_and_b32_e32 v91, 0xffff0000, v107
	v_mul_f32_e32 v88, v43, v88
	v_mul_f32_e32 v89, v43, v89
	v_mul_f32_e32 v90, v43, v90
	v_mul_f32_e32 v91, v43, v91
	v_sub_f32_e32 v6, v6, v88
	v_sub_f32_e32 v7, v7, v89
	v_sub_f32_e32 v8, v8, v90
	v_sub_f32_e32 v9, v9, v91
	v_fma_f32 v214, v197, v6, -v204
	v_fma_f32 v215, v197, v7, -v205
	v_fma_f32 v216, v197, v8, -v206
	v_fma_f32 v217, v197, v9, -v207
	v_mul_f32_e32 v214, v2, v214
	v_mul_f32_e32 v215, v3, v215
	v_mul_f32_e32 v216, v4, v216
	v_mul_f32_e32 v217, v5, v217
	v_cvt_pk_bf16_f32 v218, v214, v215
	v_cvt_pk_bf16_f32 v219, v216, v217
	global_store_dwordx2 v[24:25], v[218:219], off offset:2048 sc1
	s_mov_b64 s[0:1], 0x1000
	v_lshl_add_u64 v[24:25], v[24:25], 0, s[0:1]
	s_waitcnt vmcnt(31)
; __device__ __forceinline__ unsigned pk2(float lo, float hi) { return pg8::cvt_pk_bf16(lo, hi); }
; __device__ __forceinline__ f32x4 ld4bf(const bf16* p) { const v2u w = *(const v2u*)p; return (f32x4){bf_lo(w.x), bf_hi(w.x), bf_lo(w.y), bf_hi(w.y)}; }
; __device__ __forceinline__ void pool_prep(const bf16* X, const float* ss, const float* gain, bf16* PB, LAS unsigned char* lds, int vcu, int G, int tid) {
;     ...
;         for (int i = 0; i < 32; ++i) { const int row = ra + i, t = row - bstart;
;             const f32x4 xn = ld4bf(xp + (size_t)row * DM) * rsl[row - r0 + 16];
;             f32x4 old = {0.f, 0.f, 0.f, 0.f};
;             if (t >= w) old = ld4bf(xp + (size_t)(row - w) * DM) * rsl[row - w - r0 + 16];
;             S = S + xn - old;
;             const int cnt = (t + 1 < w) ? t + 1 : w;
;             const f32x4 p = (S * (1.0f / (float)cnt) - xn) * gn;
;             v2u o; o.x = pk2(p[0], p[1]); o.y = pk2(p[2], p[3]); *(v2u*)(PB + (size_t)row * DM + 4 * q) = o; }
	v_lshlrev_b32_e32 v200, 16, v112
	v_and_b32_e32 v201, 0xffff0000, v112
	v_lshlrev_b32_e32 v202, 16, v113
	v_and_b32_e32 v203, 0xffff0000, v113
	v_mul_f32_e32 v204, v46, v200
	v_mul_f32_e32 v205, v46, v201
	v_mul_f32_e32 v206, v46, v202
	v_mul_f32_e32 v207, v46, v203
	v_fma_f32 v6, v46, v200, v6
	v_fma_f32 v7, v46, v201, v7
	v_fma_f32 v8, v46, v202, v8
	v_fma_f32 v9, v46, v203, v9
	v_lshlrev_b32_e32 v88, 16, v108
	v_and_b32_e32 v89, 0xffff0000, v108
	v_lshlrev_b32_e32 v90, 16, v109
	v_and_b32_e32 v91, 0xffff0000, v109
	v_mul_f32_e32 v88, v44, v88
	v_mul_f32_e32 v89, v44, v89
	v_mul_f32_e32 v90, v44, v90
	v_mul_f32_e32 v91, v44, v91
	v_sub_f32_e32 v6, v6, v88
	v_sub_f32_e32 v7, v7, v89
	v_sub_f32_e32 v8, v8, v90
	v_sub_f32_e32 v9, v9, v91
	v_fma_f32 v214, v197, v6, -v204
	v_fma_f32 v215, v197, v7, -v205
	v_fma_f32 v216, v197, v8, -v206
	v_fma_f32 v217, v197, v9, -v207
	v_mul_f32_e32 v214, v2, v214
	v_mul_f32_e32 v215, v3, v215
	v_mul_f32_e32 v216, v4, v216
	v_mul_f32_e32 v217, v5, v217
	v_cvt_pk_bf16_f32 v218, v214, v215
	v_cvt_pk_bf16_f32 v219, v216, v217
	global_store_dwordx2 v[24:25], v[218:219], off sc1
	s_waitcnt vmcnt(31)
	v_lshlrev_b32_e32 v200, 16, v114
	v_and_b32_e32 v201, 0xffff0000, v114
	v_lshlrev_b32_e32 v202, 16, v115
	v_and_b32_e32 v203, 0xffff0000, v115
	v_mul_f32_e32 v204, v47, v200
	v_mul_f32_e32 v205, v47, v201
	v_mul_f32_e32 v206, v47, v202
	v_mul_f32_e32 v207, v47, v203
	v_fma_f32 v6, v47, v200, v6
	v_fma_f32 v7, v47, v201, v7
	v_fma_f32 v8, v47, v202, v8
	v_fma_f32 v9, v47, v203, v9
	v_lshlrev_b32_e32 v88, 16, v110
	v_and_b32_e32 v89, 0xffff0000, v110
	v_lshlrev_b32_e32 v90, 16, v111
	v_and_b32_e32 v91, 0xffff0000, v111
	v_mul_f32_e32 v88, v45, v88
	v_mul_f32_e32 v89, v45, v89
	v_mul_f32_e32 v90, v45, v90
	v_mul_f32_e32 v91, v45, v91
	v_sub_f32_e32 v6, v6, v88
	v_sub_f32_e32 v7, v7, v89
	v_sub_f32_e32 v8, v8, v90
	v_sub_f32_e32 v9, v9, v91
	v_fma_f32 v214, v197, v6, -v204
	v_fma_f32 v215, v197, v7, -v205
	v_fma_f32 v216, v197, v8, -v206
	v_fma_f32 v217, v197, v9, -v207
	v_mul_f32_e32 v214, v2, v214
	v_mul_f32_e32 v215, v3, v215
	v_mul_f32_e32 v216, v4, v216
	v_mul_f32_e32 v217, v5, v217
	v_cvt_pk_bf16_f32 v218, v214, v215
	v_cvt_pk_bf16_f32 v219, v216, v217
	global_store_dwordx2 v[24:25], v[218:219], off offset:2048 sc1
	s_mov_b64 s[0:1], 0x1000
	v_lshl_add_u64 v[24:25], v[24:25], 0, s[0:1]
	s_waitcnt vmcnt(31)
	v_lshlrev_b32_e32 v200, 16, v116
	v_and_b32_e32 v201, 0xffff0000, v116
	v_lshlrev_b32_e32 v202, 16, v117
	v_and_b32_e32 v203, 0xffff0000, v117
	v_mul_f32_e32 v204, v48, v200
	v_mul_f32_e32 v205, v48, v201
	v_mul_f32_e32 v206, v48, v202
	v_mul_f32_e32 v207, v48, v203
	v_fma_f32 v6, v48, v200, v6
	v_fma_f32 v7, v48, v201, v7
	v_fma_f32 v8, v48, v202, v8
	v_fma_f32 v9, v48, v203, v9
	v_lshlrev_b32_e32 v88, 16, v112
	v_and_b32_e32 v89, 0xffff0000, v112
	v_lshlrev_b32_e32 v90, 16, v113
	v_and_b32_e32 v91, 0xffff0000, v113
	v_mul_f32_e32 v88, v46, v88
	v_mul_f32_e32 v89, v46, v89
	v_mul_f32_e32 v90, v46, v90
	v_mul_f32_e32 v91, v46, v91
	v_sub_f32_e32 v6, v6, v88
	v_sub_f32_e32 v7, v7, v89
	v_sub_f32_e32 v8, v8, v90
	v_sub_f32_e32 v9, v9, v91
	v_fma_f32 v214, v197, v6, -v204
	v_fma_f32 v215, v197, v7, -v205
	v_fma_f32 v216, v197, v8, -v206
	v_fma_f32 v217, v197, v9, -v207
	v_mul_f32_e32 v214, v2, v214
	v_mul_f32_e32 v215, v3, v215
	v_mul_f32_e32 v216, v4, v216
	v_mul_f32_e32 v217, v5, v217
	v_cvt_pk_bf16_f32 v218, v214, v215
	v_cvt_pk_bf16_f32 v219, v216, v217
	global_store_dwordx2 v[24:25], v[218:219], off sc1
	s_waitcnt vmcnt(31)
	v_lshlrev_b32_e32 v200, 16, v118
	v_and_b32_e32 v201, 0xffff0000, v118
	v_lshlrev_b32_e32 v202, 16, v119
	v_and_b32_e32 v203, 0xffff0000, v119
	v_mul_f32_e32 v204, v49, v200
	v_mul_f32_e32 v205, v49, v201
	v_mul_f32_e32 v206, v49, v202
	v_mul_f32_e32 v207, v49, v203
	v_fma_f32 v6, v49, v200, v6
	v_fma_f32 v7, v49, v201, v7
	v_fma_f32 v8, v49, v202, v8
	v_fma_f32 v9, v49, v203, v9
	v_lshlrev_b32_e32 v88, 16, v114
	v_and_b32_e32 v89, 0xffff0000, v114
	v_lshlrev_b32_e32 v90, 16, v115
	v_and_b32_e32 v91, 0xffff0000, v115
	v_mul_f32_e32 v88, v47, v88
	v_mul_f32_e32 v89, v47, v89
	v_mul_f32_e32 v90, v47, v90
	v_mul_f32_e32 v91, v47, v91
	v_sub_f32_e32 v6, v6, v88
	v_sub_f32_e32 v7, v7, v89
	v_sub_f32_e32 v8, v8, v90
	v_sub_f32_e32 v9, v9, v91
	v_fma_f32 v214, v197, v6, -v204
	v_fma_f32 v215, v197, v7, -v205
	v_fma_f32 v216, v197, v8, -v206
	v_fma_f32 v217, v197, v9, -v207
	v_mul_f32_e32 v214, v2, v214
	v_mul_f32_e32 v215, v3, v215
	v_mul_f32_e32 v216, v4, v216
	v_mul_f32_e32 v217, v5, v217
	v_cvt_pk_bf16_f32 v218, v214, v215
	v_cvt_pk_bf16_f32 v219, v216, v217
	global_store_dwordx2 v[24:25], v[218:219], off offset:2048 sc1
	s_mov_b64 s[0:1], 0x1000
	v_lshl_add_u64 v[24:25], v[24:25], 0, s[0:1]
	s_waitcnt vmcnt(31)
	v_lshlrev_b32_e32 v200, 16, v120
	v_and_b32_e32 v201, 0xffff0000, v120
	v_lshlrev_b32_e32 v202, 16, v121
	v_and_b32_e32 v203, 0xffff0000, v121
	v_mul_f32_e32 v204, v50, v200
	v_mul_f32_e32 v205, v50, v201
	v_mul_f32_e32 v206, v50, v202
	v_mul_f32_e32 v207, v50, v203
	v_fma_f32 v6, v50, v200, v6
	v_fma_f32 v7, v50, v201, v7
	v_fma_f32 v8, v50, v202, v8
	v_fma_f32 v9, v50, v203, v9
	v_lshlrev_b32_e32 v88, 16, v116
	v_and_b32_e32 v89, 0xffff0000, v116
	v_lshlrev_b32_e32 v90, 16, v117
	v_and_b32_e32 v91, 0xffff0000, v117
	v_mul_f32_e32 v88, v48, v88
	v_mul_f32_e32 v89, v48, v89
	v_mul_f32_e32 v90, v48, v90
	v_mul_f32_e32 v91, v48, v91
	v_sub_f32_e32 v6, v6, v88
	v_sub_f32_e32 v7, v7, v89
	v_sub_f32_e32 v8, v8, v90
	v_sub_f32_e32 v9, v9, v91
	v_fma_f32 v214, v197, v6, -v204
	v_fma_f32 v215, v197, v7, -v205
	v_fma_f32 v216, v197, v8, -v206
	v_fma_f32 v217, v197, v9, -v207
	v_mul_f32_e32 v214, v2, v214
	v_mul_f32_e32 v215, v3, v215
	v_mul_f32_e32 v216, v4, v216
	v_mul_f32_e32 v217, v5, v217
	v_cvt_pk_bf16_f32 v218, v214, v215
	v_cvt_pk_bf16_f32 v219, v216, v217
	global_store_dwordx2 v[24:25], v[218:219], off sc1
	s_waitcnt vmcnt(31)
; __device__ __forceinline__ unsigned pk2(float lo, float hi) { return pg8::cvt_pk_bf16(lo, hi); }
; __device__ __forceinline__ f32x4 ld4bf(const bf16* p) { const v2u w = *(const v2u*)p; return (f32x4){bf_lo(w.x), bf_hi(w.x), bf_lo(w.y), bf_hi(w.y)}; }
; __device__ __forceinline__ void pool_prep(const bf16* X, const float* ss, const float* gain, bf16* PB, LAS unsigned char* lds, int vcu, int G, int tid) {
;     ...
;         for (int i = 0; i < 32; ++i) { const int row = ra + i, t = row - bstart;
;             const f32x4 xn = ld4bf(xp + (size_t)row * DM) * rsl[row - r0 + 16];
;             f32x4 old = {0.f, 0.f, 0.f, 0.f};
;             if (t >= w) old = ld4bf(xp + (size_t)(row - w) * DM) * rsl[row - w - r0 + 16];
;             S = S + xn - old;
;             const int cnt = (t + 1 < w) ? t + 1 : w;
;             const f32x4 p = (S * (1.0f / (float)cnt) - xn) * gn;
;             v2u o; o.x = pk2(p[0], p[1]); o.y = pk2(p[2], p[3]); *(v2u*)(PB + (size_t)row * DM + 4 * q) = o; }
	v_lshlrev_b32_e32 v200, 16, v122
	v_and_b32_e32 v201, 0xffff0000, v122
	v_lshlrev_b32_e32 v202, 16, v123
	v_and_b32_e32 v203, 0xffff0000, v123
	v_mul_f32_e32 v204, v51, v200
	v_mul_f32_e32 v205, v51, v201
	v_mul_f32_e32 v206, v51, v202
	v_mul_f32_e32 v207, v51, v203
	v_fma_f32 v6, v51, v200, v6
	v_fma_f32 v7, v51, v201, v7
	v_fma_f32 v8, v51, v202, v8
	v_fma_f32 v9, v51, v203, v9
	v_lshlrev_b32_e32 v88, 16, v118
	v_and_b32_e32 v89, 0xffff0000, v118
	v_lshlrev_b32_e32 v90, 16, v119
	v_and_b32_e32 v91, 0xffff0000, v119
	v_mul_f32_e32 v88, v49, v88
	v_mul_f32_e32 v89, v49, v89
	v_mul_f32_e32 v90, v49, v90
	v_mul_f32_e32 v91, v49, v91
	v_sub_f32_e32 v6, v6, v88
	v_sub_f32_e32 v7, v7, v89
	v_sub_f32_e32 v8, v8, v90
	v_sub_f32_e32 v9, v9, v91
	v_fma_f32 v214, v197, v6, -v204
	v_fma_f32 v215, v197, v7, -v205
	v_fma_f32 v216, v197, v8, -v206
	v_fma_f32 v217, v197, v9, -v207
	v_mul_f32_e32 v214, v2, v214
	v_mul_f32_e32 v215, v3, v215
	v_mul_f32_e32 v216, v4, v216
	v_mul_f32_e32 v217, v5, v217
	v_cvt_pk_bf16_f32 v218, v214, v215
	v_cvt_pk_bf16_f32 v219, v216, v217
	global_store_dwordx2 v[24:25], v[218:219], off offset:2048 sc1
	s_mov_b64 s[0:1], 0x1000
	v_lshl_add_u64 v[24:25], v[24:25], 0, s[0:1]
	s_waitcnt vmcnt(31)
	v_lshlrev_b32_e32 v200, 16, v124
	v_and_b32_e32 v201, 0xffff0000, v124
	v_lshlrev_b32_e32 v202, 16, v125
	v_and_b32_e32 v203, 0xffff0000, v125
	v_mul_f32_e32 v204, v52, v200
	v_mul_f32_e32 v205, v52, v201
	v_mul_f32_e32 v206, v52, v202
	v_mul_f32_e32 v207, v52, v203
	v_fma_f32 v6, v52, v200, v6
	v_fma_f32 v7, v52, v201, v7
	v_fma_f32 v8, v52, v202, v8
	v_fma_f32 v9, v52, v203, v9
	v_lshlrev_b32_e32 v88, 16, v120
	v_and_b32_e32 v89, 0xffff0000, v120
	v_lshlrev_b32_e32 v90, 16, v121
	v_and_b32_e32 v91, 0xffff0000, v121
	v_mul_f32_e32 v88, v50, v88
	v_mul_f32_e32 v89, v50, v89
	v_mul_f32_e32 v90, v50, v90
	v_mul_f32_e32 v91, v50, v91
	v_sub_f32_e32 v6, v6, v88
	v_sub_f32_e32 v7, v7, v89
	v_sub_f32_e32 v8, v8, v90
	v_sub_f32_e32 v9, v9, v91
	v_fma_f32 v214, v197, v6, -v204
	v_fma_f32 v215, v197, v7, -v205
	v_fma_f32 v216, v197, v8, -v206
	v_fma_f32 v217, v197, v9, -v207
	v_mul_f32_e32 v214, v2, v214
	v_mul_f32_e32 v215, v3, v215
	v_mul_f32_e32 v216, v4, v216
	v_mul_f32_e32 v217, v5, v217
	v_cvt_pk_bf16_f32 v218, v214, v215
	v_cvt_pk_bf16_f32 v219, v216, v217
	global_store_dwordx2 v[24:25], v[218:219], off sc1
	s_waitcnt vmcnt(31)
	v_lshlrev_b32_e32 v200, 16, v126
	v_and_b32_e32 v201, 0xffff0000, v126
	v_lshlrev_b32_e32 v202, 16, v127
	v_and_b32_e32 v203, 0xffff0000, v127
	v_mul_f32_e32 v204, v53, v200
	v_mul_f32_e32 v205, v53, v201
	v_mul_f32_e32 v206, v53, v202
	v_mul_f32_e32 v207, v53, v203
	v_fma_f32 v6, v53, v200, v6
	v_fma_f32 v7, v53, v201, v7
	v_fma_f32 v8, v53, v202, v8
	v_fma_f32 v9, v53, v203, v9
	v_lshlrev_b32_e32 v88, 16, v122
	v_and_b32_e32 v89, 0xffff0000, v122
	v_lshlrev_b32_e32 v90, 16, v123
	v_and_b32_e32 v91, 0xffff0000, v123
	v_mul_f32_e32 v88, v51, v88
	v_mul_f32_e32 v89, v51, v89
	v_mul_f32_e32 v90, v51, v90
	v_mul_f32_e32 v91, v51, v91
	v_sub_f32_e32 v6, v6, v88
	v_sub_f32_e32 v7, v7, v89
	v_sub_f32_e32 v8, v8, v90
	v_sub_f32_e32 v9, v9, v91
	v_fma_f32 v214, v197, v6, -v204
	v_fma_f32 v215, v197, v7, -v205
	v_fma_f32 v216, v197, v8, -v206
	v_fma_f32 v217, v197, v9, -v207
	v_mul_f32_e32 v214, v2, v214
	v_mul_f32_e32 v215, v3, v215
	v_mul_f32_e32 v216, v4, v216
	v_mul_f32_e32 v217, v5, v217
	v_cvt_pk_bf16_f32 v218, v214, v215
	v_cvt_pk_bf16_f32 v219, v216, v217
	global_store_dwordx2 v[24:25], v[218:219], off offset:2048 sc1
	s_mov_b64 s[0:1], 0x1000
	v_lshl_add_u64 v[24:25], v[24:25], 0, s[0:1]
	s_waitcnt vmcnt(31)
	v_lshlrev_b32_e32 v200, 16, v128
	v_and_b32_e32 v201, 0xffff0000, v128
	v_lshlrev_b32_e32 v202, 16, v129
	v_and_b32_e32 v203, 0xffff0000, v129
	v_mul_f32_e32 v204, v54, v200
	v_mul_f32_e32 v205, v54, v201
	v_mul_f32_e32 v206, v54, v202
	v_mul_f32_e32 v207, v54, v203
	v_fma_f32 v6, v54, v200, v6
	v_fma_f32 v7, v54, v201, v7
	v_fma_f32 v8, v54, v202, v8
	v_fma_f32 v9, v54, v203, v9
	v_lshlrev_b32_e32 v88, 16, v124
	v_and_b32_e32 v89, 0xffff0000, v124
	v_lshlrev_b32_e32 v90, 16, v125
	v_and_b32_e32 v91, 0xffff0000, v125
	v_mul_f32_e32 v88, v52, v88
	v_mul_f32_e32 v89, v52, v89
	v_mul_f32_e32 v90, v52, v90
	v_mul_f32_e32 v91, v52, v91
	v_sub_f32_e32 v6, v6, v88
	v_sub_f32_e32 v7, v7, v89
	v_sub_f32_e32 v8, v8, v90
	v_sub_f32_e32 v9, v9, v91
	v_fma_f32 v214, v197, v6, -v204
	v_fma_f32 v215, v197, v7, -v205
	v_fma_f32 v216, v197, v8, -v206
	v_fma_f32 v217, v197, v9, -v207
	v_mul_f32_e32 v214, v2, v214
	v_mul_f32_e32 v215, v3, v215
	v_mul_f32_e32 v216, v4, v216
	v_mul_f32_e32 v217, v5, v217
	v_cvt_pk_bf16_f32 v218, v214, v215
	v_cvt_pk_bf16_f32 v219, v216, v217
	global_store_dwordx2 v[24:25], v[218:219], off sc1
	s_waitcnt vmcnt(31)
	v_lshlrev_b32_e32 v200, 16, v130
	v_and_b32_e32 v201, 0xffff0000, v130
	v_lshlrev_b32_e32 v202, 16, v131
	v_and_b32_e32 v203, 0xffff0000, v131
	v_mul_f32_e32 v204, v55, v200
	v_mul_f32_e32 v205, v55, v201
	v_mul_f32_e32 v206, v55, v202
	v_mul_f32_e32 v207, v55, v203
	v_fma_f32 v6, v55, v200, v6
	v_fma_f32 v7, v55, v201, v7
	v_fma_f32 v8, v55, v202, v8
	v_fma_f32 v9, v55, v203, v9
	v_lshlrev_b32_e32 v88, 16, v126
	v_and_b32_e32 v89, 0xffff0000, v126
	v_lshlrev_b32_e32 v90, 16, v127
	v_and_b32_e32 v91, 0xffff0000, v127
	v_mul_f32_e32 v88, v53, v88
	v_mul_f32_e32 v89, v53, v89
	v_mul_f32_e32 v90, v53, v90
	v_mul_f32_e32 v91, v53, v91
	v_sub_f32_e32 v6, v6, v88
	v_sub_f32_e32 v7, v7, v89
	v_sub_f32_e32 v8, v8, v90
	v_sub_f32_e32 v9, v9, v91
	v_fma_f32 v214, v197, v6, -v204
	v_fma_f32 v215, v197, v7, -v205
	v_fma_f32 v216, v197, v8, -v206
	v_fma_f32 v217, v197, v9, -v207
	v_mul_f32_e32 v214, v2, v214
	v_mul_f32_e32 v215, v3, v215
	v_mul_f32_e32 v216, v4, v216
	v_mul_f32_e32 v217, v5, v217
	v_cvt_pk_bf16_f32 v218, v214, v215
	v_cvt_pk_bf16_f32 v219, v216, v217
	global_store_dwordx2 v[24:25], v[218:219], off offset:2048 sc1
	s_mov_b64 s[0:1], 0x1000
	v_lshl_add_u64 v[24:25], v[24:25], 0, s[0:1]
	s_waitcnt vmcnt(31)
; __device__ __forceinline__ unsigned pk2(float lo, float hi) { return pg8::cvt_pk_bf16(lo, hi); }
; __device__ __forceinline__ f32x4 ld4bf(const bf16* p) { const v2u w = *(const v2u*)p; return (f32x4){bf_lo(w.x), bf_hi(w.x), bf_lo(w.y), bf_hi(w.y)}; }
; __device__ __forceinline__ void pool_prep(const bf16* X, const float* ss, const float* gain, bf16* PB, LAS unsigned char* lds, int vcu, int G, int tid) {
;     ...
;         for (int i = 0; i < 32; ++i) { const int row = ra + i, t = row - bstart;
;             const f32x4 xn = ld4bf(xp + (size_t)row * DM) * rsl[row - r0 + 16];
;             f32x4 old = {0.f, 0.f, 0.f, 0.f};
;             if (t >= w) old = ld4bf(xp + (size_t)(row - w) * DM) * rsl[row - w - r0 + 16];
;             S = S + xn - old;
;             const int cnt = (t + 1 < w) ? t + 1 : w;
;             const f32x4 p = (S * (1.0f / (float)cnt) - xn) * gn;
;             v2u o; o.x = pk2(p[0], p[1]); o.y = pk2(p[2], p[3]); *(v2u*)(PB + (size_t)row * DM + 4 * q) = o; }
	v_lshlrev_b32_e32 v200, 16, v132
	v_and_b32_e32 v201, 0xffff0000, v132
	v_lshlrev_b32_e32 v202, 16, v133
	v_and_b32_e32 v203, 0xffff0000, v133
	v_mul_f32_e32 v204, v56, v200
	v_mul_f32_e32 v205, v56, v201
	v_mul_f32_e32 v206, v56, v202
	v_mul_f32_e32 v207, v56, v203
	v_fma_f32 v6, v56, v200, v6
	v_fma_f32 v7, v56, v201, v7
	v_fma_f32 v8, v56, v202, v8
	v_fma_f32 v9, v56, v203, v9
	v_lshlrev_b32_e32 v88, 16, v128
	v_and_b32_e32 v89, 0xffff0000, v128
	v_lshlrev_b32_e32 v90, 16, v129
	v_and_b32_e32 v91, 0xffff0000, v129
	v_mul_f32_e32 v88, v54, v88
	v_mul_f32_e32 v89, v54, v89
	v_mul_f32_e32 v90, v54, v90
	v_mul_f32_e32 v91, v54, v91
	v_sub_f32_e32 v6, v6, v88
	v_sub_f32_e32 v7, v7, v89
	v_sub_f32_e32 v8, v8, v90
	v_sub_f32_e32 v9, v9, v91
	v_fma_f32 v214, v197, v6, -v204
	v_fma_f32 v215, v197, v7, -v205
	v_fma_f32 v216, v197, v8, -v206
	v_fma_f32 v217, v197, v9, -v207
	v_mul_f32_e32 v214, v2, v214
	v_mul_f32_e32 v215, v3, v215
	v_mul_f32_e32 v216, v4, v216
	v_mul_f32_e32 v217, v5, v217
	v_cvt_pk_bf16_f32 v218, v214, v215
	v_cvt_pk_bf16_f32 v219, v216, v217
	global_store_dwordx2 v[24:25], v[218:219], off sc1
	s_waitcnt vmcnt(31)
	v_lshlrev_b32_e32 v200, 16, v134
	v_and_b32_e32 v201, 0xffff0000, v134
	v_lshlrev_b32_e32 v202, 16, v135
	v_and_b32_e32 v203, 0xffff0000, v135
	v_mul_f32_e32 v204, v57, v200
	v_mul_f32_e32 v205, v57, v201
	v_mul_f32_e32 v206, v57, v202
	v_mul_f32_e32 v207, v57, v203
	v_fma_f32 v6, v57, v200, v6
	v_fma_f32 v7, v57, v201, v7
	v_fma_f32 v8, v57, v202, v8
	v_fma_f32 v9, v57, v203, v9
	v_lshlrev_b32_e32 v88, 16, v130
	v_and_b32_e32 v89, 0xffff0000, v130
	v_lshlrev_b32_e32 v90, 16, v131
	v_and_b32_e32 v91, 0xffff0000, v131
	v_mul_f32_e32 v88, v55, v88
	v_mul_f32_e32 v89, v55, v89
	v_mul_f32_e32 v90, v55, v90
	v_mul_f32_e32 v91, v55, v91
	v_sub_f32_e32 v6, v6, v88
	v_sub_f32_e32 v7, v7, v89
	v_sub_f32_e32 v8, v8, v90
	v_sub_f32_e32 v9, v9, v91
	v_fma_f32 v214, v197, v6, -v204
	v_fma_f32 v215, v197, v7, -v205
	v_fma_f32 v216, v197, v8, -v206
	v_fma_f32 v217, v197, v9, -v207
	v_mul_f32_e32 v214, v2, v214
	v_mul_f32_e32 v215, v3, v215
	v_mul_f32_e32 v216, v4, v216
	v_mul_f32_e32 v217, v5, v217
	v_cvt_pk_bf16_f32 v218, v214, v215
	v_cvt_pk_bf16_f32 v219, v216, v217
	global_store_dwordx2 v[24:25], v[218:219], off offset:2048 sc1
	s_mov_b64 s[0:1], 0x1000
	v_lshl_add_u64 v[24:25], v[24:25], 0, s[0:1]
	s_waitcnt vmcnt(31)
	v_lshlrev_b32_e32 v200, 16, v136
	v_and_b32_e32 v201, 0xffff0000, v136
	v_lshlrev_b32_e32 v202, 16, v137
	v_and_b32_e32 v203, 0xffff0000, v137
	v_mul_f32_e32 v204, v58, v200
	v_mul_f32_e32 v205, v58, v201
	v_mul_f32_e32 v206, v58, v202
	v_mul_f32_e32 v207, v58, v203
	v_fma_f32 v6, v58, v200, v6
	v_fma_f32 v7, v58, v201, v7
	v_fma_f32 v8, v58, v202, v8
	v_fma_f32 v9, v58, v203, v9
	v_lshlrev_b32_e32 v88, 16, v132
	v_and_b32_e32 v89, 0xffff0000, v132
	v_lshlrev_b32_e32 v90, 16, v133
	v_and_b32_e32 v91, 0xffff0000, v133
	v_mul_f32_e32 v88, v56, v88
	v_mul_f32_e32 v89, v56, v89
	v_mul_f32_e32 v90, v56, v90
	v_mul_f32_e32 v91, v56, v91
	v_sub_f32_e32 v6, v6, v88
	v_sub_f32_e32 v7, v7, v89
	v_sub_f32_e32 v8, v8, v90
	v_sub_f32_e32 v9, v9, v91
	v_fma_f32 v214, v197, v6, -v204
	v_fma_f32 v215, v197, v7, -v205
	v_fma_f32 v216, v197, v8, -v206
	v_fma_f32 v217, v197, v9, -v207
	v_mul_f32_e32 v214, v2, v214
	v_mul_f32_e32 v215, v3, v215
	v_mul_f32_e32 v216, v4, v216
	v_mul_f32_e32 v217, v5, v217
	v_cvt_pk_bf16_f32 v218, v214, v215
	v_cvt_pk_bf16_f32 v219, v216, v217
	global_store_dwordx2 v[24:25], v[218:219], off sc1
	s_waitcnt vmcnt(31)
	v_lshlrev_b32_e32 v200, 16, v138
	v_and_b32_e32 v201, 0xffff0000, v138
	v_lshlrev_b32_e32 v202, 16, v139
	v_and_b32_e32 v203, 0xffff0000, v139
	v_mul_f32_e32 v204, v59, v200
	v_mul_f32_e32 v205, v59, v201
	v_mul_f32_e32 v206, v59, v202
	v_mul_f32_e32 v207, v59, v203
	v_fma_f32 v6, v59, v200, v6
	v_fma_f32 v7, v59, v201, v7
	v_fma_f32 v8, v59, v202, v8
	v_fma_f32 v9, v59, v203, v9
	v_lshlrev_b32_e32 v88, 16, v134
	v_and_b32_e32 v89, 0xffff0000, v134
	v_lshlrev_b32_e32 v90, 16, v135
	v_and_b32_e32 v91, 0xffff0000, v135
	v_mul_f32_e32 v88, v57, v88
	v_mul_f32_e32 v89, v57, v89
	v_mul_f32_e32 v90, v57, v90
	v_mul_f32_e32 v91, v57, v91
	v_sub_f32_e32 v6, v6, v88
	v_sub_f32_e32 v7, v7, v89
	v_sub_f32_e32 v8, v8, v90
	v_sub_f32_e32 v9, v9, v91
	v_fma_f32 v214, v197, v6, -v204
	v_fma_f32 v215, v197, v7, -v205
	v_fma_f32 v216, v197, v8, -v206
	v_fma_f32 v217, v197, v9, -v207
	v_mul_f32_e32 v214, v2, v214
	v_mul_f32_e32 v215, v3, v215
	v_mul_f32_e32 v216, v4, v216
	v_mul_f32_e32 v217, v5, v217
	v_cvt_pk_bf16_f32 v218, v214, v215
	v_cvt_pk_bf16_f32 v219, v216, v217
	global_store_dwordx2 v[24:25], v[218:219], off offset:2048 sc1
	s_mov_b64 s[0:1], 0x1000
	v_lshl_add_u64 v[24:25], v[24:25], 0, s[0:1]
	s_waitcnt vmcnt(31)
	v_lshlrev_b32_e32 v200, 16, v140
	v_and_b32_e32 v201, 0xffff0000, v140
	v_lshlrev_b32_e32 v202, 16, v141
	v_and_b32_e32 v203, 0xffff0000, v141
	v_mul_f32_e32 v204, v60, v200
	v_mul_f32_e32 v205, v60, v201
	v_mul_f32_e32 v206, v60, v202
	v_mul_f32_e32 v207, v60, v203
	v_fma_f32 v6, v60, v200, v6
	v_fma_f32 v7, v60, v201, v7
	v_fma_f32 v8, v60, v202, v8
	v_fma_f32 v9, v60, v203, v9
	v_lshlrev_b32_e32 v88, 16, v136
	v_and_b32_e32 v89, 0xffff0000, v136
	v_lshlrev_b32_e32 v90, 16, v137
	v_and_b32_e32 v91, 0xffff0000, v137
	v_mul_f32_e32 v88, v58, v88
	v_mul_f32_e32 v89, v58, v89
	v_mul_f32_e32 v90, v58, v90
	v_mul_f32_e32 v91, v58, v91
	v_sub_f32_e32 v6, v6, v88
	v_sub_f32_e32 v7, v7, v89
	v_sub_f32_e32 v8, v8, v90
	v_sub_f32_e32 v9, v9, v91
	v_fma_f32 v214, v197, v6, -v204
	v_fma_f32 v215, v197, v7, -v205
	v_fma_f32 v216, v197, v8, -v206
	v_fma_f32 v217, v197, v9, -v207
	v_mul_f32_e32 v214, v2, v214
	v_mul_f32_e32 v215, v3, v215
	v_mul_f32_e32 v216, v4, v216
	v_mul_f32_e32 v217, v5, v217
	v_cvt_pk_bf16_f32 v218, v214, v215
	v_cvt_pk_bf16_f32 v219, v216, v217
	global_store_dwordx2 v[24:25], v[218:219], off sc1
	s_waitcnt vmcnt(31)
; __device__ __forceinline__ unsigned pk2(float lo, float hi) { return pg8::cvt_pk_bf16(lo, hi); }
; __device__ __forceinline__ f32x4 ld4bf(const bf16* p) { const v2u w = *(const v2u*)p; return (f32x4){bf_lo(w.x), bf_hi(w.x), bf_lo(w.y), bf_hi(w.y)}; }
; __device__ __forceinline__ void pool_prep(const bf16* X, const float* ss, const float* gain, bf16* PB, LAS unsigned char* lds, int vcu, int G, int tid) {
;     ...
;         for (int i = 0; i < 32; ++i) { const int row = ra + i, t = row - bstart;
;             const f32x4 xn = ld4bf(xp + (size_t)row * DM) * rsl[row - r0 + 16];
;             f32x4 old = {0.f, 0.f, 0.f, 0.f};
;             if (t >= w) old = ld4bf(xp + (size_t)(row - w) * DM) * rsl[row - w - r0 + 16];
;             S = S + xn - old;
;             const int cnt = (t + 1 < w) ? t + 1 : w;
;             const f32x4 p = (S * (1.0f / (float)cnt) - xn) * gn;
;             v2u o; o.x = pk2(p[0], p[1]); o.y = pk2(p[2], p[3]); *(v2u*)(PB + (size_t)row * DM + 4 * q) = o; }
	v_lshlrev_b32_e32 v200, 16, v142
	v_and_b32_e32 v201, 0xffff0000, v142
	v_lshlrev_b32_e32 v202, 16, v143
	v_and_b32_e32 v203, 0xffff0000, v143
	v_mul_f32_e32 v204, v61, v200
	v_mul_f32_e32 v205, v61, v201
	v_mul_f32_e32 v206, v61, v202
	v_mul_f32_e32 v207, v61, v203
	v_fma_f32 v6, v61, v200, v6
	v_fma_f32 v7, v61, v201, v7
	v_fma_f32 v8, v61, v202, v8
	v_fma_f32 v9, v61, v203, v9
	v_lshlrev_b32_e32 v88, 16, v138
	v_and_b32_e32 v89, 0xffff0000, v138
	v_lshlrev_b32_e32 v90, 16, v139
	v_and_b32_e32 v91, 0xffff0000, v139
	v_mul_f32_e32 v88, v59, v88
	v_mul_f32_e32 v89, v59, v89
	v_mul_f32_e32 v90, v59, v90
	v_mul_f32_e32 v91, v59, v91
	v_sub_f32_e32 v6, v6, v88
	v_sub_f32_e32 v7, v7, v89
	v_sub_f32_e32 v8, v8, v90
	v_sub_f32_e32 v9, v9, v91
	v_fma_f32 v214, v197, v6, -v204
	v_fma_f32 v215, v197, v7, -v205
	v_fma_f32 v216, v197, v8, -v206
	v_fma_f32 v217, v197, v9, -v207
	v_mul_f32_e32 v214, v2, v214
	v_mul_f32_e32 v215, v3, v215
	v_mul_f32_e32 v216, v4, v216
	v_mul_f32_e32 v217, v5, v217
	v_cvt_pk_bf16_f32 v218, v214, v215
	v_cvt_pk_bf16_f32 v219, v216, v217
	global_store_dwordx2 v[24:25], v[218:219], off offset:2048 sc1
	s_mov_b64 s[0:1], 0x1000
	v_lshl_add_u64 v[24:25], v[24:25], 0, s[0:1]
	s_waitcnt vmcnt(31)
	v_lshlrev_b32_e32 v200, 16, v144
	v_and_b32_e32 v201, 0xffff0000, v144
	v_lshlrev_b32_e32 v202, 16, v145
	v_and_b32_e32 v203, 0xffff0000, v145
	v_mul_f32_e32 v204, v62, v200
	v_mul_f32_e32 v205, v62, v201
	v_mul_f32_e32 v206, v62, v202
	v_mul_f32_e32 v207, v62, v203
	v_fma_f32 v6, v62, v200, v6
	v_fma_f32 v7, v62, v201, v7
	v_fma_f32 v8, v62, v202, v8
	v_fma_f32 v9, v62, v203, v9
	v_lshlrev_b32_e32 v88, 16, v140
	v_and_b32_e32 v89, 0xffff0000, v140
	v_lshlrev_b32_e32 v90, 16, v141
	v_and_b32_e32 v91, 0xffff0000, v141
	v_mul_f32_e32 v88, v60, v88
	v_mul_f32_e32 v89, v60, v89
	v_mul_f32_e32 v90, v60, v90
	v_mul_f32_e32 v91, v60, v91
	v_sub_f32_e32 v6, v6, v88
	v_sub_f32_e32 v7, v7, v89
	v_sub_f32_e32 v8, v8, v90
	v_sub_f32_e32 v9, v9, v91
	v_fma_f32 v214, v197, v6, -v204
	v_fma_f32 v215, v197, v7, -v205
	v_fma_f32 v216, v197, v8, -v206
	v_fma_f32 v217, v197, v9, -v207
	v_mul_f32_e32 v214, v2, v214
	v_mul_f32_e32 v215, v3, v215
	v_mul_f32_e32 v216, v4, v216
	v_mul_f32_e32 v217, v5, v217
	v_cvt_pk_bf16_f32 v218, v214, v215
	v_cvt_pk_bf16_f32 v219, v216, v217
	global_store_dwordx2 v[24:25], v[218:219], off sc1
	s_waitcnt vmcnt(31)
	v_lshlrev_b32_e32 v200, 16, v146
	v_and_b32_e32 v201, 0xffff0000, v146
	v_lshlrev_b32_e32 v202, 16, v147
	v_and_b32_e32 v203, 0xffff0000, v147
	v_mul_f32_e32 v204, v63, v200
	v_mul_f32_e32 v205, v63, v201
	v_mul_f32_e32 v206, v63, v202
	v_mul_f32_e32 v207, v63, v203
	v_fma_f32 v6, v63, v200, v6
	v_fma_f32 v7, v63, v201, v7
	v_fma_f32 v8, v63, v202, v8
	v_fma_f32 v9, v63, v203, v9
	v_lshlrev_b32_e32 v88, 16, v142
	v_and_b32_e32 v89, 0xffff0000, v142
	v_lshlrev_b32_e32 v90, 16, v143
	v_and_b32_e32 v91, 0xffff0000, v143
	v_mul_f32_e32 v88, v61, v88
	v_mul_f32_e32 v89, v61, v89
	v_mul_f32_e32 v90, v61, v90
	v_mul_f32_e32 v91, v61, v91
	v_sub_f32_e32 v6, v6, v88
	v_sub_f32_e32 v7, v7, v89
	v_sub_f32_e32 v8, v8, v90
	v_sub_f32_e32 v9, v9, v91
	v_fma_f32 v214, v197, v6, -v204
	v_fma_f32 v215, v197, v7, -v205
	v_fma_f32 v216, v197, v8, -v206
	v_fma_f32 v217, v197, v9, -v207
	v_mul_f32_e32 v214, v2, v214
	v_mul_f32_e32 v215, v3, v215
	v_mul_f32_e32 v216, v4, v216
	v_mul_f32_e32 v217, v5, v217
	v_cvt_pk_bf16_f32 v218, v214, v215
	v_cvt_pk_bf16_f32 v219, v216, v217
	global_store_dwordx2 v[24:25], v[218:219], off offset:2048 sc1
	s_mov_b64 s[0:1], 0x1000
	v_lshl_add_u64 v[24:25], v[24:25], 0, s[0:1]
	s_waitcnt vmcnt(31)
	v_lshlrev_b32_e32 v200, 16, v148
	v_and_b32_e32 v201, 0xffff0000, v148
	v_lshlrev_b32_e32 v202, 16, v149
	v_and_b32_e32 v203, 0xffff0000, v149
	v_mul_f32_e32 v204, v64, v200
	v_mul_f32_e32 v205, v64, v201
	v_mul_f32_e32 v206, v64, v202
	v_mul_f32_e32 v207, v64, v203
	v_fma_f32 v6, v64, v200, v6
	v_fma_f32 v7, v64, v201, v7
	v_fma_f32 v8, v64, v202, v8
	v_fma_f32 v9, v64, v203, v9
	v_lshlrev_b32_e32 v88, 16, v144
	v_and_b32_e32 v89, 0xffff0000, v144
	v_lshlrev_b32_e32 v90, 16, v145
	v_and_b32_e32 v91, 0xffff0000, v145
	v_mul_f32_e32 v88, v62, v88
	v_mul_f32_e32 v89, v62, v89
	v_mul_f32_e32 v90, v62, v90
	v_mul_f32_e32 v91, v62, v91
	v_sub_f32_e32 v6, v6, v88
	v_sub_f32_e32 v7, v7, v89
	v_sub_f32_e32 v8, v8, v90
	v_sub_f32_e32 v9, v9, v91
	v_fma_f32 v214, v197, v6, -v204
	v_fma_f32 v215, v197, v7, -v205
	v_fma_f32 v216, v197, v8, -v206
	v_fma_f32 v217, v197, v9, -v207
	v_mul_f32_e32 v214, v2, v214
	v_mul_f32_e32 v215, v3, v215
	v_mul_f32_e32 v216, v4, v216
	v_mul_f32_e32 v217, v5, v217
	v_cvt_pk_bf16_f32 v218, v214, v215
	v_cvt_pk_bf16_f32 v219, v216, v217
	global_store_dwordx2 v[24:25], v[218:219], off sc1
	s_waitcnt vmcnt(31)
	v_lshlrev_b32_e32 v200, 16, v150
	v_and_b32_e32 v201, 0xffff0000, v150
	v_lshlrev_b32_e32 v202, 16, v151
	v_and_b32_e32 v203, 0xffff0000, v151
	v_mul_f32_e32 v204, v65, v200
	v_mul_f32_e32 v205, v65, v201
	v_mul_f32_e32 v206, v65, v202
	v_mul_f32_e32 v207, v65, v203
	v_fma_f32 v6, v65, v200, v6
	v_fma_f32 v7, v65, v201, v7
	v_fma_f32 v8, v65, v202, v8
	v_fma_f32 v9, v65, v203, v9
	v_lshlrev_b32_e32 v88, 16, v146
	v_and_b32_e32 v89, 0xffff0000, v146
	v_lshlrev_b32_e32 v90, 16, v147
	v_and_b32_e32 v91, 0xffff0000, v147
	v_mul_f32_e32 v88, v63, v88
	v_mul_f32_e32 v89, v63, v89
	v_mul_f32_e32 v90, v63, v90
	v_mul_f32_e32 v91, v63, v91
	v_sub_f32_e32 v6, v6, v88
	v_sub_f32_e32 v7, v7, v89
	v_sub_f32_e32 v8, v8, v90
	v_sub_f32_e32 v9, v9, v91
	v_fma_f32 v214, v197, v6, -v204
	v_fma_f32 v215, v197, v7, -v205
	v_fma_f32 v216, v197, v8, -v206
	v_fma_f32 v217, v197, v9, -v207
	v_mul_f32_e32 v214, v2, v214
	v_mul_f32_e32 v215, v3, v215
	v_mul_f32_e32 v216, v4, v216
	v_mul_f32_e32 v217, v5, v217
	v_cvt_pk_bf16_f32 v218, v214, v215
	v_cvt_pk_bf16_f32 v219, v216, v217
	global_store_dwordx2 v[24:25], v[218:219], off offset:2048 sc1
	s_mov_b64 s[0:1], 0x1000
	v_lshl_add_u64 v[24:25], v[24:25], 0, s[0:1]
	s_waitcnt vmcnt(31)
; __device__ __forceinline__ unsigned pk2(float lo, float hi) { return pg8::cvt_pk_bf16(lo, hi); }
; __device__ __forceinline__ f32x4 ld4bf(const bf16* p) { const v2u w = *(const v2u*)p; return (f32x4){bf_lo(w.x), bf_hi(w.x), bf_lo(w.y), bf_hi(w.y)}; }
; __device__ __forceinline__ void pool_prep(const bf16* X, const float* ss, const float* gain, bf16* PB, LAS unsigned char* lds, int vcu, int G, int tid) {
;     ...
;         for (int i = 0; i < 32; ++i) { const int row = ra + i, t = row - bstart;
;             const f32x4 xn = ld4bf(xp + (size_t)row * DM) * rsl[row - r0 + 16];
;             f32x4 old = {0.f, 0.f, 0.f, 0.f};
;             if (t >= w) old = ld4bf(xp + (size_t)(row - w) * DM) * rsl[row - w - r0 + 16];
;             S = S + xn - old;
;             const int cnt = (t + 1 < w) ? t + 1 : w;
;             const f32x4 p = (S * (1.0f / (float)cnt) - xn) * gn;
;             v2u o; o.x = pk2(p[0], p[1]); o.y = pk2(p[2], p[3]); *(v2u*)(PB + (size_t)row * DM + 4 * q) = o; }
	v_lshlrev_b32_e32 v200, 16, v152
	v_and_b32_e32 v201, 0xffff0000, v152
	v_lshlrev_b32_e32 v202, 16, v153
	v_and_b32_e32 v203, 0xffff0000, v153
	v_mul_f32_e32 v204, v66, v200
	v_mul_f32_e32 v205, v66, v201
	v_mul_f32_e32 v206, v66, v202
	v_mul_f32_e32 v207, v66, v203
	v_fma_f32 v6, v66, v200, v6
	v_fma_f32 v7, v66, v201, v7
	v_fma_f32 v8, v66, v202, v8
	v_fma_f32 v9, v66, v203, v9
	v_lshlrev_b32_e32 v88, 16, v148
	v_and_b32_e32 v89, 0xffff0000, v148
	v_lshlrev_b32_e32 v90, 16, v149
	v_and_b32_e32 v91, 0xffff0000, v149
	v_mul_f32_e32 v88, v64, v88
	v_mul_f32_e32 v89, v64, v89
	v_mul_f32_e32 v90, v64, v90
	v_mul_f32_e32 v91, v64, v91
	v_sub_f32_e32 v6, v6, v88
	v_sub_f32_e32 v7, v7, v89
	v_sub_f32_e32 v8, v8, v90
	v_sub_f32_e32 v9, v9, v91
	v_fma_f32 v214, v197, v6, -v204
	v_fma_f32 v215, v197, v7, -v205
	v_fma_f32 v216, v197, v8, -v206
	v_fma_f32 v217, v197, v9, -v207
	v_mul_f32_e32 v214, v2, v214
	v_mul_f32_e32 v215, v3, v215
	v_mul_f32_e32 v216, v4, v216
	v_mul_f32_e32 v217, v5, v217
	v_cvt_pk_bf16_f32 v218, v214, v215
	v_cvt_pk_bf16_f32 v219, v216, v217
	global_store_dwordx2 v[24:25], v[218:219], off sc1
	s_waitcnt vmcnt(31)
	v_lshlrev_b32_e32 v200, 16, v154
	v_and_b32_e32 v201, 0xffff0000, v154
	v_lshlrev_b32_e32 v202, 16, v155
	v_and_b32_e32 v203, 0xffff0000, v155
	v_mul_f32_e32 v204, v67, v200
	v_mul_f32_e32 v205, v67, v201
	v_mul_f32_e32 v206, v67, v202
	v_mul_f32_e32 v207, v67, v203
	v_fma_f32 v6, v67, v200, v6
	v_fma_f32 v7, v67, v201, v7
	v_fma_f32 v8, v67, v202, v8
	v_fma_f32 v9, v67, v203, v9
	v_lshlrev_b32_e32 v88, 16, v150
	v_and_b32_e32 v89, 0xffff0000, v150
	v_lshlrev_b32_e32 v90, 16, v151
	v_and_b32_e32 v91, 0xffff0000, v151
	v_mul_f32_e32 v88, v65, v88
	v_mul_f32_e32 v89, v65, v89
	v_mul_f32_e32 v90, v65, v90
	v_mul_f32_e32 v91, v65, v91
	v_sub_f32_e32 v6, v6, v88
	v_sub_f32_e32 v7, v7, v89
	v_sub_f32_e32 v8, v8, v90
	v_sub_f32_e32 v9, v9, v91
	v_fma_f32 v214, v197, v6, -v204
	v_fma_f32 v215, v197, v7, -v205
	v_fma_f32 v216, v197, v8, -v206
	v_fma_f32 v217, v197, v9, -v207
	v_mul_f32_e32 v214, v2, v214
	v_mul_f32_e32 v215, v3, v215
	v_mul_f32_e32 v216, v4, v216
	v_mul_f32_e32 v217, v5, v217
	v_cvt_pk_bf16_f32 v218, v214, v215
	v_cvt_pk_bf16_f32 v219, v216, v217
	global_store_dwordx2 v[24:25], v[218:219], off offset:2048 sc1
	s_mov_b64 s[0:1], 0x1000
	v_lshl_add_u64 v[24:25], v[24:25], 0, s[0:1]
	s_waitcnt vmcnt(31)
	v_lshlrev_b32_e32 v200, 16, v156
	v_and_b32_e32 v201, 0xffff0000, v156
	v_lshlrev_b32_e32 v202, 16, v157
	v_and_b32_e32 v203, 0xffff0000, v157
	v_mul_f32_e32 v204, v68, v200
	v_mul_f32_e32 v205, v68, v201
	v_mul_f32_e32 v206, v68, v202
	v_mul_f32_e32 v207, v68, v203
	v_fma_f32 v6, v68, v200, v6
	v_fma_f32 v7, v68, v201, v7
	v_fma_f32 v8, v68, v202, v8
	v_fma_f32 v9, v68, v203, v9
	v_lshlrev_b32_e32 v88, 16, v152
	v_and_b32_e32 v89, 0xffff0000, v152
	v_lshlrev_b32_e32 v90, 16, v153
	v_and_b32_e32 v91, 0xffff0000, v153
	v_mul_f32_e32 v88, v66, v88
	v_mul_f32_e32 v89, v66, v89
	v_mul_f32_e32 v90, v66, v90
	v_mul_f32_e32 v91, v66, v91
	v_sub_f32_e32 v6, v6, v88
	v_sub_f32_e32 v7, v7, v89
	v_sub_f32_e32 v8, v8, v90
	v_sub_f32_e32 v9, v9, v91
	v_fma_f32 v214, v197, v6, -v204
	v_fma_f32 v215, v197, v7, -v205
	v_fma_f32 v216, v197, v8, -v206
	v_fma_f32 v217, v197, v9, -v207
	v_mul_f32_e32 v214, v2, v214
	v_mul_f32_e32 v215, v3, v215
	v_mul_f32_e32 v216, v4, v216
	v_mul_f32_e32 v217, v5, v217
	v_cvt_pk_bf16_f32 v218, v214, v215
	v_cvt_pk_bf16_f32 v219, v216, v217
	global_store_dwordx2 v[24:25], v[218:219], off sc1
	s_waitcnt vmcnt(31)
	v_lshlrev_b32_e32 v200, 16, v158
	v_and_b32_e32 v201, 0xffff0000, v158
	v_lshlrev_b32_e32 v202, 16, v159
	v_and_b32_e32 v203, 0xffff0000, v159
	v_mul_f32_e32 v204, v69, v200
	v_mul_f32_e32 v205, v69, v201
	v_mul_f32_e32 v206, v69, v202
	v_mul_f32_e32 v207, v69, v203
	v_fma_f32 v6, v69, v200, v6
	v_fma_f32 v7, v69, v201, v7
	v_fma_f32 v8, v69, v202, v8
	v_fma_f32 v9, v69, v203, v9
	v_lshlrev_b32_e32 v88, 16, v154
	v_and_b32_e32 v89, 0xffff0000, v154
	v_lshlrev_b32_e32 v90, 16, v155
	v_and_b32_e32 v91, 0xffff0000, v155
	v_mul_f32_e32 v88, v67, v88
	v_mul_f32_e32 v89, v67, v89
	v_mul_f32_e32 v90, v67, v90
	v_mul_f32_e32 v91, v67, v91
	v_sub_f32_e32 v6, v6, v88
	v_sub_f32_e32 v7, v7, v89
	v_sub_f32_e32 v8, v8, v90
	v_sub_f32_e32 v9, v9, v91
	v_fma_f32 v214, v197, v6, -v204
	v_fma_f32 v215, v197, v7, -v205
	v_fma_f32 v216, v197, v8, -v206
	v_fma_f32 v217, v197, v9, -v207
	v_mul_f32_e32 v214, v2, v214
	v_mul_f32_e32 v215, v3, v215
	v_mul_f32_e32 v216, v4, v216
	v_mul_f32_e32 v217, v5, v217
	v_cvt_pk_bf16_f32 v218, v214, v215
	v_cvt_pk_bf16_f32 v219, v216, v217
	global_store_dwordx2 v[24:25], v[218:219], off offset:2048 sc1
	s_mov_b64 s[0:1], 0x1000
	v_lshl_add_u64 v[24:25], v[24:25], 0, s[0:1]
	s_waitcnt vmcnt(31)
; __device__ __forceinline__ unsigned pk2(float lo, float hi) { return pg8::cvt_pk_bf16(lo, hi); }
; __device__ __forceinline__ f32x4 ld4bf(const bf16* p) { const v2u w = *(const v2u*)p; return (f32x4){bf_lo(w.x), bf_hi(w.x), bf_lo(w.y), bf_hi(w.y)}; }
; __device__ __forceinline__ void pool_prep(const bf16* X, const float* ss, const float* gain, bf16* PB, LAS unsigned char* lds, int vcu, int G, int tid) {
;     ...
;         for (int i = 0; i < 32; ++i) { const int row = ra + i, t = row - bstart;
;             const f32x4 xn = ld4bf(xp + (size_t)row * DM) * rsl[row - r0 + 16];
;             f32x4 old = {0.f, 0.f, 0.f, 0.f};
;             if (t >= w) old = ld4bf(xp + (size_t)(row - w) * DM) * rsl[row - w - r0 + 16];
;             S = S + xn - old;
;             const int cnt = (t + 1 < w) ? t + 1 : w;
;             const f32x4 p = (S * (1.0f / (float)cnt) - xn) * gn;
;             v2u o; o.x = pk2(p[0], p[1]); o.y = pk2(p[2], p[3]); *(v2u*)(PB + (size_t)row * DM + 4 * q) = o; }
	v_lshlrev_b32_e32 v200, 16, v160
	v_and_b32_e32 v201, 0xffff0000, v160
	v_lshlrev_b32_e32 v202, 16, v161
	v_and_b32_e32 v203, 0xffff0000, v161
	v_mul_f32_e32 v204, v70, v200
	v_mul_f32_e32 v205, v70, v201
	v_mul_f32_e32 v206, v70, v202
	v_mul_f32_e32 v207, v70, v203
	v_fma_f32 v6, v70, v200, v6
	v_fma_f32 v7, v70, v201, v7
	v_fma_f32 v8, v70, v202, v8
	v_fma_f32 v9, v70, v203, v9
	v_lshlrev_b32_e32 v88, 16, v156
	v_and_b32_e32 v89, 0xffff0000, v156
	v_lshlrev_b32_e32 v90, 16, v157
	v_and_b32_e32 v91, 0xffff0000, v157
	v_mul_f32_e32 v88, v68, v88
	v_mul_f32_e32 v89, v68, v89
	v_mul_f32_e32 v90, v68, v90
	v_mul_f32_e32 v91, v68, v91
	v_sub_f32_e32 v6, v6, v88
	v_sub_f32_e32 v7, v7, v89
	v_sub_f32_e32 v8, v8, v90
	v_sub_f32_e32 v9, v9, v91
	v_fma_f32 v214, v197, v6, -v204
	v_fma_f32 v215, v197, v7, -v205
	v_fma_f32 v216, v197, v8, -v206
	v_fma_f32 v217, v197, v9, -v207
	v_mul_f32_e32 v214, v2, v214
	v_mul_f32_e32 v215, v3, v215
	v_mul_f32_e32 v216, v4, v216
	v_mul_f32_e32 v217, v5, v217
	v_cvt_pk_bf16_f32 v218, v214, v215
	v_cvt_pk_bf16_f32 v219, v216, v217
	global_store_dwordx2 v[24:25], v[218:219], off sc1
	s_waitcnt vmcnt(31)
	v_lshlrev_b32_e32 v200, 16, v162
	v_and_b32_e32 v201, 0xffff0000, v162
	v_lshlrev_b32_e32 v202, 16, v163
	v_and_b32_e32 v203, 0xffff0000, v163
	v_mul_f32_e32 v204, v71, v200
	v_mul_f32_e32 v205, v71, v201
	v_mul_f32_e32 v206, v71, v202
	v_mul_f32_e32 v207, v71, v203
	v_fma_f32 v6, v71, v200, v6
	v_fma_f32 v7, v71, v201, v7
	v_fma_f32 v8, v71, v202, v8
	v_fma_f32 v9, v71, v203, v9
	v_lshlrev_b32_e32 v88, 16, v158
	v_and_b32_e32 v89, 0xffff0000, v158
	v_lshlrev_b32_e32 v90, 16, v159
	v_and_b32_e32 v91, 0xffff0000, v159
	v_mul_f32_e32 v88, v69, v88
	v_mul_f32_e32 v89, v69, v89
	v_mul_f32_e32 v90, v69, v90
	v_mul_f32_e32 v91, v69, v91
	v_sub_f32_e32 v6, v6, v88
	v_sub_f32_e32 v7, v7, v89
	v_sub_f32_e32 v8, v8, v90
	v_sub_f32_e32 v9, v9, v91
	v_fma_f32 v214, v197, v6, -v204
	v_fma_f32 v215, v197, v7, -v205
	v_fma_f32 v216, v197, v8, -v206
	v_fma_f32 v217, v197, v9, -v207
	v_mul_f32_e32 v214, v2, v214
	v_mul_f32_e32 v215, v3, v215
	v_mul_f32_e32 v216, v4, v216
	v_mul_f32_e32 v217, v5, v217
	v_cvt_pk_bf16_f32 v218, v214, v215
	v_cvt_pk_bf16_f32 v219, v216, v217
	global_store_dwordx2 v[24:25], v[218:219], off offset:2048 sc1
	s_mov_b64 s[0:1], 0x1000
	v_lshl_add_u64 v[24:25], v[24:25], 0, s[0:1]
	s_waitcnt vmcnt(31)
	v_lshlrev_b32_e32 v200, 16, v164
	v_and_b32_e32 v201, 0xffff0000, v164
	v_lshlrev_b32_e32 v202, 16, v165
	v_and_b32_e32 v203, 0xffff0000, v165
	v_mul_f32_e32 v204, v72, v200
	v_mul_f32_e32 v205, v72, v201
	v_mul_f32_e32 v206, v72, v202
	v_mul_f32_e32 v207, v72, v203
	v_fma_f32 v6, v72, v200, v6
	v_fma_f32 v7, v72, v201, v7
	v_fma_f32 v8, v72, v202, v8
	v_fma_f32 v9, v72, v203, v9
	v_lshlrev_b32_e32 v88, 16, v160
	v_and_b32_e32 v89, 0xffff0000, v160
	v_lshlrev_b32_e32 v90, 16, v161
	v_and_b32_e32 v91, 0xffff0000, v161
	v_mul_f32_e32 v88, v70, v88
	v_mul_f32_e32 v89, v70, v89
	v_mul_f32_e32 v90, v70, v90
	v_mul_f32_e32 v91, v70, v91
	v_sub_f32_e32 v6, v6, v88
	v_sub_f32_e32 v7, v7, v89
	v_sub_f32_e32 v8, v8, v90
	v_sub_f32_e32 v9, v9, v91
	v_fma_f32 v214, v197, v6, -v204
	v_fma_f32 v215, v197, v7, -v205
	v_fma_f32 v216, v197, v8, -v206
	v_fma_f32 v217, v197, v9, -v207
	v_mul_f32_e32 v214, v2, v214
	v_mul_f32_e32 v215, v3, v215
	v_mul_f32_e32 v216, v4, v216
	v_mul_f32_e32 v217, v5, v217
	v_cvt_pk_bf16_f32 v218, v214, v215
	v_cvt_pk_bf16_f32 v219, v216, v217
	global_store_dwordx2 v[24:25], v[218:219], off sc1
	s_waitcnt vmcnt(31)
	v_lshlrev_b32_e32 v200, 16, v166
	v_and_b32_e32 v201, 0xffff0000, v166
	v_lshlrev_b32_e32 v202, 16, v167
	v_and_b32_e32 v203, 0xffff0000, v167
	v_mul_f32_e32 v204, v73, v200
	v_mul_f32_e32 v205, v73, v201
	v_mul_f32_e32 v206, v73, v202
	v_mul_f32_e32 v207, v73, v203
	v_fma_f32 v6, v73, v200, v6
	v_fma_f32 v7, v73, v201, v7
	v_fma_f32 v8, v73, v202, v8
	v_fma_f32 v9, v73, v203, v9
	v_lshlrev_b32_e32 v88, 16, v162
	v_and_b32_e32 v89, 0xffff0000, v162
	v_lshlrev_b32_e32 v90, 16, v163
	v_and_b32_e32 v91, 0xffff0000, v163
	v_mul_f32_e32 v88, v71, v88
	v_mul_f32_e32 v89, v71, v89
	v_mul_f32_e32 v90, v71, v90
	v_mul_f32_e32 v91, v71, v91
	v_sub_f32_e32 v6, v6, v88
	v_sub_f32_e32 v7, v7, v89
	v_sub_f32_e32 v8, v8, v90
	v_sub_f32_e32 v9, v9, v91
	v_fma_f32 v214, v197, v6, -v204
	v_fma_f32 v215, v197, v7, -v205
	v_fma_f32 v216, v197, v8, -v206
	v_fma_f32 v217, v197, v9, -v207
	v_mul_f32_e32 v214, v2, v214
	v_mul_f32_e32 v215, v3, v215
	v_mul_f32_e32 v216, v4, v216
	v_mul_f32_e32 v217, v5, v217
	v_cvt_pk_bf16_f32 v218, v214, v215
	v_cvt_pk_bf16_f32 v219, v216, v217
	global_store_dwordx2 v[24:25], v[218:219], off offset:2048 sc1
	s_branch .LBB0_308
